# H2 + tile-boundary re-alignment: both wave groups run their epilogues concurrently (one extra conditional barrier per group per tile)
# speedup vs baseline: 1.0051x; 1.0051x over previous
; #define PG8_STAGE(bufoff, gbase, voff) do { _Pragma("unroll") for (int _i = 0; _i < 2; ++_i) \
;         __builtin_amdgcn_global_load_lds((const unsigned*)((const char*)(gbase) + (voff)[_i]), (PG8_LAS unsigned*)(lds + (bufoff) + ldsw + _i * 8192), 16, 0, 0); } while (0)
; #define PG8_WAIT_V(n) asm volatile("s_waitcnt vmcnt(" #n ")" ::: "memory")
; #define PG8_BAR __builtin_amdgcn_s_barrier()
; template <class Epi, class Sched>
; __device__ __forceinline__ void gemm_phase(PG8_LAS unsigned char* lds, const Gemm g, const Sched& S, const Epi& E) {
;     const int tid = threadIdx.x, wid = __builtin_amdgcn_readfirstlane(tid >> 6), lane = tid & 63, wr = wid >> 2, wc = wid & 3, fr = lane & 15, fq = lane >> 4;
;     const int K = g.K, nt = K / BK;
;     unsigned voffA[2], voffB[2];
; #pragma unroll
;     for (int i = 0; i < 2; ++i) { int R, C; stage_rc(tid * 16 + i * 8192, R, C); const int Rb = Epi::PERM ? ((R & ~31) + perm32(R & 31)) : R;
;         voffA[i] = (unsigned)(R * K + C) * 2u; voffB[i] = (unsigned)(Rb * K + C) * 2u; }
;     const size_t kstep = (size_t)(BK * 2);
;     const size_t hstep = (size_t)HALF * K * 2;
;     const size_t tstep = 2 * hstep;
;     const unsigned ldsw = (unsigned)wid * 1024u;
;     const int aoff = lds_byte(wr * 64 + fr, fq * 8), boff = lds_byte(wc * 32 + fr, fq * 8);
;     ...
;     Unit cur, nxt; int ui = 0;
;     if (!S.next(0, cur)) return;
;     f32x4 acc[2][2][4][2];
; #pragma unroll
;     for (int a = 0; a < 2; ++a)
; #pragma unroll
;         for (int b = 0; b < 2; ++b)
; #pragma unroll
;             for (int m = 0; m < 4; ++m)
; #pragma unroll
;                 for (int n = 0; n < 2; ++n) acc[a][b][m][n] = (f32x4){0.f, 0.f, 0.f, 0.f};
;     bf16x8 At[4][2], B0[2][2], B1[2][2];
;     const char* cA = (const char*)g.A + (size_t)cur.pm * tstep; const char* cB = (const char*)g.Bt + (size_t)cur.pn * tstep;
;     S.a_ready(cur);
;     PG8_STAGE(PG8_SB(0, 0), cB, voffB); PG8_STAGE(PG8_SA(0, 0), cA, voffA); PG8_STAGE(PG8_SB(0, 1), cB + hstep, voffB); PG8_STAGE(PG8_SA(0, 1), cA + hstep, voffA);
;     if (wr == 1) PG8_BAR;
;     PG8_WAIT_V(4); PG8_BAR;
;     PG8_STAGE(PG8_SB(1, 0), cB + kstep, voffB); PG8_STAGE(PG8_SA(1, 0), cA + kstep, voffA); PG8_STAGE(PG8_SB(1, 1), cB + hstep + kstep, voffB);
;     PG8_WAIT_V(6); PG8_BAR;
;     for (;;) {
.LBB0_230:
	s_add_u32 s6, s58, 0x23d86000
	s_addc_u32 s7, s59, 0
	s_add_u32 s82, s58, 0xfc86000
	s_addc_u32 s83, s59, 0
	s_add_u32 s8, s58, 0x1fd86000
	s_addc_u32 s9, s59, 0
	s_waitcnt lgkmcnt(0)
	s_add_u32 s20, s58, 0x6a24000
	s_addc_u32 s21, s59, 0
	s_lshl_b32 s3, s3, 5
	s_mov_b64 s[26:27], 0x80
	s_and_b32 s3, s3, 0x60
	s_add_i32 m0, s67, 0x18000
	v_lshl_add_u64 v[6:7], v[6:7], 0, s[26:27]
	s_lshl_b32 s5, s2, 13
	s_lshl_b32 s10, s3, 7
	v_readfirstlane_b32 s98, v242
	s_lshr_b32 s98, s98, 8
	s_waitcnt vmcnt(2)
	s_barrier
	global_load_lds_dwordx4 v[6:7], off
	v_lshl_add_u64 v[4:5], v[4:5], 0, s[26:27]
	s_add_i32 m0, s67, 0x1a000
	s_add_i32 s84, s67, 0x8000
	s_add_i32 s85, s67, 0xa000
	global_load_lds_dwordx4 v[4:5], off
	v_lshl_add_u64 v[0:1], v[0:1], 0, s[26:27]
	s_mov_b32 m0, s84
	s_add_u32 s28, s70, 0x80080
	global_load_lds_dwordx4 v[0:1], off
	v_lshl_add_u64 v[0:1], v[2:3], 0, s[26:27]
	s_mov_b32 m0, s85
	s_addc_u32 s29, s71, 0
	global_load_lds_dwordx4 v[0:1], off
	s_add_i32 m0, s67, 0x1c000
	v_lshl_add_u64 v[0:1], s[28:29], 0, v[138:139]
	global_load_lds_dwordx4 v[0:1], off
	v_lshl_add_u64 v[0:1], s[28:29], 0, v[142:143]
	s_add_i32 m0, s67, 0x1e000
	v_lshlrev_b32_e32 v2, 2, v242
	global_load_lds_dwordx4 v[0:1], off
	v_and_b32_e32 v0, 15, v242
	v_lshl_or_b32 v147, s2, 6, v0
	v_lshlrev_b32_e32 v1, 1, v12
	v_lshlrev_b32_e32 v3, 6, v242
	s_movk_i32 s2, 0x3c0
	v_lshl_or_b32 v0, v0, 6, v1
	v_and_b32_e32 v2, 32, v2
	v_and_or_b32 v1, v3, s2, v1
	v_bitop3_b32 v160, s10, v1, v2 bitop3:0xf6
	v_lshlrev_b32_e32 v1, 9, v242
	v_bitop3_b32 v0, v0, s5, v2 bitop3:0xde
	v_and_b32_e32 v1, 0x70000, v1
	v_lshlrev_b32_e32 v2, 12, v10
	v_or3_b32 v1, v8, v1, v2
	v_add_u32_e32 v148, v1, v9
	v_lshlrev_b32_e32 v1, 5, v11
	s_waitcnt vmcnt(6)
	v_and_b32_e32 v1, 0xf0000, v1
	v_or_b32_e32 v146, s3, v12
	v_or3_b32 v1, v8, v1, v2
	s_add_i32 s90, 0, 0x10000
	s_add_i32 s91, 0, 0x14000
	v_or_b32_e32 v161, 0xfffff400, v146
	s_ashr_i32 s86, s62, 31
	s_mov_b32 s87, s62
	s_ashr_i32 s88, s12, 31
	s_lshl_b32 s89, s74, 2
	v_mov_b32_e32 v149, v145
	v_add_u32_e32 v150, v1, v9
	v_mov_b32_e32 v151, v145
	v_mov_b64_e32 v[152:153], s[0:1]
	v_add_u32_e32 v162, s90, v160
	v_add_u32_e32 v163, 0, v0
	v_add_u32_e32 v164, s91, v160
	s_mov_b64 s[28:29], 0x40000
	s_mov_b64 s[30:31], 0x48000
	s_mov_b64 s[34:35], 0x50000
	s_mov_b64 s[38:39], 0x58000
	s_mov_b32 s92, 0x80000
	s_mov_b64 s[40:41], 0x90000
	s_mov_b32 s93, 0x90000
	s_mov_b64 s[42:43], 0xa0000
	s_mov_b32 s94, 0xa0000
	s_mov_b64 s[44:45], 0xb0000
	s_mov_b32 s95, 0xb0000
	s_mov_b32 s96, 0
	s_barrier
	s_branch .LBB0_232
.LBB0_231:
	s_cmp_eq_u32 s98, 0
	s_cbranch_scc1 .Lxb_235
	s_barrier

; #define PG8_STAGE(bufoff, gbase, voff) do { _Pragma("unroll") for (int _i = 0; _i < 2; ++_i) \
;         __builtin_amdgcn_global_load_lds((const unsigned*)((const char*)(gbase) + (voff)[_i]), (PG8_LAS unsigned*)(lds + (bufoff) + ldsw + _i * 8192), 16, 0, 0); } while (0)
; #define PG8_LDA(dst, b, h) do { _Pragma("unroll") for (int m = 0; m < 4; ++m) _Pragma("unroll") for (int k = 0; k < 2; ++k) dst[m][k] = *(const PG8_LAS bf16x8*)(lds + PG8_SA(b, h) + aoff + m * 2048 + k * 1024); } while (0)
; #define PG8_LDB(dst, b, h) do { _Pragma("unroll") for (int n = 0; n < 2; ++n) _Pragma("unroll") for (int k = 0; k < 2; ++k) dst[n][k] = *(const PG8_LAS bf16x8*)(lds + PG8_SB(b, h) + boff + n * 2048 + k * 1024); } while (0)
; #define PG8_MMA(ai, bj, At, Bt) do { __builtin_amdgcn_s_setprio(1); _Pragma("unroll") for (int m = 0; m < 4; ++m) _Pragma("unroll") for (int n = 0; n < 2; ++n) _Pragma("unroll") for (int k = 0; k < 2; ++k) \
;         acc[ai][bj][m][n] = __builtin_amdgcn_mfma_f32_16x16x32_bf16(Bt[n][k], At[m][k], acc[ai][bj][m][n], 0, 0, 0); __builtin_amdgcn_s_setprio(0); } while (0)
; #define PG8_WAIT_V(n) asm volatile("s_waitcnt vmcnt(" #n ")" ::: "memory")
; #define PG8_WAIT_L(n) asm volatile("s_waitcnt lgkmcnt(" #n ")" ::: "memory")
; #define PG8_BAR __builtin_amdgcn_s_barrier()
; #define PG8_SCHED __builtin_amdgcn_sched_barrier(0)
; template <class Epi, class Sched>
; __device__ __forceinline__ void gemm_phase(PG8_LAS unsigned char* lds, const Gemm g, const Sched& S, const Epi& E) {
;     ...
;             PG8_LDB(B0, 0, 0); PG8_SCHED; PG8_LDA(At, 0, 0); PG8_STAGE(PG8_SA(1, 1), a1 + hstep, voffA);
;             PG8_WAIT_L(8); PG8_BAR; PG8_WAIT_L(0); PG8_MMA(0, 0, At, B0); PG8_BAR; PG8_SCHED;
;             PG8_LDB(B1, 0, 1); PG8_STAGE(PG8_SB(0, 0), b2, voffB);
;             PG8_BAR; PG8_WAIT_L(0); PG8_MMA(0, 1, At, B1); PG8_BAR;
;             PG8_LDA(At, 0, 1); PG8_STAGE(PG8_SA(0, 0), a2, voffA);
;             PG8_BAR; PG8_WAIT_L(0); PG8_MMA(1, 0, At, B0); PG8_BAR; PG8_SCHED;
;             PG8_STAGE(PG8_SB(0, 1), b2 + hstep, voffB);
;             PG8_WAIT_V(6); PG8_BAR; PG8_MMA(1, 1, At, B1); PG8_BAR;
;             PG8_LDB(B0, 1, 0); PG8_SCHED; PG8_LDA(At, 1, 0); PG8_STAGE(PG8_SA(0, 1), a2 + hstep, voffA);
.LBB0_235:
	s_setprio 0
	ds_read_b128 v[128:131], v162
	ds_read_b128 v[132:135], v162 offset:1024
	ds_read_b128 v[154:157], v162 offset:2048
	ds_read_b128 v[166:169], v162 offset:3072
	ds_read_b128 v[170:173], v163
	ds_read_b128 v[174:177], v163 offset:1024
	ds_read_b128 v[178:181], v163 offset:2048
	ds_read_b128 v[182:185], v163 offset:3072
	ds_read_b128 v[186:189], v163 offset:4096
	ds_read_b128 v[190:193], v163 offset:5120
	ds_read_b128 v[194:197], v163 offset:6144
	ds_read_b128 v[198:201], v163 offset:7168
	ds_read_b128 v[202:205], v164
	ds_read_b128 v[206:209], v164 offset:1024
	ds_read_b128 v[210:213], v164 offset:2048
	ds_read_b128 v[214:217], v164 offset:3072
	s_add_u32 s10, s68, 0xfff80080
	s_addc_u32 s11, s69, -1
	s_cmp_eq_u32 vcc_hi, 28
	s_cselect_b32 s73, s0, s11
	s_cselect_b32 s72, s5, s10
	s_cselect_b32 s71, s47, vcc_lo
	s_cselect_b32 s70, s49, s97
	v_lshl_add_u64 v[158:159], s[68:69], 0, v[148:149]
	s_add_i32 m0, s67, 0xc000
	s_nop 0
	global_load_lds_dwordx4 v[158:159], off
	v_lshl_add_u64 v[158:159], s[68:69], 0, v[150:151]
	s_add_i32 m0, s67, 0xe000
	s_nop 0
	global_load_lds_dwordx4 v[158:159], off
	s_waitcnt vmcnt(8)
	s_waitcnt lgkmcnt(0)
	s_setprio 1
	s_barrier
	v_mfma_f32_16x16x32_bf16 v[124:127], v[128:131], v[170:173], v[124:127]
	v_mfma_f32_16x16x32_bf16 v[120:123], v[154:157], v[170:173], v[120:123]
	v_mfma_f32_16x16x32_bf16 v[116:119], v[128:131], v[178:181], v[116:119]
	v_mfma_f32_16x16x32_bf16 v[112:115], v[154:157], v[178:181], v[112:115]
	v_mfma_f32_16x16x32_bf16 v[108:111], v[128:131], v[186:189], v[108:111]
	v_mfma_f32_16x16x32_bf16 v[104:107], v[154:157], v[186:189], v[104:107]
	v_mfma_f32_16x16x32_bf16 v[100:103], v[128:131], v[194:197], v[100:103]
	v_mfma_f32_16x16x32_bf16 v[96:99], v[154:157], v[194:197], v[96:99]
	v_mfma_f32_16x16x32_bf16 v[124:127], v[132:135], v[174:177], v[124:127]
	v_mfma_f32_16x16x32_bf16 v[120:123], v[166:169], v[174:177], v[120:123]
	v_mfma_f32_16x16x32_bf16 v[116:119], v[132:135], v[182:185], v[116:119]
	v_mfma_f32_16x16x32_bf16 v[112:115], v[166:169], v[182:185], v[112:115]
	v_mfma_f32_16x16x32_bf16 v[108:111], v[132:135], v[190:193], v[108:111]
	v_mfma_f32_16x16x32_bf16 v[104:107], v[166:169], v[190:193], v[104:107]
	v_mfma_f32_16x16x32_bf16 v[100:103], v[132:135], v[198:201], v[100:103]
	v_mfma_f32_16x16x32_bf16 v[96:99], v[166:169], v[198:201], v[96:99]
	v_mfma_f32_16x16x32_bf16 v[60:63], v[202:205], v[170:173], v[60:63]
	v_mfma_f32_16x16x32_bf16 v[56:59], v[210:213], v[170:173], v[56:59]
	v_mfma_f32_16x16x32_bf16 v[52:55], v[202:205], v[178:181], v[52:55]
	v_mfma_f32_16x16x32_bf16 v[48:51], v[210:213], v[178:181], v[48:51]
	v_mfma_f32_16x16x32_bf16 v[44:47], v[202:205], v[186:189], v[44:47]
	v_mfma_f32_16x16x32_bf16 v[40:43], v[210:213], v[186:189], v[40:43]
	v_mfma_f32_16x16x32_bf16 v[36:39], v[202:205], v[194:197], v[36:39]
	v_mfma_f32_16x16x32_bf16 v[32:35], v[210:213], v[194:197], v[32:35]
	v_mfma_f32_16x16x32_bf16 v[60:63], v[206:209], v[174:177], v[60:63]
	v_mfma_f32_16x16x32_bf16 v[56:59], v[214:217], v[174:177], v[56:59]
	v_mfma_f32_16x16x32_bf16 v[52:55], v[206:209], v[182:185], v[52:55]
	v_mfma_f32_16x16x32_bf16 v[48:51], v[214:217], v[182:185], v[48:51]
	v_mfma_f32_16x16x32_bf16 v[44:47], v[206:209], v[190:193], v[44:47]
	v_mfma_f32_16x16x32_bf16 v[40:43], v[214:217], v[190:193], v[40:43]
	v_mfma_f32_16x16x32_bf16 v[36:39], v[206:209], v[198:201], v[36:39]
	v_mfma_f32_16x16x32_bf16 v[32:35], v[214:217], v[198:201], v[32:35]
	s_barrier
	s_setprio 0
	ds_read_b128 v[170:173], v163 offset:16384
	ds_read_b128 v[174:177], v163 offset:17408
	ds_read_b128 v[178:181], v163 offset:18432
	ds_read_b128 v[182:185], v163 offset:19456
	ds_read_b128 v[186:189], v163 offset:20480
	ds_read_b128 v[190:193], v163 offset:21504
	ds_read_b128 v[194:197], v163 offset:22528
	ds_read_b128 v[198:201], v163 offset:23552
	s_add_i32 s10, s90, s78
	v_lshl_add_u64 v[158:159], s[70:71], 0, v[138:139]
	s_mov_b32 m0, s10
	s_nop 0
	global_load_lds_dwordx4 v[158:159], off
	v_lshl_add_u64 v[218:219], s[70:71], 0, v[142:143]
	s_add_i32 m0, s10, 0x2000
	s_nop 0
	global_load_lds_dwordx4 v[218:219], off
	s_mov_b32 m0, s67
	v_lshl_add_u64 v[220:221], s[72:73], 0, v[136:137]
	global_load_lds_dwordx4 v[220:221], off
	v_lshl_add_u64 v[222:223], s[72:73], 0, v[140:141]
	s_mov_b32 m0, s79
	s_nop 0
	global_load_lds_dwordx4 v[222:223], off
	s_add_u32 s10, s70, 0x80000
	s_addc_u32 s11, s71, 0
	s_add_i32 s33, s91, s78
	v_lshl_add_u64 v[224:225], s[10:11], 0, v[138:139]
	s_mov_b32 m0, s33
	s_nop 0
	global_load_lds_dwordx4 v[224:225], off
	v_lshl_add_u64 v[224:225], s[10:11], 0, v[142:143]
	s_add_i32 m0, s33, 0x2000
	s_nop 0
	global_load_lds_dwordx4 v[224:225], off
	s_waitcnt vmcnt(8)
	s_waitcnt lgkmcnt(0)
	s_setprio 1
	s_barrier
; #define PG8_STAGE(bufoff, gbase, voff) do { _Pragma("unroll") for (int _i = 0; _i < 2; ++_i) \
;         __builtin_amdgcn_global_load_lds((const unsigned*)((const char*)(gbase) + (voff)[_i]), (PG8_LAS unsigned*)(lds + (bufoff) + ldsw + _i * 8192), 16, 0, 0); } while (0)
; #define PG8_LDA(dst, b, h) do { _Pragma("unroll") for (int m = 0; m < 4; ++m) _Pragma("unroll") for (int k = 0; k < 2; ++k) dst[m][k] = *(const PG8_LAS bf16x8*)(lds + PG8_SA(b, h) + aoff + m * 2048 + k * 1024); } while (0)
; #define PG8_LDB(dst, b, h) do { _Pragma("unroll") for (int n = 0; n < 2; ++n) _Pragma("unroll") for (int k = 0; k < 2; ++k) dst[n][k] = *(const PG8_LAS bf16x8*)(lds + PG8_SB(b, h) + boff + n * 2048 + k * 1024); } while (0)
; #define PG8_MMA(ai, bj, At, Bt) do { __builtin_amdgcn_s_setprio(1); _Pragma("unroll") for (int m = 0; m < 4; ++m) _Pragma("unroll") for (int n = 0; n < 2; ++n) _Pragma("unroll") for (int k = 0; k < 2; ++k) \
;         acc[ai][bj][m][n] = __builtin_amdgcn_mfma_f32_16x16x32_bf16(Bt[n][k], At[m][k], acc[ai][bj][m][n], 0, 0, 0); __builtin_amdgcn_s_setprio(0); } while (0)
; #define PG8_WAIT_L(n) asm volatile("s_waitcnt lgkmcnt(" #n ")" ::: "memory")
; #define PG8_BAR __builtin_amdgcn_s_barrier()
; #define PG8_SCHED __builtin_amdgcn_sched_barrier(0)
; template <class Epi, class Sched>
; __device__ __forceinline__ void gemm_phase(PG8_LAS unsigned char* lds, const Gemm g, const Sched& S, const Epi& E) {
;     ...
;             PG8_LDB(B0, 1, 0); PG8_SCHED; PG8_LDA(At, 1, 0); PG8_STAGE(PG8_SA(0, 1), a2 + hstep, voffA);
;             PG8_WAIT_L(8); PG8_BAR; PG8_WAIT_L(0); PG8_MMA(0, 0, At, B0); PG8_BAR; PG8_SCHED;
;             PG8_LDB(B1, 1, 1); PG8_STAGE(PG8_SB(1, 0), b3, voffB);
;             PG8_BAR; PG8_WAIT_L(0); PG8_MMA(0, 1, At, B1); PG8_BAR;
;             PG8_LDA(At, 1, 1); PG8_STAGE(PG8_SA(1, 0), a3, voffA);
	v_mfma_f32_16x16x32_bf16 v[92:95], v[128:131], v[170:173], v[92:95]
	v_mfma_f32_16x16x32_bf16 v[88:91], v[154:157], v[170:173], v[88:91]
	v_mfma_f32_16x16x32_bf16 v[84:87], v[128:131], v[178:181], v[84:87]
	v_mfma_f32_16x16x32_bf16 v[80:83], v[154:157], v[178:181], v[80:83]
	v_mfma_f32_16x16x32_bf16 v[76:79], v[128:131], v[186:189], v[76:79]
	v_mfma_f32_16x16x32_bf16 v[72:75], v[154:157], v[186:189], v[72:75]
	v_mfma_f32_16x16x32_bf16 v[68:71], v[128:131], v[194:197], v[68:71]
	v_mfma_f32_16x16x32_bf16 v[64:67], v[154:157], v[194:197], v[64:67]
	s_add_i32 s33, 0, 0x18000
	v_add_u32_e32 v144, s33, v160
	v_mfma_f32_16x16x32_bf16 v[92:95], v[132:135], v[174:177], v[92:95]
	v_mfma_f32_16x16x32_bf16 v[88:91], v[166:169], v[174:177], v[88:91]
	v_mfma_f32_16x16x32_bf16 v[84:87], v[132:135], v[182:185], v[84:87]
	v_mfma_f32_16x16x32_bf16 v[80:83], v[166:169], v[182:185], v[80:83]
	v_mfma_f32_16x16x32_bf16 v[76:79], v[132:135], v[190:193], v[76:79]
	v_mfma_f32_16x16x32_bf16 v[72:75], v[166:169], v[190:193], v[72:75]
	v_mfma_f32_16x16x32_bf16 v[68:71], v[132:135], v[198:201], v[68:71]
	v_mfma_f32_16x16x32_bf16 v[64:67], v[166:169], v[198:201], v[64:67]
	v_mfma_f32_16x16x32_bf16 v[28:31], v[202:205], v[170:173], v[28:31]
	v_mfma_f32_16x16x32_bf16 v[24:27], v[210:213], v[170:173], v[24:27]
	v_mfma_f32_16x16x32_bf16 v[20:23], v[202:205], v[178:181], v[20:23]
	v_mfma_f32_16x16x32_bf16 v[16:19], v[210:213], v[178:181], v[16:19]
	v_mfma_f32_16x16x32_bf16 v[12:15], v[202:205], v[186:189], v[12:15]
	v_mfma_f32_16x16x32_bf16 v[8:11], v[210:213], v[186:189], v[8:11]
	v_mfma_f32_16x16x32_bf16 v[4:7], v[202:205], v[194:197], v[4:7]
	v_mfma_f32_16x16x32_bf16 v[0:3], v[210:213], v[194:197], v[0:3]
	v_mfma_f32_16x16x32_bf16 v[28:31], v[206:209], v[174:177], v[28:31]
	v_mfma_f32_16x16x32_bf16 v[24:27], v[214:217], v[174:177], v[24:27]
	v_mfma_f32_16x16x32_bf16 v[20:23], v[206:209], v[182:185], v[20:23]
	v_mfma_f32_16x16x32_bf16 v[16:19], v[214:217], v[182:185], v[16:19]
	v_mfma_f32_16x16x32_bf16 v[12:15], v[206:209], v[190:193], v[12:15]
	v_mfma_f32_16x16x32_bf16 v[8:11], v[214:217], v[190:193], v[8:11]
	v_mfma_f32_16x16x32_bf16 v[4:7], v[206:209], v[198:201], v[4:7]
	v_mfma_f32_16x16x32_bf16 v[0:3], v[214:217], v[198:201], v[0:3]
	s_barrier
	s_setprio 0
	ds_read_b128 v[128:131], v162 offset:32768
	ds_read_b128 v[132:135], v162 offset:33792
	ds_read_b128 v[154:157], v162 offset:34816
	ds_read_b128 v[166:169], v162 offset:35840
	ds_read_b128 v[170:173], v163 offset:32768
	ds_read_b128 v[174:177], v163 offset:33792
	ds_read_b128 v[178:181], v163 offset:34816
	ds_read_b128 v[182:185], v163 offset:35840
	ds_read_b128 v[186:189], v163 offset:36864
	ds_read_b128 v[190:193], v163 offset:37888
	ds_read_b128 v[194:197], v163 offset:38912
	ds_read_b128 v[198:201], v163 offset:39936
	ds_read_b128 v[202:205], v164 offset:32768
	ds_read_b128 v[206:209], v164 offset:33792
	ds_read_b128 v[210:213], v164 offset:34816
	ds_read_b128 v[214:217], v164 offset:35840
	s_add_u32 s10, s72, 0x80000
	s_addc_u32 s11, s73, 0
	s_mov_b32 m0, s80
	v_lshl_add_u64 v[224:225], s[10:11], 0, v[136:137]
	global_load_lds_dwordx4 v[224:225], off
	v_lshl_add_u64 v[224:225], s[10:11], 0, v[140:141]
	s_mov_b32 m0, s81
	s_nop 0
	global_load_lds_dwordx4 v[224:225], off
	s_waitcnt vmcnt(8)
	s_waitcnt lgkmcnt(0)
	s_setprio 1
	s_barrier
	v_mfma_f32_16x16x32_bf16 v[124:127], v[128:131], v[170:173], v[124:127]
	v_mfma_f32_16x16x32_bf16 v[120:123], v[154:157], v[170:173], v[120:123]
	v_mfma_f32_16x16x32_bf16 v[116:119], v[128:131], v[178:181], v[116:119]
	v_mfma_f32_16x16x32_bf16 v[112:115], v[154:157], v[178:181], v[112:115]
	v_mfma_f32_16x16x32_bf16 v[108:111], v[128:131], v[186:189], v[108:111]
	v_mfma_f32_16x16x32_bf16 v[104:107], v[154:157], v[186:189], v[104:107]
	v_mfma_f32_16x16x32_bf16 v[100:103], v[128:131], v[194:197], v[100:103]
	v_mfma_f32_16x16x32_bf16 v[96:99], v[154:157], v[194:197], v[96:99]
	v_mfma_f32_16x16x32_bf16 v[124:127], v[132:135], v[174:177], v[124:127]
	v_mfma_f32_16x16x32_bf16 v[120:123], v[166:169], v[174:177], v[120:123]
	v_mfma_f32_16x16x32_bf16 v[116:119], v[132:135], v[182:185], v[116:119]
	v_mfma_f32_16x16x32_bf16 v[112:115], v[166:169], v[182:185], v[112:115]
	v_mfma_f32_16x16x32_bf16 v[108:111], v[132:135], v[190:193], v[108:111]
	v_mfma_f32_16x16x32_bf16 v[104:107], v[166:169], v[190:193], v[104:107]
	v_mfma_f32_16x16x32_bf16 v[100:103], v[132:135], v[198:201], v[100:103]
	v_mfma_f32_16x16x32_bf16 v[96:99], v[166:169], v[198:201], v[96:99]
	v_mfma_f32_16x16x32_bf16 v[60:63], v[202:205], v[170:173], v[60:63]
	v_mfma_f32_16x16x32_bf16 v[56:59], v[210:213], v[170:173], v[56:59]
	v_mfma_f32_16x16x32_bf16 v[52:55], v[202:205], v[178:181], v[52:55]
	v_mfma_f32_16x16x32_bf16 v[48:51], v[210:213], v[178:181], v[48:51]
	v_mfma_f32_16x16x32_bf16 v[44:47], v[202:205], v[186:189], v[44:47]
	v_mfma_f32_16x16x32_bf16 v[40:43], v[210:213], v[186:189], v[40:43]
	v_mfma_f32_16x16x32_bf16 v[36:39], v[202:205], v[194:197], v[36:39]
	v_mfma_f32_16x16x32_bf16 v[32:35], v[210:213], v[194:197], v[32:35]
	v_mfma_f32_16x16x32_bf16 v[60:63], v[206:209], v[174:177], v[60:63]
	v_mfma_f32_16x16x32_bf16 v[56:59], v[214:217], v[174:177], v[56:59]
	v_mfma_f32_16x16x32_bf16 v[52:55], v[206:209], v[182:185], v[52:55]
	v_mfma_f32_16x16x32_bf16 v[48:51], v[214:217], v[182:185], v[48:51]
	v_mfma_f32_16x16x32_bf16 v[44:47], v[206:209], v[190:193], v[44:47]
	v_mfma_f32_16x16x32_bf16 v[40:43], v[214:217], v[190:193], v[40:43]
	v_mfma_f32_16x16x32_bf16 v[36:39], v[206:209], v[198:201], v[36:39]
	v_mfma_f32_16x16x32_bf16 v[32:35], v[214:217], v[198:201], v[32:35]
	s_barrier
; #define PG8_STAGE(bufoff, gbase, voff) do { _Pragma("unroll") for (int _i = 0; _i < 2; ++_i) \
;         __builtin_amdgcn_global_load_lds((const unsigned*)((const char*)(gbase) + (voff)[_i]), (PG8_LAS unsigned*)(lds + (bufoff) + ldsw + _i * 8192), 16, 0, 0); } while (0)
; #define PG8_LDA(dst, b, h) do { _Pragma("unroll") for (int m = 0; m < 4; ++m) _Pragma("unroll") for (int k = 0; k < 2; ++k) dst[m][k] = *(const PG8_LAS bf16x8*)(lds + PG8_SA(b, h) + aoff + m * 2048 + k * 1024); } while (0)
; #define PG8_MMA(ai, bj, At, Bt) do { __builtin_amdgcn_s_setprio(1); _Pragma("unroll") for (int m = 0; m < 4; ++m) _Pragma("unroll") for (int n = 0; n < 2; ++n) _Pragma("unroll") for (int k = 0; k < 2; ++k) \
;         acc[ai][bj][m][n] = __builtin_amdgcn_mfma_f32_16x16x32_bf16(Bt[n][k], At[m][k], acc[ai][bj][m][n], 0, 0, 0); __builtin_amdgcn_s_setprio(0); } while (0)
; #define PG8_WAIT_V(n) asm volatile("s_waitcnt vmcnt(" #n ")" ::: "memory")
; #define PG8_WAIT_L(n) asm volatile("s_waitcnt lgkmcnt(" #n ")" ::: "memory")
; #define PG8_BAR __builtin_amdgcn_s_barrier()
; #define PG8_SCHED __builtin_amdgcn_sched_barrier(0)
; template <class Epi, class Sched>
; __device__ __forceinline__ void gemm_phase(PG8_LAS unsigned char* lds, const Gemm g, const Sched& S, const Epi& E) {
;     ...
;             PG8_LDA(At, 1, 1); PG8_STAGE(PG8_SA(1, 0), a3, voffA);
;             PG8_BAR; PG8_WAIT_L(0); PG8_MMA(1, 0, At, B0); PG8_BAR; PG8_SCHED;
;             PG8_STAGE(PG8_SB(1, 1), b3 + hstep, voffB);
;             PG8_WAIT_V(6); PG8_BAR; PG8_MMA(1, 1, At, B1); PG8_BAR;
;         }
;         E(acc, cur, wr, wc, fr, fq); S.done(cur);
	s_setprio 0
	ds_read_b128 v[170:173], v163 offset:49152
	ds_read_b128 v[174:177], v163 offset:50176
	ds_read_b128 v[178:181], v163 offset:51200
	ds_read_b128 v[182:185], v163 offset:52224
	ds_read_b128 v[186:189], v163 offset:53248
	ds_read_b128 v[190:193], v163 offset:54272
	ds_read_b128 v[194:197], v163 offset:55296
	ds_read_b128 v[198:201], v163 offset:56320
	s_add_i32 s72, 0, 0x1c000
	s_add_i32 s10, s33, s78
	v_add_u32_e32 v144, s72, v160
	v_lshl_add_u64 v[158:159], v[158:159], 0, s[26:27]
	s_mov_b32 m0, s10
	s_nop 0
	global_load_lds_dwordx4 v[158:159], off
	v_lshl_add_u64 v[158:159], v[218:219], 0, s[26:27]
	s_add_i32 m0, s10, 0x2000
	s_nop 0
	global_load_lds_dwordx4 v[158:159], off
	s_mov_b32 m0, s84
	v_lshl_add_u64 v[158:159], v[220:221], 0, s[26:27]
	global_load_lds_dwordx4 v[158:159], off
	v_lshl_add_u64 v[158:159], v[222:223], 0, s[26:27]
	s_mov_b32 m0, s85
	s_nop 0
	global_load_lds_dwordx4 v[158:159], off
	s_add_u32 s10, s70, 0x80080
	s_addc_u32 s11, s71, 0
	s_add_i32 s33, s72, s78
	v_lshl_add_u64 v[224:225], s[10:11], 0, v[138:139]
	s_mov_b32 m0, s33
	s_nop 0
	global_load_lds_dwordx4 v[224:225], off
	v_lshl_add_u64 v[224:225], s[10:11], 0, v[142:143]
	s_add_i32 m0, s33, 0x2000
	s_nop 0
	global_load_lds_dwordx4 v[224:225], off
	s_waitcnt vmcnt(8)
	s_waitcnt lgkmcnt(0)
	s_setprio 1
	s_barrier
	v_mfma_f32_16x16x32_bf16 v[92:95], v[128:131], v[170:173], v[92:95]
	v_mfma_f32_16x16x32_bf16 v[88:91], v[154:157], v[170:173], v[88:91]
	v_mfma_f32_16x16x32_bf16 v[84:87], v[128:131], v[178:181], v[84:87]
	v_mfma_f32_16x16x32_bf16 v[80:83], v[154:157], v[178:181], v[80:83]
	v_mfma_f32_16x16x32_bf16 v[76:79], v[128:131], v[186:189], v[76:79]
	v_mfma_f32_16x16x32_bf16 v[72:75], v[154:157], v[186:189], v[72:75]
	v_mfma_f32_16x16x32_bf16 v[68:71], v[128:131], v[194:197], v[68:71]
	v_mfma_f32_16x16x32_bf16 v[64:67], v[154:157], v[194:197], v[64:67]
	s_add_i32 vcc_hi, vcc_hi, 2
	s_add_u32 s68, s68, 0x100
	s_addc_u32 s69, s69, 0
	s_add_u32 s97, s97, 0x100
	s_addc_u32 vcc_lo, vcc_lo, 0
	s_cmp_gt_u32 vcc_hi, 29
	v_mfma_f32_16x16x32_bf16 v[92:95], v[132:135], v[174:177], v[92:95]
	v_mfma_f32_16x16x32_bf16 v[88:91], v[166:169], v[174:177], v[88:91]
	v_mfma_f32_16x16x32_bf16 v[84:87], v[132:135], v[182:185], v[84:87]
	v_mfma_f32_16x16x32_bf16 v[80:83], v[166:169], v[182:185], v[80:83]
	v_mfma_f32_16x16x32_bf16 v[76:79], v[132:135], v[190:193], v[76:79]
	v_mfma_f32_16x16x32_bf16 v[72:75], v[166:169], v[190:193], v[72:75]
	v_mfma_f32_16x16x32_bf16 v[68:71], v[132:135], v[198:201], v[68:71]
	v_mfma_f32_16x16x32_bf16 v[64:67], v[166:169], v[198:201], v[64:67]
	v_mfma_f32_16x16x32_bf16 v[28:31], v[202:205], v[170:173], v[28:31]
	v_mfma_f32_16x16x32_bf16 v[24:27], v[210:213], v[170:173], v[24:27]
	v_mfma_f32_16x16x32_bf16 v[20:23], v[202:205], v[178:181], v[20:23]
	v_mfma_f32_16x16x32_bf16 v[16:19], v[210:213], v[178:181], v[16:19]
	v_mfma_f32_16x16x32_bf16 v[12:15], v[202:205], v[186:189], v[12:15]
	v_mfma_f32_16x16x32_bf16 v[8:11], v[210:213], v[186:189], v[8:11]
	v_mfma_f32_16x16x32_bf16 v[4:7], v[202:205], v[194:197], v[4:7]
	v_mfma_f32_16x16x32_bf16 v[0:3], v[210:213], v[194:197], v[0:3]
	v_mfma_f32_16x16x32_bf16 v[28:31], v[206:209], v[174:177], v[28:31]
	v_mfma_f32_16x16x32_bf16 v[24:27], v[214:217], v[174:177], v[24:27]
	v_mfma_f32_16x16x32_bf16 v[20:23], v[206:209], v[182:185], v[20:23]
	v_mfma_f32_16x16x32_bf16 v[16:19], v[214:217], v[182:185], v[16:19]
	v_mfma_f32_16x16x32_bf16 v[12:15], v[206:209], v[190:193], v[12:15]
	v_mfma_f32_16x16x32_bf16 v[8:11], v[214:217], v[190:193], v[8:11]
	v_mfma_f32_16x16x32_bf16 v[4:7], v[206:209], v[198:201], v[4:7]
	v_mfma_f32_16x16x32_bf16 v[0:3], v[214:217], v[198:201], v[0:3]
	s_barrier
	s_cbranch_scc0 .LBB0_235
	s_setprio 0
	s_cmp_lg_u32 s98, 0
	s_cbranch_scc1 .Lxa_235
	s_barrier
; __device__ __forceinline__ unsigned cvt_pk_bf16(float lo, float hi) { const bf16v2_t v = __builtin_convertvector((f32x2){lo, hi}, bf16v2_t); return __builtin_bit_cast(unsigned, v); }
;     __device__ __forceinline__ void operator()(const AccT& acc, const pg8::Unit& u, int wr, int wc, int fr, int fq) const {
;     ...
;         } else {
;             if (u.pm >= 128) return;
;             const int col = (pn - 24) * 128 + cl;
; #pragma unroll
;             for (int ai = 0; ai < 2; ++ai)
; #pragma unroll
;                 for (int m = 0; m < 4; ++m) {
;                     const f32x4 a = acc[ai][0][m][0] * acc[ai][1][m][0], b = acc[ai][0][m][1] * acc[ai][1][m][1];
;                     u32x4 w; w.x = cvt_pk_bf16(a[0], a[1]); w.y = cvt_pk_bf16(a[2], a[3]); w.z = cvt_pk_bf16(b[0], b[1]); w.w = cvt_pk_bf16(b[2], b[3]);
;                     *(u32x4*)(P + (size_t)(row0 + ai * 128 + m * 16) * 1024 + col) = w;
;                 }
.Lxa_235:
	v_lshl_add_u32 v154, s4, 8, v147
	s_cmp_gt_i32 s66, 7
	s_mov_b64 s[68:69], -1
	s_cbranch_scc0 .LBB0_277
	s_cmpk_gt_i32 s4, 0x7f
	s_cselect_b64 s[68:69], -1, 0
	s_cmpk_lt_i32 s4, 0x80
	s_cselect_b64 s[70:71], -1, 0
	s_cmp_gt_u32 s66, 23
	s_mov_b64 s[4:5], -1
	s_cbranch_scc0 .LBB0_241
	s_andn2_b64 vcc, exec, s[70:71]
	s_cbranch_vccnz .LBB0_240
	v_pk_mul_f32 v[130:131], v[126:127], v[62:63]
	v_pk_mul_f32 v[128:129], v[124:125], v[60:61]
	v_pk_mul_f32 v[132:133], v[122:123], v[58:59]
	v_ashrrev_i32_e32 v155, 31, v154
	v_lshl_add_u32 v144, s66, 7, v161
	v_pk_mul_f32 v[134:135], v[120:121], v[56:57]
	v_cvt_pk_bf16_f32 v128, v128, v129
	v_cvt_pk_bf16_f32 v129, v130, v131
	v_cvt_pk_bf16_f32 v131, v132, v133
	v_lshlrev_b64 v[132:133], 11, v[154:155]
	v_cvt_pk_bf16_f32 v130, v134, v135
	v_lshl_add_u64 v[132:133], s[8:9], 0, v[132:133]
	v_lshlrev_b64 v[134:135], 1, v[144:145]
	v_lshl_add_u64 v[132:133], v[132:133], 0, v[134:135]
	global_store_dwordx4 v[132:133], v[128:131], off
	v_pk_mul_f32 v[156:157], v[114:115], v[50:51]
	v_pk_mul_f32 v[158:159], v[112:113], v[48:49]
	v_pk_mul_f32 v[130:131], v[118:119], v[54:55]
	v_pk_mul_f32 v[128:129], v[116:117], v[52:53]
	s_mov_b32 s0, 0x40000
	v_cvt_pk_bf16_f32 v128, v128, v129
	v_cvt_pk_bf16_f32 v129, v130, v131
	v_cvt_pk_bf16_f32 v131, v156, v157
	v_or_b32_e32 v156, 16, v154
	v_ashrrev_i32_e32 v157, 31, v156
	v_lshlrev_b64 v[156:157], 11, v[156:157]
	v_lshl_add_u64 v[156:157], s[8:9], 0, v[156:157]
	v_cvt_pk_bf16_f32 v130, v158, v159
	v_lshl_add_u64 v[156:157], v[156:157], 0, v[134:135]
	global_store_dwordx4 v[156:157], v[128:131], off
	v_pk_mul_f32 v[156:157], v[106:107], v[42:43]
	v_pk_mul_f32 v[158:159], v[104:105], v[40:41]
	v_pk_mul_f32 v[130:131], v[110:111], v[46:47]
	v_pk_mul_f32 v[128:129], v[108:109], v[44:45]
	s_nop 0
	v_cvt_pk_bf16_f32 v128, v128, v129
	v_cvt_pk_bf16_f32 v129, v130, v131
	v_cvt_pk_bf16_f32 v131, v156, v157
	v_or_b32_e32 v156, 32, v154
	v_ashrrev_i32_e32 v157, 31, v156
	v_lshlrev_b64 v[156:157], 11, v[156:157]
	v_lshl_add_u64 v[156:157], s[8:9], 0, v[156:157]
	v_cvt_pk_bf16_f32 v130, v158, v159
	v_lshl_add_u64 v[156:157], v[156:157], 0, v[134:135]
	global_store_dwordx4 v[156:157], v[128:131], off
	v_pk_mul_f32 v[156:157], v[98:99], v[34:35]
	v_pk_mul_f32 v[158:159], v[96:97], v[32:33]
	v_pk_mul_f32 v[130:131], v[102:103], v[38:39]
	v_pk_mul_f32 v[128:129], v[100:101], v[36:37]
	s_nop 0
	v_cvt_pk_bf16_f32 v128, v128, v129
	v_cvt_pk_bf16_f32 v129, v130, v131
	v_cvt_pk_bf16_f32 v131, v156, v157
	v_or_b32_e32 v156, 48, v154
	v_ashrrev_i32_e32 v157, 31, v156
	v_lshlrev_b64 v[156:157], 11, v[156:157]
	v_lshl_add_u64 v[156:157], s[8:9], 0, v[156:157]
	v_cvt_pk_bf16_f32 v130, v158, v159
	v_lshl_add_u64 v[134:135], v[156:157], 0, v[134:135]
	global_store_dwordx4 v[134:135], v[128:131], off
	v_pk_mul_f32 v[134:135], v[90:91], v[26:27]
	v_pk_mul_f32 v[156:157], v[88:89], v[24:25]
	v_pk_mul_f32 v[130:131], v[94:95], v[30:31]
	v_pk_mul_f32 v[128:129], v[92:93], v[28:29]
	s_nop 0
	v_cvt_pk_bf16_f32 v128, v128, v129
	v_cvt_pk_bf16_f32 v129, v130, v131
	v_cvt_pk_bf16_f32 v131, v134, v135
	v_add_co_u32_e32 v134, vcc, s0, v132
	v_cvt_pk_bf16_f32 v130, v156, v157
	s_nop 0
	v_addc_co_u32_e32 v135, vcc, 0, v133, vcc
	global_store_dwordx4 v[134:135], v[128:131], off
	v_pk_mul_f32 v[134:135], v[82:83], v[18:19]
	s_mov_b32 s0, 0x48000
	v_pk_mul_f32 v[130:131], v[86:87], v[22:23]
	v_pk_mul_f32 v[128:129], v[84:85], v[20:21]
	v_pk_mul_f32 v[156:157], v[80:81], v[16:17]
	v_cvt_pk_bf16_f32 v128, v128, v129
	v_cvt_pk_bf16_f32 v129, v130, v131
	v_cvt_pk_bf16_f32 v131, v134, v135
	v_add_co_u32_e32 v134, vcc, s0, v132
	v_cvt_pk_bf16_f32 v130, v156, v157
	s_nop 0
	v_addc_co_u32_e32 v135, vcc, 0, v133, vcc
	global_store_dwordx4 v[134:135], v[128:131], off
	v_pk_mul_f32 v[134:135], v[74:75], v[10:11]
	s_mov_b32 s0, 0x50000
	v_pk_mul_f32 v[130:131], v[78:79], v[14:15]
	v_pk_mul_f32 v[128:129], v[76:77], v[12:13]
	v_pk_mul_f32 v[156:157], v[72:73], v[8:9]
	v_cvt_pk_bf16_f32 v128, v128, v129
	v_cvt_pk_bf16_f32 v129, v130, v131
	v_cvt_pk_bf16_f32 v131, v134, v135
	v_add_co_u32_e32 v134, vcc, s0, v132
	v_cvt_pk_bf16_f32 v130, v156, v157
	s_nop 0
	v_addc_co_u32_e32 v135, vcc, 0, v133, vcc
	global_store_dwordx4 v[134:135], v[128:131], off
	v_pk_mul_f32 v[134:135], v[66:67], v[2:3]
	v_pk_mul_f32 v[156:157], v[64:65], v[0:1]
	v_pk_mul_f32 v[130:131], v[70:71], v[6:7]
	v_pk_mul_f32 v[128:129], v[68:69], v[4:5]
	v_add_co_u32_e32 v132, vcc, 0x58000, v132
	v_cvt_pk_bf16_f32 v128, v128, v129
	v_cvt_pk_bf16_f32 v129, v130, v131
	v_cvt_pk_bf16_f32 v130, v156, v157
	v_cvt_pk_bf16_f32 v131, v134, v135
	v_addc_co_u32_e32 v133, vcc, 0, v133, vcc
	global_store_dwordx4 v[132:133], v[128:131], off

; #define PG8_STAGE(bufoff, gbase, voff) do { _Pragma("unroll") for (int _i = 0; _i < 2; ++_i) \
;         __builtin_amdgcn_global_load_lds((const unsigned*)((const char*)(gbase) + (voff)[_i]), (PG8_LAS unsigned*)(lds + (bufoff) + ldsw + _i * 8192), 16, 0, 0); } while (0)
; #define PG8_WAIT_V(n) asm volatile("s_waitcnt vmcnt(" #n ")" ::: "memory")
; #define PG8_BAR __builtin_amdgcn_s_barrier()
; template <class Epi, class Sched>
; __device__ __forceinline__ void gemm_phase(PG8_LAS unsigned char* lds, const Gemm g, const Sched& S, const Epi& E) {
;     const int tid = threadIdx.x, wid = __builtin_amdgcn_readfirstlane(tid >> 6), lane = tid & 63, wr = wid >> 2, wc = wid & 3, fr = lane & 15, fq = lane >> 4;
;     const int K = g.K, nt = K / BK;
;     unsigned voffA[2], voffB[2];
; #pragma unroll
;     for (int i = 0; i < 2; ++i) { int R, C; stage_rc(tid * 16 + i * 8192, R, C); const int Rb = Epi::PERM ? ((R & ~31) + perm32(R & 31)) : R;
;         voffA[i] = (unsigned)(R * K + C) * 2u; voffB[i] = (unsigned)(Rb * K + C) * 2u; }
;     const size_t kstep = (size_t)(BK * 2);
;     const size_t hstep = (size_t)HALF * K * 2;
;     const size_t tstep = 2 * hstep;
;     const unsigned ldsw = (unsigned)wid * 1024u;
;     const int aoff = lds_byte(wr * 64 + fr, fq * 8), boff = lds_byte(wc * 32 + fr, fq * 8);
;     ...
;     Unit cur, nxt; int ui = 0;
;     if (!S.next(0, cur)) return;
;     f32x4 acc[2][2][4][2];
; #pragma unroll
;     for (int a = 0; a < 2; ++a)
; #pragma unroll
;         for (int b = 0; b < 2; ++b)
; #pragma unroll
;             for (int m = 0; m < 4; ++m)
; #pragma unroll
;                 for (int n = 0; n < 2; ++n) acc[a][b][m][n] = (f32x4){0.f, 0.f, 0.f, 0.f};
;     bf16x8 At[4][2], B0[2][2], B1[2][2];
;     const char* cA = (const char*)g.A + (size_t)cur.pm * tstep; const char* cB = (const char*)g.Bt + (size_t)cur.pn * tstep;
;     S.a_ready(cur);
;     PG8_STAGE(PG8_SB(0, 0), cB, voffB); PG8_STAGE(PG8_SA(0, 0), cA, voffA); PG8_STAGE(PG8_SB(0, 1), cB + hstep, voffB); PG8_STAGE(PG8_SA(0, 1), cA + hstep, voffA);
;     if (wr == 1) PG8_BAR;
;     PG8_WAIT_V(4); PG8_BAR;
;     PG8_STAGE(PG8_SB(1, 0), cB + kstep, voffB); PG8_STAGE(PG8_SA(1, 0), cA + kstep, voffA); PG8_STAGE(PG8_SB(1, 1), cB + hstep + kstep, voffB);
;     PG8_WAIT_V(6); PG8_BAR;
.LBB0_658:
	s_add_u32 s0, s58, 0xfc86000
	s_addc_u32 s1, s59, 0
	s_lshl_b32 s4, s4, 5
	s_and_b32 s10, s4, 0x60
	s_mov_b64 s[4:5], 0x80
	s_add_i32 m0, s29, 0x18000
	v_lshl_add_u64 v[6:7], v[6:7], 0, s[4:5]
	s_lshl_b32 s8, s3, 13
	s_lshl_b32 s11, s10, 7
	v_readfirstlane_b32 s98, v242
	s_lshr_b32 s98, s98, 8
	s_waitcnt vmcnt(2)
	s_barrier
	global_load_lds_dwordx4 v[6:7], off
	v_lshl_add_u64 v[4:5], v[4:5], 0, s[4:5]
	s_add_i32 m0, s29, 0x1a000
	s_add_i32 s50, s29, 0x8000
	s_add_i32 s51, s29, 0xa000
	global_load_lds_dwordx4 v[4:5], off
	v_lshl_add_u64 v[2:3], v[2:3], 0, s[4:5]
	s_mov_b32 m0, s50
	s_add_u32 s6, s34, 0x80080
	global_load_lds_dwordx4 v[2:3], off
	v_lshl_add_u64 v[0:1], v[0:1], 0, s[4:5]
	s_mov_b32 m0, s51
	s_addc_u32 s7, s35, 0
	global_load_lds_dwordx4 v[0:1], off
	s_add_i32 m0, s29, 0x1c000
	v_lshl_add_u64 v[0:1], s[6:7], 0, v[146:147]
	global_load_lds_dwordx4 v[0:1], off
	v_lshl_add_u64 v[0:1], s[6:7], 0, v[150:151]
	s_add_i32 m0, s29, 0x1e000
	s_sext_i32_i8 s69, s2
	global_load_lds_dwordx4 v[0:1], off
	v_and_b32_e32 v0, 15, v242
	v_lshlrev_b32_e32 v1, 1, v11
	v_lshlrev_b32_e32 v2, 2, v242
	v_lshlrev_b32_e32 v3, 6, v242
	s_movk_i32 s2, 0x3c0
	v_lshl_or_b32 v166, s3, 6, v0
	v_lshl_or_b32 v0, v0, 6, v1
	v_and_b32_e32 v2, 32, v2
	v_and_or_b32 v1, v3, s2, v1
	v_bitop3_b32 v167, s11, v1, v2 bitop3:0xf6
	v_lshlrev_b32_e32 v1, 9, v242
	v_bitop3_b32 v0, v0, s8, v2 bitop3:0xde
	v_and_b32_e32 v1, 0x70000, v1
	v_lshlrev_b32_e32 v2, 12, v10
	v_or3_b32 v1, v8, v1, v2
	v_add_u32_e32 v152, v1, v9
	v_lshlrev_b32_e32 v1, 5, v12
	s_waitcnt vmcnt(6)
	v_and_b32_e32 v1, 0xf0000, v1
	v_or3_b32 v1, v8, v1, v2
	s_add_i32 s66, 0, 0x10000
	s_add_i32 s67, 0, 0x14000
	s_ashr_i32 s64, s62, 31
	s_mov_b32 s65, s62
	v_or_b32_e32 v168, s10, v11
	v_mov_b32_e32 v153, v147
	v_add_u32_e32 v154, v1, v9
	v_mov_b32_e32 v155, v147
	v_mov_b64_e32 v[156:157], 0x400
	v_mov_b64_e32 v[158:159], 0x3ff
	v_add_u32_e32 v169, s66, v167
	v_add_u32_e32 v170, 0, v0
	v_add_u32_e32 v171, s67, v167
	s_mov_b64 s[6:7], 0x6a04000
	s_mov_b32 s68, 0x6a04000
	s_mov_b32 s8, 0x3f9837f0
	s_barrier

; #define PG8_STAGE(bufoff, gbase, voff) do { _Pragma("unroll") for (int _i = 0; _i < 2; ++_i) \
;         __builtin_amdgcn_global_load_lds((const unsigned*)((const char*)(gbase) + (voff)[_i]), (PG8_LAS unsigned*)(lds + (bufoff) + ldsw + _i * 8192), 16, 0, 0); } while (0)
; #define PG8_LDA(dst, b, h) do { _Pragma("unroll") for (int m = 0; m < 4; ++m) _Pragma("unroll") for (int k = 0; k < 2; ++k) dst[m][k] = *(const PG8_LAS bf16x8*)(lds + PG8_SA(b, h) + aoff + m * 2048 + k * 1024); } while (0)
; #define PG8_LDB(dst, b, h) do { _Pragma("unroll") for (int n = 0; n < 2; ++n) _Pragma("unroll") for (int k = 0; k < 2; ++k) dst[n][k] = *(const PG8_LAS bf16x8*)(lds + PG8_SB(b, h) + boff + n * 2048 + k * 1024); } while (0)
; #define PG8_MMA(ai, bj, At, Bt) do { __builtin_amdgcn_s_setprio(1); _Pragma("unroll") for (int m = 0; m < 4; ++m) _Pragma("unroll") for (int n = 0; n < 2; ++n) _Pragma("unroll") for (int k = 0; k < 2; ++k) \
;         acc[ai][bj][m][n] = __builtin_amdgcn_mfma_f32_16x16x32_bf16(Bt[n][k], At[m][k], acc[ai][bj][m][n], 0, 0, 0); __builtin_amdgcn_s_setprio(0); } while (0)
; #define PG8_WAIT_V(n) asm volatile("s_waitcnt vmcnt(" #n ")" ::: "memory")
; #define PG8_WAIT_L(n) asm volatile("s_waitcnt lgkmcnt(" #n ")" ::: "memory")
; #define PG8_BAR __builtin_amdgcn_s_barrier()
; template <class Epi, class Sched>
; __device__ __forceinline__ void gemm_phase(PG8_LAS unsigned char* lds, const Gemm g, const Sched& S, const Epi& E) {
;     ...
;             const char* a1 = cA + (size_t)(t + 1) * kstep;
;             const char* a2 = last ? nA : cA + (size_t)(t + 2) * kstep; const char* b2 = last ? nB : cB + (size_t)(t + 2) * kstep;
;             const char* a3 = a2 + kstep; const char* b3 = b2 + kstep;
;             if (last && has_next) S.a_ready(nxt);
;             PG8_LDB(B0, 0, 0); PG8_SCHED; PG8_LDA(At, 0, 0); PG8_STAGE(PG8_SA(1, 1), a1 + hstep, voffA);
;             PG8_WAIT_L(8); PG8_BAR; PG8_WAIT_L(0); PG8_MMA(0, 0, At, B0); PG8_BAR; PG8_SCHED;
;             PG8_LDB(B1, 0, 1); PG8_STAGE(PG8_SB(0, 0), b2, voffB);
;             PG8_BAR; PG8_WAIT_L(0); PG8_MMA(0, 1, At, B1); PG8_BAR;
;             PG8_LDA(At, 0, 1); PG8_STAGE(PG8_SA(0, 0), a2, voffA);
;             PG8_BAR; PG8_WAIT_L(0); PG8_MMA(1, 0, At, B0); PG8_BAR; PG8_SCHED;
;             PG8_STAGE(PG8_SB(0, 1), b2 + hstep, voffB);
;             PG8_WAIT_V(6); PG8_BAR; PG8_MMA(1, 1, At, B1); PG8_BAR;
.LBB0_666:
	s_setprio 0
	ds_read_b128 v[128:131], v169
	ds_read_b128 v[132:135], v169 offset:1024
	ds_read_b128 v[136:139], v169 offset:2048
	ds_read_b128 v[140:143], v169 offset:3072
	ds_read_b128 v[160:163], v170
	ds_read_b128 v[172:175], v170 offset:1024
	ds_read_b128 v[176:179], v170 offset:2048
	ds_read_b128 v[180:183], v170 offset:3072
	ds_read_b128 v[184:187], v170 offset:4096
	ds_read_b128 v[188:191], v170 offset:5120
	ds_read_b128 v[192:195], v170 offset:6144
	ds_read_b128 v[196:199], v170 offset:7168
	ds_read_b128 v[200:203], v171
	ds_read_b128 v[204:207], v171 offset:1024
	ds_read_b128 v[208:211], v171 offset:2048
	ds_read_b128 v[212:215], v171 offset:3072
	s_add_u32 s10, s30, 0xfff80080
	s_addc_u32 s11, s31, -1
	s_cmp_eq_u32 s74, 28
	s_cselect_b32 s39, s19, s11
	s_cselect_b32 s38, s70, s10
	s_cselect_b32 s35, s17, s73
	s_cselect_b32 s34, s71, s72
	v_lshl_add_u64 v[164:165], s[30:31], 0, v[152:153]
	s_add_i32 m0, s29, 0xc000
	s_nop 0
	global_load_lds_dwordx4 v[164:165], off
	v_lshl_add_u64 v[164:165], s[30:31], 0, v[154:155]
	s_add_i32 m0, s29, 0xe000
	s_nop 0
	global_load_lds_dwordx4 v[164:165], off
	s_waitcnt vmcnt(8)
	s_waitcnt lgkmcnt(0)
	s_setprio 1
	s_barrier
	v_mfma_f32_16x16x32_bf16 v[120:123], v[128:131], v[160:163], v[120:123]
	v_mfma_f32_16x16x32_bf16 v[124:127], v[136:139], v[160:163], v[124:127]
	v_mfma_f32_16x16x32_bf16 v[112:115], v[128:131], v[176:179], v[112:115]
	v_mfma_f32_16x16x32_bf16 v[116:119], v[136:139], v[176:179], v[116:119]
	v_mfma_f32_16x16x32_bf16 v[96:99], v[128:131], v[184:187], v[96:99]
	v_mfma_f32_16x16x32_bf16 v[88:91], v[136:139], v[184:187], v[88:91]
	v_mfma_f32_16x16x32_bf16 v[80:83], v[128:131], v[192:195], v[80:83]
	v_mfma_f32_16x16x32_bf16 v[72:75], v[136:139], v[192:195], v[72:75]
	v_mfma_f32_16x16x32_bf16 v[120:123], v[132:135], v[172:175], v[120:123]
	v_mfma_f32_16x16x32_bf16 v[124:127], v[140:143], v[172:175], v[124:127]
	v_mfma_f32_16x16x32_bf16 v[112:115], v[132:135], v[180:183], v[112:115]
	v_mfma_f32_16x16x32_bf16 v[116:119], v[140:143], v[180:183], v[116:119]
	v_mfma_f32_16x16x32_bf16 v[96:99], v[132:135], v[188:191], v[96:99]
	v_mfma_f32_16x16x32_bf16 v[88:91], v[140:143], v[188:191], v[88:91]
	v_mfma_f32_16x16x32_bf16 v[80:83], v[132:135], v[196:199], v[80:83]
	v_mfma_f32_16x16x32_bf16 v[72:75], v[140:143], v[196:199], v[72:75]
	v_mfma_f32_16x16x32_bf16 v[108:111], v[200:203], v[160:163], v[108:111]
	v_mfma_f32_16x16x32_bf16 v[104:107], v[208:211], v[160:163], v[104:107]
	v_mfma_f32_16x16x32_bf16 v[100:103], v[200:203], v[176:179], v[100:103]
	v_mfma_f32_16x16x32_bf16 v[92:95], v[208:211], v[176:179], v[92:95]
	v_mfma_f32_16x16x32_bf16 v[84:87], v[200:203], v[184:187], v[84:87]
	v_mfma_f32_16x16x32_bf16 v[76:79], v[208:211], v[184:187], v[76:79]
	v_mfma_f32_16x16x32_bf16 v[68:71], v[200:203], v[192:195], v[68:71]
	v_mfma_f32_16x16x32_bf16 v[64:67], v[208:211], v[192:195], v[64:67]
	v_mfma_f32_16x16x32_bf16 v[108:111], v[204:207], v[172:175], v[108:111]
	v_mfma_f32_16x16x32_bf16 v[104:107], v[212:215], v[172:175], v[104:107]
	v_mfma_f32_16x16x32_bf16 v[100:103], v[204:207], v[180:183], v[100:103]
	v_mfma_f32_16x16x32_bf16 v[92:95], v[212:215], v[180:183], v[92:95]
	v_mfma_f32_16x16x32_bf16 v[84:87], v[204:207], v[188:191], v[84:87]
	v_mfma_f32_16x16x32_bf16 v[76:79], v[212:215], v[188:191], v[76:79]
	v_mfma_f32_16x16x32_bf16 v[68:71], v[204:207], v[196:199], v[68:71]
	v_mfma_f32_16x16x32_bf16 v[64:67], v[212:215], v[196:199], v[64:67]
	s_barrier
	s_setprio 0
	ds_read_b128 v[160:163], v170 offset:16384
	ds_read_b128 v[172:175], v170 offset:17408
	ds_read_b128 v[176:179], v170 offset:18432
	ds_read_b128 v[180:183], v170 offset:19456
	ds_read_b128 v[184:187], v170 offset:20480
	ds_read_b128 v[188:191], v170 offset:21504
	ds_read_b128 v[192:195], v170 offset:22528
	ds_read_b128 v[196:199], v170 offset:23552
	s_add_i32 s10, s66, s45
	v_lshl_add_u64 v[164:165], s[34:35], 0, v[146:147]
	s_mov_b32 m0, s10
	s_nop 0
	global_load_lds_dwordx4 v[164:165], off
	v_lshl_add_u64 v[216:217], s[34:35], 0, v[150:151]
	s_add_i32 m0, s10, 0x2000
	s_nop 0
	global_load_lds_dwordx4 v[216:217], off
	s_mov_b32 m0, s29
	v_lshl_add_u64 v[218:219], s[38:39], 0, v[144:145]
	global_load_lds_dwordx4 v[218:219], off
	v_lshl_add_u64 v[220:221], s[38:39], 0, v[148:149]
	s_mov_b32 m0, s46
	s_nop 0
	global_load_lds_dwordx4 v[220:221], off
	s_add_u32 s10, s34, 0x80000
	s_addc_u32 s11, s35, 0
	s_add_i32 s33, s67, s45
	v_lshl_add_u64 v[246:247], s[10:11], 0, v[146:147]
	s_mov_b32 m0, s33
	s_nop 0
	global_load_lds_dwordx4 v[246:247], off
	v_lshl_add_u64 v[246:247], s[10:11], 0, v[150:151]
	s_add_i32 m0, s33, 0x2000
	s_nop 0
	global_load_lds_dwordx4 v[246:247], off
	s_waitcnt vmcnt(8)
	s_waitcnt lgkmcnt(0)
	s_setprio 1
	s_barrier
; #define PG8_STAGE(bufoff, gbase, voff) do { _Pragma("unroll") for (int _i = 0; _i < 2; ++_i) \
;         __builtin_amdgcn_global_load_lds((const unsigned*)((const char*)(gbase) + (voff)[_i]), (PG8_LAS unsigned*)(lds + (bufoff) + ldsw + _i * 8192), 16, 0, 0); } while (0)
; #define PG8_LDA(dst, b, h) do { _Pragma("unroll") for (int m = 0; m < 4; ++m) _Pragma("unroll") for (int k = 0; k < 2; ++k) dst[m][k] = *(const PG8_LAS bf16x8*)(lds + PG8_SA(b, h) + aoff + m * 2048 + k * 1024); } while (0)
; #define PG8_LDB(dst, b, h) do { _Pragma("unroll") for (int n = 0; n < 2; ++n) _Pragma("unroll") for (int k = 0; k < 2; ++k) dst[n][k] = *(const PG8_LAS bf16x8*)(lds + PG8_SB(b, h) + boff + n * 2048 + k * 1024); } while (0)
; #define PG8_MMA(ai, bj, At, Bt) do { __builtin_amdgcn_s_setprio(1); _Pragma("unroll") for (int m = 0; m < 4; ++m) _Pragma("unroll") for (int n = 0; n < 2; ++n) _Pragma("unroll") for (int k = 0; k < 2; ++k) \
;         acc[ai][bj][m][n] = __builtin_amdgcn_mfma_f32_16x16x32_bf16(Bt[n][k], At[m][k], acc[ai][bj][m][n], 0, 0, 0); __builtin_amdgcn_s_setprio(0); } while (0)
; #define PG8_WAIT_V(n) asm volatile("s_waitcnt vmcnt(" #n ")" ::: "memory")
; #define PG8_WAIT_L(n) asm volatile("s_waitcnt lgkmcnt(" #n ")" ::: "memory")
; #define PG8_BAR __builtin_amdgcn_s_barrier()
; #define PG8_SCHED __builtin_amdgcn_sched_barrier(0)
; template <class Epi, class Sched>
; __device__ __forceinline__ void gemm_phase(PG8_LAS unsigned char* lds, const Gemm g, const Sched& S, const Epi& E) {
;     ...
;             PG8_BAR; PG8_WAIT_L(0); PG8_MMA(1, 0, At, B0); PG8_BAR; PG8_SCHED;
;             PG8_STAGE(PG8_SB(0, 1), b2 + hstep, voffB);
;             PG8_WAIT_V(6); PG8_BAR; PG8_MMA(1, 1, At, B1); PG8_BAR;
;             PG8_LDB(B0, 1, 0); PG8_SCHED; PG8_LDA(At, 1, 0); PG8_STAGE(PG8_SA(0, 1), a2 + hstep, voffA);
;             PG8_WAIT_L(8); PG8_BAR; PG8_WAIT_L(0); PG8_MMA(0, 0, At, B0); PG8_BAR; PG8_SCHED;
;             PG8_LDB(B1, 1, 1); PG8_STAGE(PG8_SB(1, 0), b3, voffB);
;             PG8_BAR; PG8_WAIT_L(0); PG8_MMA(0, 1, At, B1); PG8_BAR;
;             PG8_LDA(At, 1, 1); PG8_STAGE(PG8_SA(1, 0), a3, voffA);
;             PG8_BAR; PG8_WAIT_L(0); PG8_MMA(1, 0, At, B0); PG8_BAR; PG8_SCHED;
	v_mfma_f32_16x16x32_bf16 v[60:63], v[128:131], v[160:163], v[60:63]
	v_mfma_f32_16x16x32_bf16 v[56:59], v[136:139], v[160:163], v[56:59]
	v_mfma_f32_16x16x32_bf16 v[48:51], v[128:131], v[176:179], v[48:51]
	v_mfma_f32_16x16x32_bf16 v[40:43], v[136:139], v[176:179], v[40:43]
	v_mfma_f32_16x16x32_bf16 v[32:35], v[128:131], v[184:187], v[32:35]
	v_mfma_f32_16x16x32_bf16 v[24:27], v[136:139], v[184:187], v[24:27]
	v_mfma_f32_16x16x32_bf16 v[16:19], v[128:131], v[192:195], v[16:19]
	v_mfma_f32_16x16x32_bf16 v[8:11], v[136:139], v[192:195], v[8:11]
	s_add_i32 s33, 0, 0x18000
	v_mfma_f32_16x16x32_bf16 v[60:63], v[132:135], v[172:175], v[60:63]
	v_mfma_f32_16x16x32_bf16 v[56:59], v[140:143], v[172:175], v[56:59]
	v_mfma_f32_16x16x32_bf16 v[48:51], v[132:135], v[180:183], v[48:51]
	v_mfma_f32_16x16x32_bf16 v[40:43], v[140:143], v[180:183], v[40:43]
	v_mfma_f32_16x16x32_bf16 v[32:35], v[132:135], v[188:191], v[32:35]
	v_mfma_f32_16x16x32_bf16 v[24:27], v[140:143], v[188:191], v[24:27]
	v_mfma_f32_16x16x32_bf16 v[16:19], v[132:135], v[196:199], v[16:19]
	v_mfma_f32_16x16x32_bf16 v[8:11], v[140:143], v[196:199], v[8:11]
	v_mfma_f32_16x16x32_bf16 v[52:55], v[200:203], v[160:163], v[52:55]
	v_mfma_f32_16x16x32_bf16 v[44:47], v[208:211], v[160:163], v[44:47]
	v_mfma_f32_16x16x32_bf16 v[36:39], v[200:203], v[176:179], v[36:39]
	v_mfma_f32_16x16x32_bf16 v[28:31], v[208:211], v[176:179], v[28:31]
	v_mfma_f32_16x16x32_bf16 v[20:23], v[200:203], v[184:187], v[20:23]
	v_mfma_f32_16x16x32_bf16 v[12:15], v[208:211], v[184:187], v[12:15]
	v_mfma_f32_16x16x32_bf16 v[4:7], v[200:203], v[192:195], v[4:7]
	v_mfma_f32_16x16x32_bf16 v[0:3], v[208:211], v[192:195], v[0:3]
	v_mfma_f32_16x16x32_bf16 v[52:55], v[204:207], v[172:175], v[52:55]
	v_mfma_f32_16x16x32_bf16 v[44:47], v[212:215], v[172:175], v[44:47]
	v_mfma_f32_16x16x32_bf16 v[36:39], v[204:207], v[180:183], v[36:39]
	v_mfma_f32_16x16x32_bf16 v[28:31], v[212:215], v[180:183], v[28:31]
	v_mfma_f32_16x16x32_bf16 v[20:23], v[204:207], v[188:191], v[20:23]
	v_mfma_f32_16x16x32_bf16 v[12:15], v[212:215], v[188:191], v[12:15]
	v_mfma_f32_16x16x32_bf16 v[4:7], v[204:207], v[196:199], v[4:7]
	v_mfma_f32_16x16x32_bf16 v[0:3], v[212:215], v[196:199], v[0:3]
	s_barrier
	s_setprio 0
	ds_read_b128 v[128:131], v169 offset:32768
	ds_read_b128 v[132:135], v169 offset:33792
	ds_read_b128 v[136:139], v169 offset:34816
	ds_read_b128 v[140:143], v169 offset:35840
	ds_read_b128 v[160:163], v170 offset:32768
	ds_read_b128 v[172:175], v170 offset:33792
	ds_read_b128 v[176:179], v170 offset:34816
	ds_read_b128 v[180:183], v170 offset:35840
	ds_read_b128 v[184:187], v170 offset:36864
	ds_read_b128 v[188:191], v170 offset:37888
	ds_read_b128 v[192:195], v170 offset:38912
	ds_read_b128 v[196:199], v170 offset:39936
	ds_read_b128 v[200:203], v171 offset:32768
	ds_read_b128 v[204:207], v171 offset:33792
	ds_read_b128 v[208:211], v171 offset:34816
	ds_read_b128 v[212:215], v171 offset:35840
	s_add_u32 s10, s38, 0x80000
	s_addc_u32 s11, s39, 0
	s_mov_b32 m0, s47
	v_lshl_add_u64 v[246:247], s[10:11], 0, v[144:145]
	global_load_lds_dwordx4 v[246:247], off
	v_lshl_add_u64 v[246:247], s[10:11], 0, v[148:149]
	s_mov_b32 m0, s48
	s_nop 0
	global_load_lds_dwordx4 v[246:247], off
	s_waitcnt vmcnt(8)
	s_waitcnt lgkmcnt(0)
	s_setprio 1
	s_barrier
	v_mfma_f32_16x16x32_bf16 v[120:123], v[128:131], v[160:163], v[120:123]
	v_mfma_f32_16x16x32_bf16 v[124:127], v[136:139], v[160:163], v[124:127]
	v_mfma_f32_16x16x32_bf16 v[112:115], v[128:131], v[176:179], v[112:115]
	v_mfma_f32_16x16x32_bf16 v[116:119], v[136:139], v[176:179], v[116:119]
	v_mfma_f32_16x16x32_bf16 v[96:99], v[128:131], v[184:187], v[96:99]
	v_mfma_f32_16x16x32_bf16 v[88:91], v[136:139], v[184:187], v[88:91]
	v_mfma_f32_16x16x32_bf16 v[80:83], v[128:131], v[192:195], v[80:83]
	v_mfma_f32_16x16x32_bf16 v[72:75], v[136:139], v[192:195], v[72:75]
	v_mfma_f32_16x16x32_bf16 v[120:123], v[132:135], v[172:175], v[120:123]
	v_mfma_f32_16x16x32_bf16 v[124:127], v[140:143], v[172:175], v[124:127]
	v_mfma_f32_16x16x32_bf16 v[112:115], v[132:135], v[180:183], v[112:115]
	v_mfma_f32_16x16x32_bf16 v[116:119], v[140:143], v[180:183], v[116:119]
	v_mfma_f32_16x16x32_bf16 v[96:99], v[132:135], v[188:191], v[96:99]
	v_mfma_f32_16x16x32_bf16 v[88:91], v[140:143], v[188:191], v[88:91]
	v_mfma_f32_16x16x32_bf16 v[80:83], v[132:135], v[196:199], v[80:83]
	v_mfma_f32_16x16x32_bf16 v[72:75], v[140:143], v[196:199], v[72:75]
	v_mfma_f32_16x16x32_bf16 v[108:111], v[200:203], v[160:163], v[108:111]
	v_mfma_f32_16x16x32_bf16 v[104:107], v[208:211], v[160:163], v[104:107]
	v_mfma_f32_16x16x32_bf16 v[100:103], v[200:203], v[176:179], v[100:103]
	v_mfma_f32_16x16x32_bf16 v[92:95], v[208:211], v[176:179], v[92:95]
	v_mfma_f32_16x16x32_bf16 v[84:87], v[200:203], v[184:187], v[84:87]
	v_mfma_f32_16x16x32_bf16 v[76:79], v[208:211], v[184:187], v[76:79]
	v_mfma_f32_16x16x32_bf16 v[68:71], v[200:203], v[192:195], v[68:71]
	v_mfma_f32_16x16x32_bf16 v[64:67], v[208:211], v[192:195], v[64:67]
	v_mfma_f32_16x16x32_bf16 v[108:111], v[204:207], v[172:175], v[108:111]
	v_mfma_f32_16x16x32_bf16 v[104:107], v[212:215], v[172:175], v[104:107]
	v_mfma_f32_16x16x32_bf16 v[100:103], v[204:207], v[180:183], v[100:103]
	v_mfma_f32_16x16x32_bf16 v[92:95], v[212:215], v[180:183], v[92:95]
	v_mfma_f32_16x16x32_bf16 v[84:87], v[204:207], v[188:191], v[84:87]
	v_mfma_f32_16x16x32_bf16 v[76:79], v[212:215], v[188:191], v[76:79]
	v_mfma_f32_16x16x32_bf16 v[68:71], v[204:207], v[196:199], v[68:71]
	v_mfma_f32_16x16x32_bf16 v[64:67], v[212:215], v[196:199], v[64:67]
	s_barrier
; #define PG8_STAGE(bufoff, gbase, voff) do { _Pragma("unroll") for (int _i = 0; _i < 2; ++_i) \
;         __builtin_amdgcn_global_load_lds((const unsigned*)((const char*)(gbase) + (voff)[_i]), (PG8_LAS unsigned*)(lds + (bufoff) + ldsw + _i * 8192), 16, 0, 0); } while (0)
; #define PG8_LDA(dst, b, h) do { _Pragma("unroll") for (int m = 0; m < 4; ++m) _Pragma("unroll") for (int k = 0; k < 2; ++k) dst[m][k] = *(const PG8_LAS bf16x8*)(lds + PG8_SA(b, h) + aoff + m * 2048 + k * 1024); } while (0)
; #define PG8_MMA(ai, bj, At, Bt) do { __builtin_amdgcn_s_setprio(1); _Pragma("unroll") for (int m = 0; m < 4; ++m) _Pragma("unroll") for (int n = 0; n < 2; ++n) _Pragma("unroll") for (int k = 0; k < 2; ++k) \
;         acc[ai][bj][m][n] = __builtin_amdgcn_mfma_f32_16x16x32_bf16(Bt[n][k], At[m][k], acc[ai][bj][m][n], 0, 0, 0); __builtin_amdgcn_s_setprio(0); } while (0)
; #define PG8_WAIT_V(n) asm volatile("s_waitcnt vmcnt(" #n ")" ::: "memory")
; template <class Epi, class Sched>
; __device__ __forceinline__ void gemm_phase(PG8_LAS unsigned char* lds, const Gemm g, const Sched& S, const Epi& E) {
;     ...
;             PG8_LDA(At, 1, 1); PG8_STAGE(PG8_SA(1, 0), a3, voffA);
;             PG8_BAR; PG8_WAIT_L(0); PG8_MMA(1, 0, At, B0); PG8_BAR; PG8_SCHED;
;             PG8_STAGE(PG8_SB(1, 1), b3 + hstep, voffB);
;             PG8_WAIT_V(6); PG8_BAR; PG8_MMA(1, 1, At, B1); PG8_BAR;
;         }
;         E(acc, cur, wr, wc, fr, fq); S.done(cur);
;         if (!has_next) break;
;     __device__ __forceinline__ void operator()(const AccT& acc, const pg8::Unit& u, int wr, int wc, int fr, int fq) const {
;         const int row0 = u.pm * 256 + wr * 64 + fr, col0 = u.pn * 256 + wc * 32 + 8 * fq;
;         const float* ga = mod + (u.pm >= 64 ? 12288 : 0) + 2 * 2048;
;         f32x4 gv[2][2];
; #pragma unroll
;         for (int bj = 0; bj < 2; ++bj)
; #pragma unroll
;             for (int n = 0; n < 2; ++n) gv[bj][n] = *(const f32x4*)(ga + col0 + bj * 128 + n * 4);
; #pragma unroll
;         for (int ai = 0; ai < 2; ++ai) {
;             f32x4 xa[4][2], xb[4][2];
; #pragma unroll
;             for (int m = 0; m < 4; ++m) { const size_t off = (size_t)(row0 + ai * 128 + m * 16) * D + col0;
; #pragma unroll
;                 for (int bj = 0; bj < 2; ++bj) { xa[m][bj] = *(const f32x4*)(x + off + bj * 128); xb[m][bj] = *(const f32x4*)(x + off + bj * 128 + 4); } }
	s_setprio 0
	ds_read_b128 v[160:163], v170 offset:49152
	ds_read_b128 v[172:175], v170 offset:50176
	ds_read_b128 v[176:179], v170 offset:51200
	ds_read_b128 v[180:183], v170 offset:52224
	ds_read_b128 v[184:187], v170 offset:53248
	ds_read_b128 v[188:191], v170 offset:54272
	ds_read_b128 v[192:195], v170 offset:55296
	ds_read_b128 v[196:199], v170 offset:56320
	s_add_i32 s38, 0, 0x1c000
	s_add_i32 s10, s33, s45
	v_lshl_add_u64 v[164:165], v[164:165], 0, s[4:5]
	s_mov_b32 m0, s10
	s_nop 0
	global_load_lds_dwordx4 v[164:165], off
	v_lshl_add_u64 v[164:165], v[216:217], 0, s[4:5]
	s_add_i32 m0, s10, 0x2000
	s_nop 0
	global_load_lds_dwordx4 v[164:165], off
	s_mov_b32 m0, s50
	v_lshl_add_u64 v[164:165], v[218:219], 0, s[4:5]
	global_load_lds_dwordx4 v[164:165], off
	v_lshl_add_u64 v[164:165], v[220:221], 0, s[4:5]
	s_mov_b32 m0, s51
	s_nop 0
	global_load_lds_dwordx4 v[164:165], off
	s_add_u32 s10, s34, 0x80080
	s_addc_u32 s11, s35, 0
	s_add_i32 s33, s38, s45
	v_lshl_add_u64 v[246:247], s[10:11], 0, v[146:147]
	s_mov_b32 m0, s33
	s_nop 0
	global_load_lds_dwordx4 v[246:247], off
	v_lshl_add_u64 v[246:247], s[10:11], 0, v[150:151]
	s_add_i32 m0, s33, 0x2000
	s_nop 0
	global_load_lds_dwordx4 v[246:247], off
	s_waitcnt vmcnt(8)
	s_waitcnt lgkmcnt(0)
	s_setprio 1
	s_barrier
	v_mfma_f32_16x16x32_bf16 v[60:63], v[128:131], v[160:163], v[60:63]
	v_mfma_f32_16x16x32_bf16 v[56:59], v[136:139], v[160:163], v[56:59]
	v_mfma_f32_16x16x32_bf16 v[48:51], v[128:131], v[176:179], v[48:51]
	v_mfma_f32_16x16x32_bf16 v[40:43], v[136:139], v[176:179], v[40:43]
	v_mfma_f32_16x16x32_bf16 v[32:35], v[128:131], v[184:187], v[32:35]
	v_mfma_f32_16x16x32_bf16 v[24:27], v[136:139], v[184:187], v[24:27]
	v_mfma_f32_16x16x32_bf16 v[16:19], v[128:131], v[192:195], v[16:19]
	v_mfma_f32_16x16x32_bf16 v[8:11], v[136:139], v[192:195], v[8:11]
	s_add_i32 s74, s74, 2
	s_add_u32 s30, s30, 0x100
	s_addc_u32 s31, s31, 0
	s_add_u32 s72, s72, 0x100
	s_addc_u32 s73, s73, 0
	s_cmp_gt_u32 s74, 29
	v_mfma_f32_16x16x32_bf16 v[60:63], v[132:135], v[172:175], v[60:63]
	v_mfma_f32_16x16x32_bf16 v[56:59], v[140:143], v[172:175], v[56:59]
	v_mfma_f32_16x16x32_bf16 v[48:51], v[132:135], v[180:183], v[48:51]
	v_mfma_f32_16x16x32_bf16 v[40:43], v[140:143], v[180:183], v[40:43]
	v_mfma_f32_16x16x32_bf16 v[32:35], v[132:135], v[188:191], v[32:35]
	v_mfma_f32_16x16x32_bf16 v[24:27], v[140:143], v[188:191], v[24:27]
	v_mfma_f32_16x16x32_bf16 v[16:19], v[132:135], v[196:199], v[16:19]
	v_mfma_f32_16x16x32_bf16 v[8:11], v[140:143], v[196:199], v[8:11]
	v_mfma_f32_16x16x32_bf16 v[52:55], v[200:203], v[160:163], v[52:55]
	v_mfma_f32_16x16x32_bf16 v[44:47], v[208:211], v[160:163], v[44:47]
	v_mfma_f32_16x16x32_bf16 v[36:39], v[200:203], v[176:179], v[36:39]
	v_mfma_f32_16x16x32_bf16 v[28:31], v[208:211], v[176:179], v[28:31]
	v_mfma_f32_16x16x32_bf16 v[20:23], v[200:203], v[184:187], v[20:23]
	v_mfma_f32_16x16x32_bf16 v[12:15], v[208:211], v[184:187], v[12:15]
	v_mfma_f32_16x16x32_bf16 v[4:7], v[200:203], v[192:195], v[4:7]
	v_mfma_f32_16x16x32_bf16 v[0:3], v[208:211], v[192:195], v[0:3]
	v_mfma_f32_16x16x32_bf16 v[52:55], v[204:207], v[172:175], v[52:55]
	v_mfma_f32_16x16x32_bf16 v[44:47], v[212:215], v[172:175], v[44:47]
	v_mfma_f32_16x16x32_bf16 v[36:39], v[204:207], v[180:183], v[36:39]
	v_mfma_f32_16x16x32_bf16 v[28:31], v[212:215], v[180:183], v[28:31]
	v_mfma_f32_16x16x32_bf16 v[20:23], v[204:207], v[188:191], v[20:23]
	v_mfma_f32_16x16x32_bf16 v[12:15], v[212:215], v[188:191], v[12:15]
	v_mfma_f32_16x16x32_bf16 v[4:7], v[204:207], v[196:199], v[4:7]
	v_mfma_f32_16x16x32_bf16 v[0:3], v[212:215], v[196:199], v[0:3]
	s_barrier
	s_cbranch_scc0 .LBB0_666
	s_setprio 0
	s_cmp_lg_u32 s98, 0
	s_cbranch_scc1 .Lxa_666
	s_barrier
.Lxa_666:
	v_lshl_or_b32 v160, s69, 8, v168
	s_cmp_gt_i32 s28, 63
	v_ashrrev_i32_e32 v161, 31, v160
	v_lshl_add_u32 v164, s28, 8, v166
	s_cselect_b32 s10, 0xc000, 0
	v_lshlrev_b64 v[128:129], 2, v[160:161]
	v_ashrrev_i32_e32 v165, 31, v164
	s_add_u32 s10, s58, s10
	v_lshl_add_u64 v[162:163], s[36:37], 0, v[128:129]
	v_lshlrev_b64 v[130:131], 13, v[164:165]
	v_or_b32_e32 v220, 16, v164
	s_addc_u32 s11, s59, 0
	v_lshl_add_u64 v[130:131], v[162:163], 0, v[130:131]
	v_ashrrev_i32_e32 v221, 31, v220
	global_load_dwordx4 v[172:175], v[130:131], off offset:16
	global_load_dwordx4 v[176:179], v[130:131], off
	global_load_dwordx4 v[180:183], v[130:131], off offset:528
	global_load_dwordx4 v[184:187], v[130:131], off offset:512
	v_lshlrev_b64 v[130:131], 13, v[220:221]
	v_lshl_add_u64 v[128:129], s[10:11], 0, v[128:129]
	v_lshl_add_u64 v[200:201], v[162:163], 0, v[130:131]
	v_lshl_add_u64 v[130:131], v[128:129], 0, s[6:7]
	global_load_dwordx4 v[188:191], v[200:201], off offset:16
	global_load_dwordx4 v[192:195], v[200:201], off
	global_load_dwordx4 v[136:139], v[130:131], off offset:16
	global_load_dwordx4 v[132:135], v[130:131], off offset:512
	v_add_co_u32_e32 v128, vcc, s68, v128
	v_or_b32_e32 v236, 32, v164
	s_nop 0
	v_addc_co_u32_e32 v129, vcc, 0, v129, vcc
	global_load_dwordx4 v[140:143], v[128:129], off
	s_nop 0
	global_load_dwordx4 v[128:131], v[130:131], off offset:528
	s_nop 0
	global_load_dwordx4 v[196:199], v[200:201], off offset:512
	s_nop 0
	global_load_dwordx4 v[200:203], v[200:201], off offset:528
	v_ashrrev_i32_e32 v237, 31, v236
	v_lshlrev_b64 v[204:205], 13, v[236:237]
	v_lshl_add_u64 v[216:217], v[162:163], 0, v[204:205]
	global_load_dwordx4 v[204:207], v[216:217], off
	global_load_dwordx4 v[208:211], v[216:217], off offset:16
	global_load_dwordx4 v[212:215], v[216:217], off offset:528
	s_nop 0
	global_load_dwordx4 v[216:219], v[216:217], off offset:512
	v_or_b32_e32 v238, 48, v164
	v_ashrrev_i32_e32 v239, 31, v238
	v_lshlrev_b64 v[222:223], 12, v[164:165]
	v_lshlrev_b64 v[224:225], 13, v[238:239]
	v_lshlrev_b64 v[160:161], 1, v[160:161]
	v_lshl_add_u64 v[222:223], s[0:1], 0, v[222:223]
	v_lshl_add_u64 v[232:233], v[162:163], 0, v[224:225]
	v_lshlrev_b64 v[240:241], 12, v[220:221]
	v_lshl_add_u64 v[244:245], v[222:223], 0, v[160:161]
	global_load_dwordx4 v[220:223], v[232:233], off offset:16
	global_load_dwordx4 v[224:227], v[232:233], off
	global_load_dwordx4 v[228:231], v[232:233], off offset:528
	s_nop 0
	global_load_dwordx4 v[232:235], v[232:233], off offset:512
	s_and_b64 vcc, exec, s[2:3]
	s_mov_b32 s69, s16
	s_mov_b32 s28, s18
	s_mov_b64 s[34:35], s[26:27]
	s_mov_b64 s[30:31], s[20:21]
	s_waitcnt vmcnt(0)
;     __device__ __forceinline__ void operator()(const AccT& acc, const pg8::Unit& u, int wr, int wc, int fr, int fq) const {
;     ...
;             for (int m = 0; m < 4; ++m) { const size_t off = (size_t)(row0 + ai * 128 + m * 16) * D + col0;
; #pragma unroll
;                 for (int bj = 0; bj < 2; ++bj) {
;                     const f32x4 a = ALPHA * xa[m][bj] + gv[bj][0] * acc[ai][bj][m][0], b = ALPHA * xb[m][bj] + gv[bj][1] * acc[ai][bj][m][1];
;                     u32x4 w; w.x = pk_h2(a[0], a[1]); w.y = pk_h2(a[2], a[3]); w.z = pk_h2(b[0], b[1]); w.w = pk_h2(b[2], b[3]);
;                     *(u32x4*)(U1 + off + bj * 128) = w; } }
	v_pk_mul_f32 v[174:175], v[174:175], s[8:9] op_sel_hi:[1,0]
	v_pk_mul_f32 v[178:179], v[178:179], s[8:9] op_sel_hi:[1,0]
	v_pk_mul_f32 v[176:177], v[176:177], s[8:9] op_sel_hi:[1,0]
	v_pk_mul_f32 v[172:173], v[172:173], s[8:9] op_sel_hi:[1,0]
	v_pk_mul_f32 v[186:187], v[186:187], s[8:9] op_sel_hi:[1,0]
	v_pk_mul_f32 v[184:185], v[184:185], s[8:9] op_sel_hi:[1,0]
	v_pk_mul_f32 v[182:183], v[182:183], s[8:9] op_sel_hi:[1,0]
	v_pk_mul_f32 v[180:181], v[180:181], s[8:9] op_sel_hi:[1,0]
	v_pk_mul_f32 v[194:195], v[194:195], s[8:9] op_sel_hi:[1,0]
	v_pk_fma_f32 v[126:127], v[126:127], v[138:139], v[174:175]
	v_pk_fma_f32 v[124:125], v[124:125], v[136:137], v[172:173]
	v_pk_mul_f32 v[192:193], v[192:193], s[8:9] op_sel_hi:[1,0]
	v_pk_mul_f32 v[190:191], v[190:191], s[8:9] op_sel_hi:[1,0]
	v_pk_fma_f32 v[122:123], v[122:123], v[142:143], v[178:179]
	v_pk_fma_f32 v[120:121], v[120:121], v[140:141], v[176:177]
	v_pk_mul_f32 v[188:189], v[188:189], s[8:9] op_sel_hi:[1,0]
	v_pk_fma_f32 v[172:173], v[110:111], v[134:135], v[186:187]
	v_pk_fma_f32 v[110:111], v[108:109], v[132:133], v[184:185]
	v_cvt_pk_f16_f32 v108, v124, v125
	v_cvt_pk_f16_f32 v109, v126, v127
	v_pk_fma_f32 v[124:125], v[106:107], v[130:131], v[182:183]
	v_pk_fma_f32 v[104:105], v[104:105], v[128:129], v[180:181]
	v_cvt_pk_f16_f32 v106, v120, v121
	v_cvt_pk_f16_f32 v107, v122, v123
	v_pk_fma_f32 v[118:119], v[118:119], v[138:139], v[190:191]
	v_pk_fma_f32 v[116:117], v[116:117], v[136:137], v[188:189]
	v_cvt_pk_f16_f32 v110, v110, v111
	v_cvt_pk_f16_f32 v111, v172, v173
	v_pk_fma_f32 v[114:115], v[114:115], v[142:143], v[194:195]
	v_pk_fma_f32 v[126:127], v[112:113], v[140:141], v[192:193]
	v_cvt_pk_f16_f32 v112, v104, v105
	v_cvt_pk_f16_f32 v113, v124, v125
	global_store_dwordx4 v[244:245], v[106:109], off
	global_store_dwordx4 v[244:245], v[110:113], off offset:256
	v_cvt_pk_f16_f32 v104, v126, v127
	v_lshl_add_u64 v[108:109], s[0:1], 0, v[240:241]
	v_cvt_pk_f16_f32 v105, v114, v115
	v_cvt_pk_f16_f32 v106, v116, v117
	v_cvt_pk_f16_f32 v107, v118, v119
	v_lshl_add_u64 v[108:109], v[108:109], 0, v[160:161]
	global_store_dwordx4 v[108:109], v[104:107], off
	v_add_u32_e32 v172, 0x80, v164
	v_ashrrev_i32_e32 v173, 31, v172
	v_pk_mul_f32 v[104:105], v[198:199], s[8:9] op_sel_hi:[1,0]
	v_pk_mul_f32 v[106:107], v[196:197], s[8:9] op_sel_hi:[1,0]
	v_pk_fma_f32 v[102:103], v[102:103], v[134:135], v[104:105]
	v_pk_fma_f32 v[100:101], v[100:101], v[132:133], v[106:107]
	v_pk_mul_f32 v[104:105], v[202:203], s[8:9] op_sel_hi:[1,0]
	v_pk_mul_f32 v[106:107], v[200:201], s[8:9] op_sel_hi:[1,0]
	v_pk_fma_f32 v[104:105], v[94:95], v[130:131], v[104:105]
	v_pk_fma_f32 v[94:95], v[92:93], v[128:129], v[106:107]
	v_cvt_pk_f16_f32 v92, v100, v101
	v_cvt_pk_f16_f32 v93, v102, v103
	v_cvt_pk_f16_f32 v94, v94, v95
	v_cvt_pk_f16_f32 v95, v104, v105
	global_store_dwordx4 v[108:109], v[92:95], off offset:256
	v_pk_mul_f32 v[100:101], v[204:205], s[8:9] op_sel_hi:[1,0]
	v_add_u32_e32 v174, 0x90, v164
	v_pk_mul_f32 v[94:95], v[206:207], s[8:9] op_sel_hi:[1,0]
	v_lshlrev_b64 v[92:93], 12, v[236:237]
	v_pk_fma_f32 v[94:95], v[98:99], v[142:143], v[94:95]
	v_pk_fma_f32 v[96:97], v[96:97], v[140:141], v[100:101]
	v_pk_mul_f32 v[98:99], v[210:211], s[8:9] op_sel_hi:[1,0]
	v_pk_mul_f32 v[100:101], v[208:209], s[8:9] op_sel_hi:[1,0]
	v_pk_fma_f32 v[98:99], v[90:91], v[138:139], v[98:99]
	v_pk_fma_f32 v[90:91], v[88:89], v[136:137], v[100:101]
	v_lshl_add_u64 v[92:93], s[0:1], 0, v[92:93]
	v_cvt_pk_f16_f32 v88, v96, v97
	v_cvt_pk_f16_f32 v89, v94, v95
	v_cvt_pk_f16_f32 v90, v90, v91
	v_cvt_pk_f16_f32 v91, v98, v99
	v_lshl_add_u64 v[92:93], v[92:93], 0, v[160:161]
	global_store_dwordx4 v[92:93], v[88:91], off
	v_ashrrev_i32_e32 v175, 31, v174
	v_add_u32_e32 v176, 0xa0, v164
	v_pk_mul_f32 v[88:89], v[218:219], s[8:9] op_sel_hi:[1,0]
	v_pk_mul_f32 v[90:91], v[216:217], s[8:9] op_sel_hi:[1,0]
	v_pk_fma_f32 v[86:87], v[86:87], v[134:135], v[88:89]
	v_pk_fma_f32 v[84:85], v[84:85], v[132:133], v[90:91]
	v_pk_mul_f32 v[88:89], v[214:215], s[8:9] op_sel_hi:[1,0]
	v_pk_mul_f32 v[90:91], v[212:213], s[8:9] op_sel_hi:[1,0]
	v_pk_fma_f32 v[88:89], v[78:79], v[130:131], v[88:89]
	v_pk_fma_f32 v[78:79], v[76:77], v[128:129], v[90:91]
	v_cvt_pk_f16_f32 v76, v84, v85
	v_cvt_pk_f16_f32 v77, v86, v87
	v_cvt_pk_f16_f32 v78, v78, v79
	v_cvt_pk_f16_f32 v79, v88, v89
	global_store_dwordx4 v[92:93], v[76:79], off offset:256
	v_pk_mul_f32 v[84:85], v[224:225], s[8:9] op_sel_hi:[1,0]
	v_ashrrev_i32_e32 v177, 31, v176
	v_pk_mul_f32 v[78:79], v[226:227], s[8:9] op_sel_hi:[1,0]
	v_lshlrev_b64 v[76:77], 12, v[238:239]
	v_pk_fma_f32 v[78:79], v[82:83], v[142:143], v[78:79]
	v_pk_fma_f32 v[80:81], v[80:81], v[140:141], v[84:85]
	v_pk_mul_f32 v[82:83], v[222:223], s[8:9] op_sel_hi:[1,0]
	v_pk_mul_f32 v[84:85], v[220:221], s[8:9] op_sel_hi:[1,0]
	v_pk_fma_f32 v[82:83], v[74:75], v[138:139], v[82:83]
	v_pk_fma_f32 v[74:75], v[72:73], v[136:137], v[84:85]
	v_lshl_add_u64 v[76:77], s[0:1], 0, v[76:77]
	v_cvt_pk_f16_f32 v72, v80, v81
	v_cvt_pk_f16_f32 v73, v78, v79
	v_cvt_pk_f16_f32 v74, v74, v75
	v_cvt_pk_f16_f32 v75, v82, v83
	v_lshl_add_u64 v[76:77], v[76:77], 0, v[160:161]
	global_store_dwordx4 v[76:77], v[72:75], off
	v_lshlrev_b64 v[80:81], 13, v[174:175]
	v_lshl_add_u64 v[92:93], v[162:163], 0, v[80:81]
	v_pk_mul_f32 v[72:73], v[234:235], s[8:9] op_sel_hi:[1,0]
	v_pk_mul_f32 v[74:75], v[232:233], s[8:9] op_sel_hi:[1,0]
	v_pk_fma_f32 v[70:71], v[70:71], v[134:135], v[72:73]
	v_pk_fma_f32 v[68:69], v[68:69], v[132:133], v[74:75]
	v_pk_mul_f32 v[72:73], v[230:231], s[8:9] op_sel_hi:[1,0]
	v_pk_mul_f32 v[74:75], v[228:229], s[8:9] op_sel_hi:[1,0]
;     __device__ __forceinline__ void operator()(const AccT& acc, const pg8::Unit& u, int wr, int wc, int fr, int fq) const {
;     ...
;             for (int m = 0; m < 4; ++m) { const size_t off = (size_t)(row0 + ai * 128 + m * 16) * D + col0;
; #pragma unroll
;                 for (int bj = 0; bj < 2; ++bj) { xa[m][bj] = *(const f32x4*)(x + off + bj * 128); xb[m][bj] = *(const f32x4*)(x + off + bj * 128 + 4); } }
; #pragma unroll
;             for (int m = 0; m < 4; ++m) { const size_t off = (size_t)(row0 + ai * 128 + m * 16) * D + col0;
; #pragma unroll
;                 for (int bj = 0; bj < 2; ++bj) {
;                     const f32x4 a = ALPHA * xa[m][bj] + gv[bj][0] * acc[ai][bj][m][0], b = ALPHA * xb[m][bj] + gv[bj][1] * acc[ai][bj][m][1];
;                     u32x4 w; w.x = pk_h2(a[0], a[1]); w.y = pk_h2(a[2], a[3]); w.z = pk_h2(b[0], b[1]); w.w = pk_h2(b[2], b[3]);
;                     *(u32x4*)(U1 + off + bj * 128) = w; } }
	v_pk_fma_f32 v[72:73], v[66:67], v[130:131], v[72:73]
	v_pk_fma_f32 v[66:67], v[64:65], v[128:129], v[74:75]
	v_cvt_pk_f16_f32 v64, v68, v69
	v_cvt_pk_f16_f32 v65, v70, v71
	v_cvt_pk_f16_f32 v66, v66, v67
	v_cvt_pk_f16_f32 v67, v72, v73
	global_store_dwordx4 v[76:77], v[64:67], off offset:256
	v_lshlrev_b64 v[96:97], 13, v[176:177]
	v_lshl_add_u64 v[108:109], v[162:163], 0, v[96:97]
	v_lshlrev_b64 v[64:65], 13, v[172:173]
	v_lshl_add_u64 v[76:77], v[162:163], 0, v[64:65]
	global_load_dwordx4 v[64:67], v[76:77], off
	global_load_dwordx4 v[68:71], v[76:77], off offset:16
	global_load_dwordx4 v[72:75], v[76:77], off offset:512
	s_nop 0
	global_load_dwordx4 v[76:79], v[76:77], off offset:528
	s_nop 0
	global_load_dwordx4 v[80:83], v[92:93], off
	global_load_dwordx4 v[84:87], v[92:93], off offset:16
	global_load_dwordx4 v[88:91], v[92:93], off offset:512
	s_nop 0
	global_load_dwordx4 v[92:95], v[92:93], off offset:528
	s_nop 0
	global_load_dwordx4 v[96:99], v[108:109], off
	global_load_dwordx4 v[100:103], v[108:109], off offset:16
	global_load_dwordx4 v[104:107], v[108:109], off offset:528
	s_nop 0
	global_load_dwordx4 v[108:111], v[108:109], off offset:512
	v_add_u32_e32 v164, 0xb0, v164
	v_ashrrev_i32_e32 v165, 31, v164
	v_lshlrev_b64 v[112:113], 13, v[164:165]
	v_lshl_add_u64 v[124:125], v[162:163], 0, v[112:113]
	global_load_dwordx4 v[112:115], v[124:125], off offset:16
	global_load_dwordx4 v[116:119], v[124:125], off
	global_load_dwordx4 v[120:123], v[124:125], off offset:528
	s_nop 0
	global_load_dwordx4 v[124:127], v[124:125], off offset:512
	v_lshlrev_b64 v[162:163], 12, v[172:173]
	s_waitcnt vmcnt(0)
; #define PG8_WAIT_V(n) asm volatile("s_waitcnt vmcnt(" #n ")" ::: "memory")
; #define PG8_BAR __builtin_amdgcn_s_barrier()
; template <class Epi, class Sched>
; __device__ __forceinline__ void gemm_phase(PG8_LAS unsigned char* lds, const Gemm g, const Sched& S, const Epi& E) {
;     ...
;         E(acc, cur, wr, wc, fr, fq); S.done(cur);
;         if (!has_next) break;
; #pragma unroll
;         for (int a = 0; a < 2; ++a)
; #pragma unroll
;             for (int b = 0; b < 2; ++b)
; #pragma unroll
;                 for (int m = 0; m < 4; ++m)
; #pragma unroll
;                     for (int n = 0; n < 2; ++n) acc[a][b][m][n] = (f32x4){0.f, 0.f, 0.f, 0.f};
;         cur = nxt; cA = nA; cB = nB; ++ui;
;     }
;     PG8_WAIT_V(0);
;     if (wr == 0) PG8_BAR;
;     PG8_BAR;
;     __device__ __forceinline__ void operator()(const AccT& acc, const pg8::Unit& u, int wr, int wc, int fr, int fq) const {
;     ...
;             for (int m = 0; m < 4; ++m) { const size_t off = (size_t)(row0 + ai * 128 + m * 16) * D + col0;
; #pragma unroll
;                 for (int bj = 0; bj < 2; ++bj) {
;                     const f32x4 a = ALPHA * xa[m][bj] + gv[bj][0] * acc[ai][bj][m][0], b = ALPHA * xb[m][bj] + gv[bj][1] * acc[ai][bj][m][1];
;                     u32x4 w; w.x = pk_h2(a[0], a[1]); w.y = pk_h2(a[2], a[3]); w.z = pk_h2(b[0], b[1]); w.w = pk_h2(b[2], b[3]);
;                     *(u32x4*)(U1 + off + bj * 128) = w; } }
	v_pk_mul_f32 v[66:67], v[66:67], s[8:9] op_sel_hi:[1,0]
	v_pk_mul_f32 v[64:65], v[64:65], s[8:9] op_sel_hi:[1,0]
	v_pk_fma_f32 v[62:63], v[62:63], v[142:143], v[66:67]
	v_pk_fma_f32 v[60:61], v[60:61], v[140:141], v[64:65]
	v_pk_mul_f32 v[64:65], v[70:71], s[8:9] op_sel_hi:[1,0]
	v_pk_mul_f32 v[66:67], v[68:69], s[8:9] op_sel_hi:[1,0]
	v_pk_fma_f32 v[64:65], v[58:59], v[138:139], v[64:65]
	v_pk_fma_f32 v[58:59], v[56:57], v[136:137], v[66:67]
	v_cvt_pk_f16_f32 v56, v60, v61
	v_lshl_add_u64 v[60:61], s[0:1], 0, v[162:163]
	v_cvt_pk_f16_f32 v57, v62, v63
	v_cvt_pk_f16_f32 v58, v58, v59
	v_cvt_pk_f16_f32 v59, v64, v65
	v_lshl_add_u64 v[60:61], v[60:61], 0, v[160:161]
	global_store_dwordx4 v[60:61], v[56:59], off
	s_nop 1
	v_pk_mul_f32 v[56:57], v[74:75], s[8:9] op_sel_hi:[1,0]
	v_pk_mul_f32 v[58:59], v[72:73], s[8:9] op_sel_hi:[1,0]
	v_pk_fma_f32 v[54:55], v[54:55], v[134:135], v[56:57]
	v_pk_fma_f32 v[52:53], v[52:53], v[132:133], v[58:59]
	v_pk_mul_f32 v[56:57], v[78:79], s[8:9] op_sel_hi:[1,0]
	v_pk_mul_f32 v[58:59], v[76:77], s[8:9] op_sel_hi:[1,0]
	v_pk_fma_f32 v[56:57], v[46:47], v[130:131], v[56:57]
	v_pk_fma_f32 v[46:47], v[44:45], v[128:129], v[58:59]
	v_cvt_pk_f16_f32 v44, v52, v53
	v_cvt_pk_f16_f32 v45, v54, v55
	v_cvt_pk_f16_f32 v46, v46, v47
	v_cvt_pk_f16_f32 v47, v56, v57
	global_store_dwordx4 v[60:61], v[44:47], off offset:256
	v_pk_mul_f32 v[52:53], v[80:81], s[8:9] op_sel_hi:[1,0]
	s_nop 0
	v_pk_mul_f32 v[46:47], v[82:83], s[8:9] op_sel_hi:[1,0]
	v_lshlrev_b64 v[44:45], 12, v[174:175]
	v_pk_fma_f32 v[46:47], v[50:51], v[142:143], v[46:47]
	v_pk_fma_f32 v[48:49], v[48:49], v[140:141], v[52:53]
	v_pk_mul_f32 v[50:51], v[86:87], s[8:9] op_sel_hi:[1,0]
	v_pk_mul_f32 v[52:53], v[84:85], s[8:9] op_sel_hi:[1,0]
	v_pk_fma_f32 v[50:51], v[42:43], v[138:139], v[50:51]
	v_pk_fma_f32 v[42:43], v[40:41], v[136:137], v[52:53]
	v_lshl_add_u64 v[44:45], s[0:1], 0, v[44:45]
	v_cvt_pk_f16_f32 v40, v48, v49
	v_cvt_pk_f16_f32 v41, v46, v47
	v_cvt_pk_f16_f32 v42, v42, v43
	v_cvt_pk_f16_f32 v43, v50, v51
	v_lshl_add_u64 v[44:45], v[44:45], 0, v[160:161]
	global_store_dwordx4 v[44:45], v[40:43], off
	s_nop 1
	v_pk_mul_f32 v[40:41], v[90:91], s[8:9] op_sel_hi:[1,0]
	v_pk_mul_f32 v[42:43], v[88:89], s[8:9] op_sel_hi:[1,0]
	v_pk_fma_f32 v[38:39], v[38:39], v[134:135], v[40:41]
	v_pk_fma_f32 v[36:37], v[36:37], v[132:133], v[42:43]
	v_pk_mul_f32 v[40:41], v[94:95], s[8:9] op_sel_hi:[1,0]
	v_pk_mul_f32 v[42:43], v[92:93], s[8:9] op_sel_hi:[1,0]
	v_pk_fma_f32 v[40:41], v[30:31], v[130:131], v[40:41]
	v_pk_fma_f32 v[30:31], v[28:29], v[128:129], v[42:43]
	v_cvt_pk_f16_f32 v28, v36, v37
	v_cvt_pk_f16_f32 v29, v38, v39
	v_cvt_pk_f16_f32 v30, v30, v31
	v_cvt_pk_f16_f32 v31, v40, v41
	global_store_dwordx4 v[44:45], v[28:31], off offset:256
	v_pk_mul_f32 v[36:37], v[96:97], s[8:9] op_sel_hi:[1,0]
	s_nop 0
	v_pk_mul_f32 v[30:31], v[98:99], s[8:9] op_sel_hi:[1,0]
	v_lshlrev_b64 v[28:29], 12, v[176:177]
	v_pk_fma_f32 v[30:31], v[34:35], v[142:143], v[30:31]
	v_pk_fma_f32 v[32:33], v[32:33], v[140:141], v[36:37]
	v_pk_mul_f32 v[34:35], v[102:103], s[8:9] op_sel_hi:[1,0]
	v_pk_mul_f32 v[36:37], v[100:101], s[8:9] op_sel_hi:[1,0]
	v_pk_fma_f32 v[34:35], v[26:27], v[138:139], v[34:35]
	v_pk_fma_f32 v[26:27], v[24:25], v[136:137], v[36:37]
	v_lshl_add_u64 v[28:29], s[0:1], 0, v[28:29]
	v_cvt_pk_f16_f32 v24, v32, v33
	v_cvt_pk_f16_f32 v25, v30, v31
	v_cvt_pk_f16_f32 v26, v26, v27
	v_cvt_pk_f16_f32 v27, v34, v35
	v_lshl_add_u64 v[28:29], v[28:29], 0, v[160:161]
	global_store_dwordx4 v[28:29], v[24:27], off
	s_nop 1
	v_pk_mul_f32 v[24:25], v[110:111], s[8:9] op_sel_hi:[1,0]
	v_pk_mul_f32 v[26:27], v[108:109], s[8:9] op_sel_hi:[1,0]
	v_pk_fma_f32 v[22:23], v[22:23], v[134:135], v[24:25]
	v_pk_fma_f32 v[20:21], v[20:21], v[132:133], v[26:27]
	v_pk_mul_f32 v[24:25], v[106:107], s[8:9] op_sel_hi:[1,0]
	v_pk_mul_f32 v[26:27], v[104:105], s[8:9] op_sel_hi:[1,0]
	v_pk_fma_f32 v[24:25], v[14:15], v[130:131], v[24:25]
	v_pk_fma_f32 v[14:15], v[12:13], v[128:129], v[26:27]
	v_cvt_pk_f16_f32 v12, v20, v21
	v_cvt_pk_f16_f32 v13, v22, v23
	v_cvt_pk_f16_f32 v14, v14, v15
	v_cvt_pk_f16_f32 v15, v24, v25
	global_store_dwordx4 v[28:29], v[12:15], off offset:256
	v_pk_mul_f32 v[20:21], v[116:117], s[8:9] op_sel_hi:[1,0]
	s_nop 0
	v_pk_mul_f32 v[14:15], v[118:119], s[8:9] op_sel_hi:[1,0]
	v_lshlrev_b64 v[12:13], 12, v[164:165]
	v_pk_fma_f32 v[14:15], v[18:19], v[142:143], v[14:15]
	v_pk_fma_f32 v[16:17], v[16:17], v[140:141], v[20:21]
	v_pk_mul_f32 v[18:19], v[114:115], s[8:9] op_sel_hi:[1,0]
	v_pk_mul_f32 v[20:21], v[112:113], s[8:9] op_sel_hi:[1,0]
	v_pk_fma_f32 v[18:19], v[10:11], v[138:139], v[18:19]
	v_pk_fma_f32 v[10:11], v[8:9], v[136:137], v[20:21]
	v_lshl_add_u64 v[12:13], s[0:1], 0, v[12:13]
	v_cvt_pk_f16_f32 v8, v16, v17
	v_cvt_pk_f16_f32 v9, v14, v15
	v_cvt_pk_f16_f32 v10, v10, v11
	v_cvt_pk_f16_f32 v11, v18, v19
	v_lshl_add_u64 v[12:13], v[12:13], 0, v[160:161]
	global_store_dwordx4 v[12:13], v[8:11], off
	s_nop 1
	v_pk_mul_f32 v[8:9], v[126:127], s[8:9] op_sel_hi:[1,0]
	v_pk_mul_f32 v[10:11], v[124:125], s[8:9] op_sel_hi:[1,0]
	v_pk_fma_f32 v[6:7], v[6:7], v[134:135], v[8:9]
	v_pk_fma_f32 v[4:5], v[4:5], v[132:133], v[10:11]
	v_pk_mul_f32 v[8:9], v[122:123], s[8:9] op_sel_hi:[1,0]
	v_pk_mul_f32 v[10:11], v[120:121], s[8:9] op_sel_hi:[1,0]
	v_pk_fma_f32 v[8:9], v[2:3], v[130:131], v[8:9]
	v_pk_fma_f32 v[2:3], v[0:1], v[128:129], v[10:11]
	v_cvt_pk_f16_f32 v0, v4, v5
	v_cvt_pk_f16_f32 v1, v6, v7
	v_cvt_pk_f16_f32 v2, v2, v3
	v_cvt_pk_f16_f32 v3, v8, v9
	global_store_dwordx4 v[12:13], v[0:3], off offset:256
	s_cmp_eq_u32 s98, 0
	s_cbranch_scc1 .Lxb_666
	s_barrier
.Lxb_666:
	s_cbranch_vccz .LBB0_659
	s_waitcnt vmcnt(0)
	s_cmpk_gt_u32 s9, 0xff
	s_cbranch_scc1 .LBB0_670
	s_barrier

; #define PG8_STAGE(bufoff, gbase, voff) do { _Pragma("unroll") for (int _i = 0; _i < 2; ++_i) \
;         __builtin_amdgcn_global_load_lds((const unsigned*)((const char*)(gbase) + (voff)[_i]), (PG8_LAS unsigned*)(lds + (bufoff) + ldsw + _i * 8192), 16, 0, 0); } while (0)
; #define PG8_WAIT_V(n) asm volatile("s_waitcnt vmcnt(" #n ")" ::: "memory")
; #define PG8_BAR __builtin_amdgcn_s_barrier()
; template <class Epi, class Sched>
; __device__ __forceinline__ void gemm_phase(PG8_LAS unsigned char* lds, const Gemm g, const Sched& S, const Epi& E) {
;     const int tid = threadIdx.x, wid = __builtin_amdgcn_readfirstlane(tid >> 6), lane = tid & 63, wr = wid >> 2, wc = wid & 3, fr = lane & 15, fq = lane >> 4;
;     const int K = g.K, nt = K / BK;
;     unsigned voffA[2], voffB[2];
; #pragma unroll
;     for (int i = 0; i < 2; ++i) { int R, C; stage_rc(tid * 16 + i * 8192, R, C); const int Rb = Epi::PERM ? ((R & ~31) + perm32(R & 31)) : R;
;         voffA[i] = (unsigned)(R * K + C) * 2u; voffB[i] = (unsigned)(Rb * K + C) * 2u; }
;     const size_t kstep = (size_t)(BK * 2);
;     const size_t hstep = (size_t)HALF * K * 2;
;     const size_t tstep = 2 * hstep;
;     const unsigned ldsw = (unsigned)wid * 1024u;
;     const int aoff = lds_byte(wr * 64 + fr, fq * 8), boff = lds_byte(wc * 32 + fr, fq * 8);
;     ...
;     Unit cur, nxt; int ui = 0;
;     if (!S.next(0, cur)) return;
;     f32x4 acc[2][2][4][2];
; #pragma unroll
;     for (int a = 0; a < 2; ++a)
; #pragma unroll
;         for (int b = 0; b < 2; ++b)
; #pragma unroll
;             for (int m = 0; m < 4; ++m)
; #pragma unroll
;                 for (int n = 0; n < 2; ++n) acc[a][b][m][n] = (f32x4){0.f, 0.f, 0.f, 0.f};
;     bf16x8 At[4][2], B0[2][2], B1[2][2];
;     const char* cA = (const char*)g.A + (size_t)cur.pm * tstep; const char* cB = (const char*)g.Bt + (size_t)cur.pn * tstep;
;     S.a_ready(cur);
;     PG8_STAGE(PG8_SB(0, 0), cB, voffB); PG8_STAGE(PG8_SA(0, 0), cA, voffA); PG8_STAGE(PG8_SB(0, 1), cB + hstep, voffB); PG8_STAGE(PG8_SA(0, 1), cA + hstep, voffA);
;     if (wr == 1) PG8_BAR;
;     PG8_WAIT_V(4); PG8_BAR;
;     PG8_STAGE(PG8_SB(1, 0), cB + kstep, voffB); PG8_STAGE(PG8_SA(1, 0), cA + kstep, voffA); PG8_STAGE(PG8_SB(1, 1), cB + hstep + kstep, voffB);
;     PG8_WAIT_V(6); PG8_BAR;
.LBB0_799:
	s_add_u32 s0, s58, 0x1fd86000
	s_addc_u32 s1, s59, 0
	s_lshl_b32 s4, s4, 5
	s_and_b32 s9, s4, 0x60
	s_mov_b64 s[4:5], 0x80
	s_add_i32 m0, s21, 0x18000
	v_lshl_add_u64 v[6:7], v[6:7], 0, s[4:5]
	s_lshl_b32 s8, s3, 13
	s_lshl_b32 s10, s9, 7
	v_readfirstlane_b32 s98, v242
	s_lshr_b32 s98, s98, 8
	s_waitcnt vmcnt(2)
	s_barrier
	global_load_lds_dwordx4 v[6:7], off
	v_lshl_add_u64 v[4:5], v[4:5], 0, s[4:5]
	s_add_i32 m0, s21, 0x1a000
	s_add_i32 s46, s21, 0x8000
	s_add_i32 s47, s21, 0xa000
	global_load_lds_dwordx4 v[4:5], off
	v_lshl_add_u64 v[2:3], v[2:3], 0, s[4:5]
	s_mov_b32 m0, s46
	s_add_u32 s6, s28, 0x80080
	global_load_lds_dwordx4 v[2:3], off
	v_lshl_add_u64 v[0:1], v[0:1], 0, s[4:5]
	s_mov_b32 m0, s47
	s_addc_u32 s7, s29, 0
	global_load_lds_dwordx4 v[0:1], off
	s_add_i32 m0, s21, 0x1c000
	v_lshl_add_u64 v[0:1], s[6:7], 0, v[132:133]
	global_load_lds_dwordx4 v[0:1], off
	v_lshl_add_u64 v[0:1], s[6:7], 0, v[128:129]
	s_add_i32 m0, s21, 0x1e000
	s_sext_i32_i16 s65, s2
	global_load_lds_dwordx4 v[0:1], off
	v_and_b32_e32 v0, 15, v242
	v_lshlrev_b32_e32 v1, 1, v11
	v_lshlrev_b32_e32 v2, 2, v242
	v_lshlrev_b32_e32 v3, 6, v242
	s_movk_i32 s2, 0x3c0
	v_lshl_or_b32 v144, s3, 6, v0
	v_lshl_or_b32 v0, v0, 6, v1
	v_and_b32_e32 v2, 32, v2
	v_and_or_b32 v1, v3, s2, v1
	v_bitop3_b32 v145, s10, v1, v2 bitop3:0xf6
	v_lshlrev_b32_e32 v1, 9, v242
	v_bitop3_b32 v0, v0, s8, v2 bitop3:0xde
	v_and_b32_e32 v1, 0x70000, v1
	v_lshlrev_b32_e32 v2, 12, v12
	v_or3_b32 v1, v9, v1, v2
	v_add_u32_e32 v136, v1, v10
	v_lshlrev_b32_e32 v1, 5, v8
	s_waitcnt vmcnt(6)
	v_and_b32_e32 v1, 0xf0000, v1
	v_or3_b32 v1, v9, v1, v2
	s_add_i32 s50, 0, 0x10000
	s_add_i32 s51, 0, 0x14000
	s_ashr_i32 s48, s62, 31
	s_mov_b32 s49, s62
	v_or_b32_e32 v146, s9, v11
	v_mov_b32_e32 v137, v133
	v_add_u32_e32 v138, v1, v10
	v_mov_b32_e32 v139, v133
	v_mov_b64_e32 v[140:141], 0x1600
	v_mov_b64_e32 v[142:143], 0x15ff
	v_add_u32_e32 v147, s50, v145
	v_add_u32_e32 v148, 0, v0
	v_add_u32_e32 v149, s51, v145
	s_movk_i32 s64, 0x2c00
	s_barrier

; #define PG8_STAGE(bufoff, gbase, voff) do { _Pragma("unroll") for (int _i = 0; _i < 2; ++_i) \
;         __builtin_amdgcn_global_load_lds((const unsigned*)((const char*)(gbase) + (voff)[_i]), (PG8_LAS unsigned*)(lds + (bufoff) + ldsw + _i * 8192), 16, 0, 0); } while (0)
; #define PG8_LDA(dst, b, h) do { _Pragma("unroll") for (int m = 0; m < 4; ++m) _Pragma("unroll") for (int k = 0; k < 2; ++k) dst[m][k] = *(const PG8_LAS bf16x8*)(lds + PG8_SA(b, h) + aoff + m * 2048 + k * 1024); } while (0)
; #define PG8_LDB(dst, b, h) do { _Pragma("unroll") for (int n = 0; n < 2; ++n) _Pragma("unroll") for (int k = 0; k < 2; ++k) dst[n][k] = *(const PG8_LAS bf16x8*)(lds + PG8_SB(b, h) + boff + n * 2048 + k * 1024); } while (0)
; #define PG8_MMA(ai, bj, At, Bt) do { __builtin_amdgcn_s_setprio(1); _Pragma("unroll") for (int m = 0; m < 4; ++m) _Pragma("unroll") for (int n = 0; n < 2; ++n) _Pragma("unroll") for (int k = 0; k < 2; ++k) \
;         acc[ai][bj][m][n] = __builtin_amdgcn_mfma_f32_16x16x32_bf16(Bt[n][k], At[m][k], acc[ai][bj][m][n], 0, 0, 0); __builtin_amdgcn_s_setprio(0); } while (0)
; #define PG8_WAIT_V(n) asm volatile("s_waitcnt vmcnt(" #n ")" ::: "memory")
; #define PG8_WAIT_L(n) asm volatile("s_waitcnt lgkmcnt(" #n ")" ::: "memory")
; #define PG8_BAR __builtin_amdgcn_s_barrier()
; template <class Epi, class Sched>
; __device__ __forceinline__ void gemm_phase(PG8_LAS unsigned char* lds, const Gemm g, const Sched& S, const Epi& E) {
;     ...
;             const char* a1 = cA + (size_t)(t + 1) * kstep;
;             const char* a2 = last ? nA : cA + (size_t)(t + 2) * kstep; const char* b2 = last ? nB : cB + (size_t)(t + 2) * kstep;
;             const char* a3 = a2 + kstep; const char* b3 = b2 + kstep;
;             if (last && has_next) S.a_ready(nxt);
;             PG8_LDB(B0, 0, 0); PG8_SCHED; PG8_LDA(At, 0, 0); PG8_STAGE(PG8_SA(1, 1), a1 + hstep, voffA);
;             PG8_WAIT_L(8); PG8_BAR; PG8_WAIT_L(0); PG8_MMA(0, 0, At, B0); PG8_BAR; PG8_SCHED;
;             PG8_LDB(B1, 0, 1); PG8_STAGE(PG8_SB(0, 0), b2, voffB);
;             PG8_BAR; PG8_WAIT_L(0); PG8_MMA(0, 1, At, B1); PG8_BAR;
;             PG8_LDA(At, 0, 1); PG8_STAGE(PG8_SA(0, 0), a2, voffA);
;             PG8_BAR; PG8_WAIT_L(0); PG8_MMA(1, 0, At, B0); PG8_BAR; PG8_SCHED;
;             PG8_STAGE(PG8_SB(0, 1), b2 + hstep, voffB);
;             PG8_WAIT_V(6); PG8_BAR; PG8_MMA(1, 1, At, B1); PG8_BAR;
.LBB0_803:
	s_setprio 0
	ds_read_b128 v[150:153], v147
	ds_read_b128 v[154:157], v147 offset:1024
	ds_read_b128 v[158:161], v147 offset:2048
	ds_read_b128 v[162:165], v147 offset:3072
	ds_read_b128 v[166:169], v148
	ds_read_b128 v[170:173], v148 offset:1024
	ds_read_b128 v[174:177], v148 offset:2048
	ds_read_b128 v[178:181], v148 offset:3072
	ds_read_b128 v[182:185], v148 offset:4096
	ds_read_b128 v[186:189], v148 offset:5120
	ds_read_b128 v[190:193], v148 offset:6144
	ds_read_b128 v[194:197], v148 offset:7168
	ds_read_b128 v[198:201], v149
	ds_read_b128 v[202:205], v149 offset:1024
	ds_read_b128 v[206:209], v149 offset:2048
	ds_read_b128 v[210:213], v149 offset:3072
	s_add_u32 s10, s26, 0xfff80080
	s_addc_u32 s11, s27, -1
	s_cmp_eq_u32 s70, 28
	s_cselect_b32 s31, s9, s11
	s_cselect_b32 s30, s66, s10
	s_cselect_b32 s29, s7, s69
	s_cselect_b32 s28, s67, s68
	v_lshl_add_u64 v[222:223], s[26:27], 0, v[136:137]
	s_add_i32 m0, s21, 0xc000
	s_nop 0
	global_load_lds_dwordx4 v[222:223], off
	v_lshl_add_u64 v[222:223], s[26:27], 0, v[138:139]
	s_add_i32 m0, s21, 0xe000
	s_nop 0
	global_load_lds_dwordx4 v[222:223], off
	s_waitcnt vmcnt(8)
	s_waitcnt lgkmcnt(0)
	s_setprio 1
	s_barrier
	v_mfma_f32_16x16x32_bf16 v[124:127], v[150:153], v[166:169], v[124:127]
	v_mfma_f32_16x16x32_bf16 v[120:123], v[158:161], v[166:169], v[120:123]
	v_mfma_f32_16x16x32_bf16 v[108:111], v[150:153], v[174:177], v[108:111]
	v_mfma_f32_16x16x32_bf16 v[104:107], v[158:161], v[174:177], v[104:107]
	v_mfma_f32_16x16x32_bf16 v[92:95], v[150:153], v[182:185], v[92:95]
	v_mfma_f32_16x16x32_bf16 v[88:91], v[158:161], v[182:185], v[88:91]
	v_mfma_f32_16x16x32_bf16 v[76:79], v[150:153], v[190:193], v[76:79]
	v_mfma_f32_16x16x32_bf16 v[72:75], v[158:161], v[190:193], v[72:75]
	v_mfma_f32_16x16x32_bf16 v[124:127], v[154:157], v[170:173], v[124:127]
	v_mfma_f32_16x16x32_bf16 v[120:123], v[162:165], v[170:173], v[120:123]
	v_mfma_f32_16x16x32_bf16 v[108:111], v[154:157], v[178:181], v[108:111]
	v_mfma_f32_16x16x32_bf16 v[104:107], v[162:165], v[178:181], v[104:107]
	v_mfma_f32_16x16x32_bf16 v[92:95], v[154:157], v[186:189], v[92:95]
	v_mfma_f32_16x16x32_bf16 v[88:91], v[162:165], v[186:189], v[88:91]
	v_mfma_f32_16x16x32_bf16 v[76:79], v[154:157], v[194:197], v[76:79]
	v_mfma_f32_16x16x32_bf16 v[72:75], v[162:165], v[194:197], v[72:75]
	v_mfma_f32_16x16x32_bf16 v[116:119], v[198:201], v[166:169], v[116:119]
	v_mfma_f32_16x16x32_bf16 v[112:115], v[206:209], v[166:169], v[112:115]
	v_mfma_f32_16x16x32_bf16 v[100:103], v[198:201], v[174:177], v[100:103]
	v_mfma_f32_16x16x32_bf16 v[96:99], v[206:209], v[174:177], v[96:99]
	v_mfma_f32_16x16x32_bf16 v[84:87], v[198:201], v[182:185], v[84:87]
	v_mfma_f32_16x16x32_bf16 v[80:83], v[206:209], v[182:185], v[80:83]
	v_mfma_f32_16x16x32_bf16 v[68:71], v[198:201], v[190:193], v[68:71]
	v_mfma_f32_16x16x32_bf16 v[64:67], v[206:209], v[190:193], v[64:67]
	v_mfma_f32_16x16x32_bf16 v[116:119], v[202:205], v[170:173], v[116:119]
	v_mfma_f32_16x16x32_bf16 v[112:115], v[210:213], v[170:173], v[112:115]
	v_mfma_f32_16x16x32_bf16 v[100:103], v[202:205], v[178:181], v[100:103]
	v_mfma_f32_16x16x32_bf16 v[96:99], v[210:213], v[178:181], v[96:99]
	v_mfma_f32_16x16x32_bf16 v[84:87], v[202:205], v[186:189], v[84:87]
	v_mfma_f32_16x16x32_bf16 v[80:83], v[210:213], v[186:189], v[80:83]
	v_mfma_f32_16x16x32_bf16 v[68:71], v[202:205], v[194:197], v[68:71]
	v_mfma_f32_16x16x32_bf16 v[64:67], v[210:213], v[194:197], v[64:67]
	s_barrier
	s_setprio 0
	ds_read_b128 v[166:169], v148 offset:16384
	ds_read_b128 v[170:173], v148 offset:17408
	ds_read_b128 v[174:177], v148 offset:18432
	ds_read_b128 v[178:181], v148 offset:19456
	ds_read_b128 v[182:185], v148 offset:20480
	ds_read_b128 v[186:189], v148 offset:21504
	ds_read_b128 v[190:193], v148 offset:22528
	ds_read_b128 v[194:197], v148 offset:23552
	s_add_i32 s10, s50, s39
	v_lshl_add_u64 v[214:215], s[28:29], 0, v[132:133]
	s_mov_b32 m0, s10
	s_nop 0
	global_load_lds_dwordx4 v[214:215], off
	v_lshl_add_u64 v[216:217], s[28:29], 0, v[128:129]
	s_add_i32 m0, s10, 0x2000
	s_nop 0
	global_load_lds_dwordx4 v[216:217], off
	s_mov_b32 m0, s21
	v_lshl_add_u64 v[218:219], s[30:31], 0, v[134:135]
	global_load_lds_dwordx4 v[218:219], off
	v_lshl_add_u64 v[220:221], s[30:31], 0, v[130:131]
	s_mov_b32 m0, s42
	s_nop 0
	global_load_lds_dwordx4 v[220:221], off
	s_add_u32 s10, s28, 0x80000
	s_addc_u32 s11, s29, 0
	s_add_i32 s33, s51, s39
	v_lshl_add_u64 v[222:223], s[10:11], 0, v[132:133]
	s_mov_b32 m0, s33
	s_nop 0
	global_load_lds_dwordx4 v[222:223], off
	v_lshl_add_u64 v[222:223], s[10:11], 0, v[128:129]
	s_add_i32 m0, s33, 0x2000
	s_nop 0
	global_load_lds_dwordx4 v[222:223], off
	s_waitcnt vmcnt(8)
	s_waitcnt lgkmcnt(0)
	s_setprio 1
	s_barrier
; #define PG8_STAGE(bufoff, gbase, voff) do { _Pragma("unroll") for (int _i = 0; _i < 2; ++_i) \
;         __builtin_amdgcn_global_load_lds((const unsigned*)((const char*)(gbase) + (voff)[_i]), (PG8_LAS unsigned*)(lds + (bufoff) + ldsw + _i * 8192), 16, 0, 0); } while (0)
; #define PG8_LDA(dst, b, h) do { _Pragma("unroll") for (int m = 0; m < 4; ++m) _Pragma("unroll") for (int k = 0; k < 2; ++k) dst[m][k] = *(const PG8_LAS bf16x8*)(lds + PG8_SA(b, h) + aoff + m * 2048 + k * 1024); } while (0)
; #define PG8_LDB(dst, b, h) do { _Pragma("unroll") for (int n = 0; n < 2; ++n) _Pragma("unroll") for (int k = 0; k < 2; ++k) dst[n][k] = *(const PG8_LAS bf16x8*)(lds + PG8_SB(b, h) + boff + n * 2048 + k * 1024); } while (0)
; #define PG8_MMA(ai, bj, At, Bt) do { __builtin_amdgcn_s_setprio(1); _Pragma("unroll") for (int m = 0; m < 4; ++m) _Pragma("unroll") for (int n = 0; n < 2; ++n) _Pragma("unroll") for (int k = 0; k < 2; ++k) \
;         acc[ai][bj][m][n] = __builtin_amdgcn_mfma_f32_16x16x32_bf16(Bt[n][k], At[m][k], acc[ai][bj][m][n], 0, 0, 0); __builtin_amdgcn_s_setprio(0); } while (0)
; #define PG8_WAIT_V(n) asm volatile("s_waitcnt vmcnt(" #n ")" ::: "memory")
; #define PG8_WAIT_L(n) asm volatile("s_waitcnt lgkmcnt(" #n ")" ::: "memory")
; #define PG8_BAR __builtin_amdgcn_s_barrier()
; #define PG8_SCHED __builtin_amdgcn_sched_barrier(0)
; template <class Epi, class Sched>
; __device__ __forceinline__ void gemm_phase(PG8_LAS unsigned char* lds, const Gemm g, const Sched& S, const Epi& E) {
;     ...
;             PG8_BAR; PG8_WAIT_L(0); PG8_MMA(1, 0, At, B0); PG8_BAR; PG8_SCHED;
;             PG8_STAGE(PG8_SB(0, 1), b2 + hstep, voffB);
;             PG8_WAIT_V(6); PG8_BAR; PG8_MMA(1, 1, At, B1); PG8_BAR;
;             PG8_LDB(B0, 1, 0); PG8_SCHED; PG8_LDA(At, 1, 0); PG8_STAGE(PG8_SA(0, 1), a2 + hstep, voffA);
;             PG8_WAIT_L(8); PG8_BAR; PG8_WAIT_L(0); PG8_MMA(0, 0, At, B0); PG8_BAR; PG8_SCHED;
;             PG8_LDB(B1, 1, 1); PG8_STAGE(PG8_SB(1, 0), b3, voffB);
;             PG8_BAR; PG8_WAIT_L(0); PG8_MMA(0, 1, At, B1); PG8_BAR;
;             PG8_LDA(At, 1, 1); PG8_STAGE(PG8_SA(1, 0), a3, voffA);
;             PG8_BAR; PG8_WAIT_L(0); PG8_MMA(1, 0, At, B0); PG8_BAR; PG8_SCHED;
	v_mfma_f32_16x16x32_bf16 v[60:63], v[150:153], v[166:169], v[60:63]
	v_mfma_f32_16x16x32_bf16 v[56:59], v[158:161], v[166:169], v[56:59]
	v_mfma_f32_16x16x32_bf16 v[44:47], v[150:153], v[174:177], v[44:47]
	v_mfma_f32_16x16x32_bf16 v[40:43], v[158:161], v[174:177], v[40:43]
	v_mfma_f32_16x16x32_bf16 v[28:31], v[150:153], v[182:185], v[28:31]
	v_mfma_f32_16x16x32_bf16 v[24:27], v[158:161], v[182:185], v[24:27]
	v_mfma_f32_16x16x32_bf16 v[12:15], v[150:153], v[190:193], v[12:15]
	v_mfma_f32_16x16x32_bf16 v[8:11], v[158:161], v[190:193], v[8:11]
	s_add_i32 s33, 0, 0x18000
	v_mfma_f32_16x16x32_bf16 v[60:63], v[154:157], v[170:173], v[60:63]
	v_mfma_f32_16x16x32_bf16 v[56:59], v[162:165], v[170:173], v[56:59]
	v_mfma_f32_16x16x32_bf16 v[44:47], v[154:157], v[178:181], v[44:47]
	v_mfma_f32_16x16x32_bf16 v[40:43], v[162:165], v[178:181], v[40:43]
	v_mfma_f32_16x16x32_bf16 v[28:31], v[154:157], v[186:189], v[28:31]
	v_mfma_f32_16x16x32_bf16 v[24:27], v[162:165], v[186:189], v[24:27]
	v_mfma_f32_16x16x32_bf16 v[12:15], v[154:157], v[194:197], v[12:15]
	v_mfma_f32_16x16x32_bf16 v[8:11], v[162:165], v[194:197], v[8:11]
	v_mfma_f32_16x16x32_bf16 v[52:55], v[198:201], v[166:169], v[52:55]
	v_mfma_f32_16x16x32_bf16 v[48:51], v[206:209], v[166:169], v[48:51]
	v_mfma_f32_16x16x32_bf16 v[36:39], v[198:201], v[174:177], v[36:39]
	v_mfma_f32_16x16x32_bf16 v[32:35], v[206:209], v[174:177], v[32:35]
	v_mfma_f32_16x16x32_bf16 v[20:23], v[198:201], v[182:185], v[20:23]
	v_mfma_f32_16x16x32_bf16 v[16:19], v[206:209], v[182:185], v[16:19]
	v_mfma_f32_16x16x32_bf16 v[4:7], v[198:201], v[190:193], v[4:7]
	v_mfma_f32_16x16x32_bf16 v[0:3], v[206:209], v[190:193], v[0:3]
	v_mfma_f32_16x16x32_bf16 v[52:55], v[202:205], v[170:173], v[52:55]
	v_mfma_f32_16x16x32_bf16 v[48:51], v[210:213], v[170:173], v[48:51]
	v_mfma_f32_16x16x32_bf16 v[36:39], v[202:205], v[178:181], v[36:39]
	v_mfma_f32_16x16x32_bf16 v[32:35], v[210:213], v[178:181], v[32:35]
	v_mfma_f32_16x16x32_bf16 v[20:23], v[202:205], v[186:189], v[20:23]
	v_mfma_f32_16x16x32_bf16 v[16:19], v[210:213], v[186:189], v[16:19]
	v_mfma_f32_16x16x32_bf16 v[4:7], v[202:205], v[194:197], v[4:7]
	v_mfma_f32_16x16x32_bf16 v[0:3], v[210:213], v[194:197], v[0:3]
	s_barrier
	s_setprio 0
	ds_read_b128 v[150:153], v147 offset:32768
	ds_read_b128 v[154:157], v147 offset:33792
	ds_read_b128 v[158:161], v147 offset:34816
	ds_read_b128 v[162:165], v147 offset:35840
	ds_read_b128 v[166:169], v148 offset:32768
	ds_read_b128 v[170:173], v148 offset:33792
	ds_read_b128 v[174:177], v148 offset:34816
	ds_read_b128 v[178:181], v148 offset:35840
	ds_read_b128 v[182:185], v148 offset:36864
	ds_read_b128 v[186:189], v148 offset:37888
	ds_read_b128 v[190:193], v148 offset:38912
	ds_read_b128 v[194:197], v148 offset:39936
	ds_read_b128 v[198:201], v149 offset:32768
	ds_read_b128 v[202:205], v149 offset:33792
	ds_read_b128 v[206:209], v149 offset:34816
	ds_read_b128 v[210:213], v149 offset:35840
	s_add_u32 s10, s30, 0x80000
	s_addc_u32 s11, s31, 0
	s_mov_b32 m0, s43
	v_lshl_add_u64 v[222:223], s[10:11], 0, v[134:135]
	global_load_lds_dwordx4 v[222:223], off
	v_lshl_add_u64 v[222:223], s[10:11], 0, v[130:131]
	s_mov_b32 m0, s44
	s_nop 0
	global_load_lds_dwordx4 v[222:223], off
	s_waitcnt vmcnt(8)
	s_waitcnt lgkmcnt(0)
	s_setprio 1
	s_barrier
	v_mfma_f32_16x16x32_bf16 v[124:127], v[150:153], v[166:169], v[124:127]
	v_mfma_f32_16x16x32_bf16 v[120:123], v[158:161], v[166:169], v[120:123]
	v_mfma_f32_16x16x32_bf16 v[108:111], v[150:153], v[174:177], v[108:111]
	v_mfma_f32_16x16x32_bf16 v[104:107], v[158:161], v[174:177], v[104:107]
	v_mfma_f32_16x16x32_bf16 v[92:95], v[150:153], v[182:185], v[92:95]
	v_mfma_f32_16x16x32_bf16 v[88:91], v[158:161], v[182:185], v[88:91]
	v_mfma_f32_16x16x32_bf16 v[76:79], v[150:153], v[190:193], v[76:79]
	v_mfma_f32_16x16x32_bf16 v[72:75], v[158:161], v[190:193], v[72:75]
	v_mfma_f32_16x16x32_bf16 v[124:127], v[154:157], v[170:173], v[124:127]
	v_mfma_f32_16x16x32_bf16 v[120:123], v[162:165], v[170:173], v[120:123]
	v_mfma_f32_16x16x32_bf16 v[108:111], v[154:157], v[178:181], v[108:111]
	v_mfma_f32_16x16x32_bf16 v[104:107], v[162:165], v[178:181], v[104:107]
	v_mfma_f32_16x16x32_bf16 v[92:95], v[154:157], v[186:189], v[92:95]
	v_mfma_f32_16x16x32_bf16 v[88:91], v[162:165], v[186:189], v[88:91]
	v_mfma_f32_16x16x32_bf16 v[76:79], v[154:157], v[194:197], v[76:79]
	v_mfma_f32_16x16x32_bf16 v[72:75], v[162:165], v[194:197], v[72:75]
	v_mfma_f32_16x16x32_bf16 v[116:119], v[198:201], v[166:169], v[116:119]
	v_mfma_f32_16x16x32_bf16 v[112:115], v[206:209], v[166:169], v[112:115]
	v_mfma_f32_16x16x32_bf16 v[100:103], v[198:201], v[174:177], v[100:103]
	v_mfma_f32_16x16x32_bf16 v[96:99], v[206:209], v[174:177], v[96:99]
	v_mfma_f32_16x16x32_bf16 v[84:87], v[198:201], v[182:185], v[84:87]
	v_mfma_f32_16x16x32_bf16 v[80:83], v[206:209], v[182:185], v[80:83]
	v_mfma_f32_16x16x32_bf16 v[68:71], v[198:201], v[190:193], v[68:71]
	v_mfma_f32_16x16x32_bf16 v[64:67], v[206:209], v[190:193], v[64:67]
	v_mfma_f32_16x16x32_bf16 v[116:119], v[202:205], v[170:173], v[116:119]
	v_mfma_f32_16x16x32_bf16 v[112:115], v[210:213], v[170:173], v[112:115]
	v_mfma_f32_16x16x32_bf16 v[100:103], v[202:205], v[178:181], v[100:103]
	v_mfma_f32_16x16x32_bf16 v[96:99], v[210:213], v[178:181], v[96:99]
	v_mfma_f32_16x16x32_bf16 v[84:87], v[202:205], v[186:189], v[84:87]
	v_mfma_f32_16x16x32_bf16 v[80:83], v[210:213], v[186:189], v[80:83]
	v_mfma_f32_16x16x32_bf16 v[68:71], v[202:205], v[194:197], v[68:71]
	v_mfma_f32_16x16x32_bf16 v[64:67], v[210:213], v[194:197], v[64:67]
	s_barrier
; __device__ __forceinline__ unsigned cvt_pk_bf16(float lo, float hi) { const bf16v2_t v = __builtin_convertvector((f32x2){lo, hi}, bf16v2_t); return __builtin_bit_cast(unsigned, v); }
; __device__ __forceinline__ float silu_f(float v) { return v * __builtin_amdgcn_rcpf(1.0f + __expf(-v)); }
; #define PG8_STAGE(bufoff, gbase, voff) do { _Pragma("unroll") for (int _i = 0; _i < 2; ++_i) \
;         __builtin_amdgcn_global_load_lds((const unsigned*)((const char*)(gbase) + (voff)[_i]), (PG8_LAS unsigned*)(lds + (bufoff) + ldsw + _i * 8192), 16, 0, 0); } while (0)
; #define PG8_LDA(dst, b, h) do { _Pragma("unroll") for (int m = 0; m < 4; ++m) _Pragma("unroll") for (int k = 0; k < 2; ++k) dst[m][k] = *(const PG8_LAS bf16x8*)(lds + PG8_SA(b, h) + aoff + m * 2048 + k * 1024); } while (0)
; #define PG8_WAIT_V(n) asm volatile("s_waitcnt vmcnt(" #n ")" ::: "memory")
; #define PG8_WAIT_L(n) asm volatile("s_waitcnt lgkmcnt(" #n ")" ::: "memory")
; #define PG8_BAR __builtin_amdgcn_s_barrier()
; #define PG8_SCHED __builtin_amdgcn_sched_barrier(0)
; template <class Epi, class Sched>
; __device__ __forceinline__ void gemm_phase(PG8_LAS unsigned char* lds, const Gemm g, const Sched& S, const Epi& E) {
;     ...
;             PG8_LDA(At, 1, 1); PG8_STAGE(PG8_SA(1, 0), a3, voffA);
;             PG8_BAR; PG8_WAIT_L(0); PG8_MMA(1, 0, At, B0); PG8_BAR; PG8_SCHED;
;             PG8_STAGE(PG8_SB(1, 1), b3 + hstep, voffB);
;             PG8_WAIT_V(6); PG8_BAR; PG8_MMA(1, 1, At, B1); PG8_BAR;
;         }
;         E(acc, cur, wr, wc, fr, fq); S.done(cur);
;         if (!has_next) break;
;     __device__ __forceinline__ void operator()(const AccT& acc, const pg8::Unit& u, int wr, int wc, int fr, int fq) const {
;         const int row0 = u.pm * 256 + wr * 64 + fr, col = u.pn * 128 + wc * 32 + 8 * fq;
; #pragma unroll
;         for (int ai = 0; ai < 2; ++ai)
; #pragma unroll
;             for (int m = 0; m < 4; ++m) {
;                 f32x4 a = acc[ai][0][m][0], b = acc[ai][0][m][1];
; #pragma unroll
;                 for (int j = 0; j < 4; ++j) { a[j] = silu_f(a[j]) * acc[ai][1][m][0][j]; b[j] = silu_f(b[j]) * acc[ai][1][m][1][j]; }
;                 u32x4 w; w.x = cvt_pk_bf16(a[0], a[1]); w.y = cvt_pk_bf16(a[2], a[3]); w.z = cvt_pk_bf16(b[0], b[1]); w.w = cvt_pk_bf16(b[2], b[3]);
;                 *(u32x4*)(HID + (size_t)(row0 + ai * 128 + m * 16) * DFF + col) = w;
	s_setprio 0
	ds_read_b128 v[166:169], v148 offset:49152
	ds_read_b128 v[170:173], v148 offset:50176
	ds_read_b128 v[174:177], v148 offset:51200
	ds_read_b128 v[178:181], v148 offset:52224
	ds_read_b128 v[182:185], v148 offset:53248
	ds_read_b128 v[186:189], v148 offset:54272
	ds_read_b128 v[190:193], v148 offset:55296
	ds_read_b128 v[194:197], v148 offset:56320
	s_add_i32 s30, 0, 0x1c000
	s_add_i32 s10, s33, s39
	v_lshl_add_u64 v[214:215], v[214:215], 0, s[4:5]
	s_mov_b32 m0, s10
	s_nop 0
	global_load_lds_dwordx4 v[214:215], off
	v_lshl_add_u64 v[214:215], v[216:217], 0, s[4:5]
	s_add_i32 m0, s10, 0x2000
	s_nop 0
	global_load_lds_dwordx4 v[214:215], off
	s_mov_b32 m0, s46
	v_lshl_add_u64 v[214:215], v[218:219], 0, s[4:5]
	global_load_lds_dwordx4 v[214:215], off
	v_lshl_add_u64 v[214:215], v[220:221], 0, s[4:5]
	s_mov_b32 m0, s47
	s_nop 0
	global_load_lds_dwordx4 v[214:215], off
	s_add_u32 s10, s28, 0x80080
	s_addc_u32 s11, s29, 0
	s_add_i32 s28, s30, s39
	v_lshl_add_u64 v[222:223], s[10:11], 0, v[132:133]
	s_mov_b32 m0, s28
	s_nop 0
	global_load_lds_dwordx4 v[222:223], off
	v_lshl_add_u64 v[222:223], s[10:11], 0, v[128:129]
	s_add_i32 m0, s28, 0x2000
	s_nop 0
	global_load_lds_dwordx4 v[222:223], off
	s_waitcnt vmcnt(8)
	s_waitcnt lgkmcnt(0)
	s_setprio 1
	s_barrier
	v_mfma_f32_16x16x32_bf16 v[60:63], v[150:153], v[166:169], v[60:63]
	v_mfma_f32_16x16x32_bf16 v[56:59], v[158:161], v[166:169], v[56:59]
	v_mfma_f32_16x16x32_bf16 v[44:47], v[150:153], v[174:177], v[44:47]
	v_mfma_f32_16x16x32_bf16 v[40:43], v[158:161], v[174:177], v[40:43]
	v_mfma_f32_16x16x32_bf16 v[28:31], v[150:153], v[182:185], v[28:31]
	v_mfma_f32_16x16x32_bf16 v[24:27], v[158:161], v[182:185], v[24:27]
	v_mfma_f32_16x16x32_bf16 v[12:15], v[150:153], v[190:193], v[12:15]
	v_mfma_f32_16x16x32_bf16 v[8:11], v[158:161], v[190:193], v[8:11]
	s_add_i32 s70, s70, 2
	s_add_u32 s26, s26, 0x100
	s_addc_u32 s27, s27, 0
	s_add_u32 s68, s68, 0x100
	s_addc_u32 s69, s69, 0
	s_cmp_gt_u32 s70, 29
	v_mfma_f32_16x16x32_bf16 v[60:63], v[154:157], v[170:173], v[60:63]
	v_mfma_f32_16x16x32_bf16 v[56:59], v[162:165], v[170:173], v[56:59]
	v_mfma_f32_16x16x32_bf16 v[44:47], v[154:157], v[178:181], v[44:47]
	v_mfma_f32_16x16x32_bf16 v[40:43], v[162:165], v[178:181], v[40:43]
	v_mfma_f32_16x16x32_bf16 v[28:31], v[154:157], v[186:189], v[28:31]
	v_mfma_f32_16x16x32_bf16 v[24:27], v[162:165], v[186:189], v[24:27]
	v_mfma_f32_16x16x32_bf16 v[12:15], v[154:157], v[194:197], v[12:15]
	v_mfma_f32_16x16x32_bf16 v[8:11], v[162:165], v[194:197], v[8:11]
	v_mfma_f32_16x16x32_bf16 v[52:55], v[198:201], v[166:169], v[52:55]
	v_mfma_f32_16x16x32_bf16 v[48:51], v[206:209], v[166:169], v[48:51]
	v_mfma_f32_16x16x32_bf16 v[36:39], v[198:201], v[174:177], v[36:39]
	v_mfma_f32_16x16x32_bf16 v[32:35], v[206:209], v[174:177], v[32:35]
	v_mfma_f32_16x16x32_bf16 v[20:23], v[198:201], v[182:185], v[20:23]
	v_mfma_f32_16x16x32_bf16 v[16:19], v[206:209], v[182:185], v[16:19]
	v_mfma_f32_16x16x32_bf16 v[4:7], v[198:201], v[190:193], v[4:7]
	v_mfma_f32_16x16x32_bf16 v[0:3], v[206:209], v[190:193], v[0:3]
	v_mfma_f32_16x16x32_bf16 v[52:55], v[202:205], v[170:173], v[52:55]
	v_mfma_f32_16x16x32_bf16 v[48:51], v[210:213], v[170:173], v[48:51]
	v_mfma_f32_16x16x32_bf16 v[36:39], v[202:205], v[178:181], v[36:39]
	v_mfma_f32_16x16x32_bf16 v[32:35], v[210:213], v[178:181], v[32:35]
	v_mfma_f32_16x16x32_bf16 v[20:23], v[202:205], v[186:189], v[20:23]
	v_mfma_f32_16x16x32_bf16 v[16:19], v[210:213], v[186:189], v[16:19]
	v_mfma_f32_16x16x32_bf16 v[4:7], v[202:205], v[194:197], v[4:7]
	v_mfma_f32_16x16x32_bf16 v[0:3], v[210:213], v[194:197], v[0:3]
	s_barrier
	s_cbranch_scc0 .LBB0_803
	s_setprio 0
	s_cmp_lg_u32 s98, 0
	s_cbranch_scc1 .Lxa_803
	s_barrier
.Lxa_803:
	v_mul_f32_e32 v151, 0xbfb8aa3b, v124
	v_mul_f32_e32 v154, 0xbfb8aa3b, v120
	v_exp_f32_e32 v151, v151
	v_exp_f32_e32 v155, v154
	v_mul_f32_e32 v154, 0xbfb8aa3b, v125
	v_exp_f32_e32 v156, v154
	v_add_f32_e32 v151, 1.0, v151
	v_rcp_f32_e32 v154, v151
	v_add_f32_e32 v151, 1.0, v155
	v_add_f32_e32 v155, 1.0, v156
	v_rcp_f32_e32 v155, v155
	v_mul_f32_e32 v156, 0xbfb8aa3b, v121
	v_exp_f32_e32 v157, v156
	v_rcp_f32_e32 v156, v151
	v_pk_mul_f32 v[124:125], v[124:125], v[154:155]
	v_mul_f32_e32 v151, 0xbfb8aa3b, v127
	v_pk_mul_f32 v[116:117], v[124:125], v[116:117]
	v_add_f32_e32 v124, 1.0, v157
	v_mul_f32_e32 v125, 0xbfb8aa3b, v122
	v_rcp_f32_e32 v157, v124
	v_mul_f32_e32 v124, 0xbfb8aa3b, v126
	v_exp_f32_e32 v125, v125
	v_exp_f32_e32 v124, v124
	v_exp_f32_e32 v151, v151
	v_mul_f32_e32 v154, 0xbfb8aa3b, v123
	v_exp_f32_e32 v155, v154
	v_add_f32_e32 v125, 1.0, v125
	v_add_f32_e32 v124, 1.0, v124
	v_rcp_f32_e32 v154, v125
	v_add_f32_e32 v125, 1.0, v151
	v_rcp_f32_e32 v124, v124
	v_rcp_f32_e32 v125, v125
	v_add_f32_e32 v151, 1.0, v155
	v_rcp_f32_e32 v155, v151
	v_pk_mul_f32 v[120:121], v[120:121], v[156:157]
	v_lshl_or_b32 v152, s65, 7, v146
	v_pk_mul_f32 v[112:113], v[120:121], v[112:113]
	v_pk_mul_f32 v[120:121], v[126:127], v[124:125]
	v_lshl_add_u32 v150, s20, 8, v144
	v_pk_mul_f32 v[118:119], v[120:121], v[118:119]
	v_pk_mul_f32 v[120:121], v[122:123], v[154:155]
	v_ashrrev_i32_e32 v153, 31, v152
	v_pk_mul_f32 v[114:115], v[120:121], v[114:115]
	v_cvt_pk_bf16_f32 v116, v116, v117
	v_cvt_pk_bf16_f32 v117, v118, v119
	v_cvt_pk_bf16_f32 v118, v112, v113
	v_mov_b64_e32 v[112:113], s[0:1]
	v_cvt_pk_bf16_f32 v119, v114, v115
	v_mad_i64_i32 v[120:121], s[10:11], v150, s64, v[112:113]
	v_lshlrev_b64 v[114:115], 1, v[152:153]
	v_lshl_add_u64 v[120:121], v[120:121], 0, v[114:115]
	global_store_dwordx4 v[120:121], v[116:119], off
	s_and_b64 vcc, exec, s[2:3]
	s_mov_b32 s65, s6
; __device__ __forceinline__ unsigned cvt_pk_bf16(float lo, float hi) { const bf16v2_t v = __builtin_convertvector((f32x2){lo, hi}, bf16v2_t); return __builtin_bit_cast(unsigned, v); }
; __device__ __forceinline__ float silu_f(float v) { return v * __builtin_amdgcn_rcpf(1.0f + __expf(-v)); }
;     __device__ __forceinline__ void operator()(const AccT& acc, const pg8::Unit& u, int wr, int wc, int fr, int fq) const {
;         const int row0 = u.pm * 256 + wr * 64 + fr, col = u.pn * 128 + wc * 32 + 8 * fq;
; #pragma unroll
;         for (int ai = 0; ai < 2; ++ai)
; #pragma unroll
;             for (int m = 0; m < 4; ++m) {
;                 f32x4 a = acc[ai][0][m][0], b = acc[ai][0][m][1];
; #pragma unroll
;                 for (int j = 0; j < 4; ++j) { a[j] = silu_f(a[j]) * acc[ai][1][m][0][j]; b[j] = silu_f(b[j]) * acc[ai][1][m][1][j]; }
;                 u32x4 w; w.x = cvt_pk_bf16(a[0], a[1]); w.y = cvt_pk_bf16(a[2], a[3]); w.z = cvt_pk_bf16(b[0], b[1]); w.w = cvt_pk_bf16(b[2], b[3]);
;                 *(u32x4*)(HID + (size_t)(row0 + ai * 128 + m * 16) * DFF + col) = w;
	v_mul_f32_e32 v116, 0xbfb8aa3b, v108
	v_mul_f32_e32 v117, 0xbfb8aa3b, v104
	v_mul_f32_e32 v118, 0xbfb8aa3b, v109
	v_exp_f32_e32 v116, v116
	v_exp_f32_e32 v117, v117
	v_exp_f32_e32 v118, v118
	s_mov_b32 s20, s8
	v_add_f32_e32 v116, 1.0, v116
	v_add_f32_e32 v119, 1.0, v117
	v_add_f32_e32 v117, 1.0, v118
	v_rcp_f32_e32 v116, v116
	v_rcp_f32_e32 v117, v117
	v_mul_f32_e32 v118, 0xbfb8aa3b, v105
	v_exp_f32_e32 v120, v118
	v_rcp_f32_e32 v118, v119
	v_pk_mul_f32 v[108:109], v[108:109], v[116:117]
	v_mul_f32_e32 v116, 0xbfb8aa3b, v111
	v_pk_mul_f32 v[100:101], v[108:109], v[100:101]
	v_add_f32_e32 v108, 1.0, v120
	v_rcp_f32_e32 v119, v108
	v_mul_f32_e32 v109, 0xbfb8aa3b, v106
	v_mul_f32_e32 v108, 0xbfb8aa3b, v110
	v_exp_f32_e32 v109, v109
	v_exp_f32_e32 v108, v108
	v_exp_f32_e32 v117, v116
	v_mul_f32_e32 v116, 0xbfb8aa3b, v107
	v_pk_mul_f32 v[104:105], v[104:105], v[118:119]
	v_exp_f32_e32 v118, v116
	v_add_f32_e32 v109, 1.0, v109
	v_add_f32_e32 v108, 1.0, v108
	v_rcp_f32_e32 v116, v109
	v_add_f32_e32 v109, 1.0, v117
	v_rcp_f32_e32 v108, v108
	v_rcp_f32_e32 v109, v109
	v_add_f32_e32 v117, 1.0, v118
	v_rcp_f32_e32 v117, v117
	v_pk_mul_f32 v[104:105], v[104:105], v[96:97]
	v_pk_mul_f32 v[96:97], v[110:111], v[108:109]
	s_mov_b64 s[28:29], s[18:19]
	v_pk_mul_f32 v[102:103], v[96:97], v[102:103]
	v_pk_mul_f32 v[96:97], v[106:107], v[116:117]
	s_mov_b64 s[26:27], s[16:17]
	v_pk_mul_f32 v[106:107], v[96:97], v[98:99]
	v_cvt_pk_bf16_f32 v96, v100, v101
	v_or_b32_e32 v100, 16, v150
	v_mad_i64_i32 v[100:101], s[10:11], v100, s64, v[112:113]
	v_cvt_pk_bf16_f32 v97, v102, v103
	v_cvt_pk_bf16_f32 v98, v104, v105
	v_cvt_pk_bf16_f32 v99, v106, v107
	v_lshl_add_u64 v[100:101], v[100:101], 0, v[114:115]
	global_store_dwordx4 v[100:101], v[96:99], off
	s_nop 1
	v_mul_f32_e32 v96, 0xbfb8aa3b, v92
	v_mul_f32_e32 v97, 0xbfb8aa3b, v88
	v_mul_f32_e32 v98, 0xbfb8aa3b, v93
	v_exp_f32_e32 v96, v96
	v_exp_f32_e32 v97, v97
	v_exp_f32_e32 v98, v98
	v_add_f32_e32 v96, 1.0, v96
	v_add_f32_e32 v99, 1.0, v97
	v_add_f32_e32 v97, 1.0, v98
	v_rcp_f32_e32 v96, v96
	v_rcp_f32_e32 v97, v97
	v_mul_f32_e32 v98, 0xbfb8aa3b, v89
	v_exp_f32_e32 v100, v98
	v_rcp_f32_e32 v98, v99
	v_pk_mul_f32 v[92:93], v[92:93], v[96:97]
	v_mul_f32_e32 v96, 0xbfb8aa3b, v95
	v_pk_mul_f32 v[84:85], v[92:93], v[84:85]
	v_add_f32_e32 v92, 1.0, v100
	v_rcp_f32_e32 v99, v92
	v_mul_f32_e32 v93, 0xbfb8aa3b, v90
	v_mul_f32_e32 v92, 0xbfb8aa3b, v94
	v_exp_f32_e32 v93, v93
	v_exp_f32_e32 v92, v92
	v_exp_f32_e32 v97, v96
	v_mul_f32_e32 v96, 0xbfb8aa3b, v91
	v_pk_mul_f32 v[88:89], v[88:89], v[98:99]
	v_exp_f32_e32 v98, v96
	v_add_f32_e32 v93, 1.0, v93
	v_add_f32_e32 v92, 1.0, v92
	v_rcp_f32_e32 v96, v93
	v_add_f32_e32 v93, 1.0, v97
	v_rcp_f32_e32 v92, v92
	v_rcp_f32_e32 v93, v93
	v_add_f32_e32 v97, 1.0, v98
	v_rcp_f32_e32 v97, v97
	v_pk_mul_f32 v[88:89], v[88:89], v[80:81]
	v_pk_mul_f32 v[80:81], v[94:95], v[92:93]
	s_nop 0
	v_pk_mul_f32 v[86:87], v[80:81], v[86:87]
	v_pk_mul_f32 v[80:81], v[90:91], v[96:97]
	s_nop 0
	v_pk_mul_f32 v[90:91], v[80:81], v[82:83]
	v_cvt_pk_bf16_f32 v80, v84, v85
	v_or_b32_e32 v84, 32, v150
	v_mad_i64_i32 v[84:85], s[10:11], v84, s64, v[112:113]
	v_cvt_pk_bf16_f32 v81, v86, v87
	v_cvt_pk_bf16_f32 v82, v88, v89
	v_cvt_pk_bf16_f32 v83, v90, v91
	v_lshl_add_u64 v[84:85], v[84:85], 0, v[114:115]
	global_store_dwordx4 v[84:85], v[80:83], off
	s_nop 1
	v_mul_f32_e32 v80, 0xbfb8aa3b, v76
	v_mul_f32_e32 v81, 0xbfb8aa3b, v72
	v_mul_f32_e32 v82, 0xbfb8aa3b, v77
	v_exp_f32_e32 v80, v80
	v_exp_f32_e32 v81, v81
	v_exp_f32_e32 v82, v82
	v_add_f32_e32 v80, 1.0, v80
	v_add_f32_e32 v83, 1.0, v81
	v_add_f32_e32 v81, 1.0, v82
	v_rcp_f32_e32 v80, v80
	v_rcp_f32_e32 v81, v81
	v_mul_f32_e32 v82, 0xbfb8aa3b, v73
	v_exp_f32_e32 v84, v82
	v_rcp_f32_e32 v82, v83
	v_pk_mul_f32 v[76:77], v[76:77], v[80:81]
	v_mul_f32_e32 v80, 0xbfb8aa3b, v79
	v_pk_mul_f32 v[68:69], v[76:77], v[68:69]
	v_add_f32_e32 v76, 1.0, v84
	v_rcp_f32_e32 v83, v76
	v_mul_f32_e32 v77, 0xbfb8aa3b, v74
	v_mul_f32_e32 v76, 0xbfb8aa3b, v78
	v_exp_f32_e32 v77, v77
	v_exp_f32_e32 v76, v76
	v_exp_f32_e32 v81, v80
	v_mul_f32_e32 v80, 0xbfb8aa3b, v75
	v_pk_mul_f32 v[72:73], v[72:73], v[82:83]
	v_exp_f32_e32 v82, v80
	v_add_f32_e32 v77, 1.0, v77
	v_add_f32_e32 v76, 1.0, v76
	v_rcp_f32_e32 v80, v77
	v_add_f32_e32 v77, 1.0, v81
	v_rcp_f32_e32 v76, v76
	v_rcp_f32_e32 v77, v77
	v_add_f32_e32 v81, 1.0, v82
	v_rcp_f32_e32 v81, v81
	v_pk_mul_f32 v[72:73], v[72:73], v[64:65]
	v_pk_mul_f32 v[64:65], v[78:79], v[76:77]
	s_nop 0
	v_pk_mul_f32 v[70:71], v[64:65], v[70:71]
	v_pk_mul_f32 v[64:65], v[74:75], v[80:81]
	s_nop 0
	v_pk_mul_f32 v[74:75], v[64:65], v[66:67]
	v_cvt_pk_bf16_f32 v64, v68, v69
	v_or_b32_e32 v68, 48, v150
	v_mad_i64_i32 v[68:69], s[10:11], v68, s64, v[112:113]
	v_cvt_pk_bf16_f32 v65, v70, v71
	v_cvt_pk_bf16_f32 v66, v72, v73
	v_cvt_pk_bf16_f32 v67, v74, v75
	v_lshl_add_u64 v[68:69], v[68:69], 0, v[114:115]
	global_store_dwordx4 v[68:69], v[64:67], off
	v_add_u32_e32 v68, 0x80, v150
	s_nop 0
	v_mul_f32_e32 v64, 0xbfb8aa3b, v60
	v_mul_f32_e32 v65, 0xbfb8aa3b, v56
	v_mul_f32_e32 v66, 0xbfb8aa3b, v61
	v_exp_f32_e32 v64, v64
	v_exp_f32_e32 v65, v65
	v_exp_f32_e32 v66, v66
	v_add_f32_e32 v64, 1.0, v64
	v_add_f32_e32 v67, 1.0, v65
	v_add_f32_e32 v65, 1.0, v66
	v_rcp_f32_e32 v64, v64
	v_rcp_f32_e32 v65, v65
	v_mul_f32_e32 v66, 0xbfb8aa3b, v57
	v_exp_f32_e32 v69, v66
	v_rcp_f32_e32 v66, v67
	v_pk_mul_f32 v[60:61], v[60:61], v[64:65]
	v_mul_f32_e32 v64, 0xbfb8aa3b, v63
	v_pk_mul_f32 v[52:53], v[60:61], v[52:53]
	v_add_f32_e32 v60, 1.0, v69
	v_rcp_f32_e32 v67, v60
	v_mul_f32_e32 v61, 0xbfb8aa3b, v58
	v_mul_f32_e32 v60, 0xbfb8aa3b, v62
	v_exp_f32_e32 v61, v61
; __device__ __forceinline__ unsigned cvt_pk_bf16(float lo, float hi) { const bf16v2_t v = __builtin_convertvector((f32x2){lo, hi}, bf16v2_t); return __builtin_bit_cast(unsigned, v); }
; __device__ __forceinline__ float silu_f(float v) { return v * __builtin_amdgcn_rcpf(1.0f + __expf(-v)); }
; #define PG8_WAIT_V(n) asm volatile("s_waitcnt vmcnt(" #n ")" ::: "memory")
; #define PG8_BAR __builtin_amdgcn_s_barrier()
; template <class Epi, class Sched>
; __device__ __forceinline__ void gemm_phase(PG8_LAS unsigned char* lds, const Gemm g, const Sched& S, const Epi& E) {
;     ...
;         E(acc, cur, wr, wc, fr, fq); S.done(cur);
;         if (!has_next) break;
; #pragma unroll
;         for (int a = 0; a < 2; ++a)
; #pragma unroll
;             for (int b = 0; b < 2; ++b)
; #pragma unroll
;                 for (int m = 0; m < 4; ++m)
; #pragma unroll
;                     for (int n = 0; n < 2; ++n) acc[a][b][m][n] = (f32x4){0.f, 0.f, 0.f, 0.f};
;         cur = nxt; cA = nA; cB = nB; ++ui;
;     }
;     PG8_WAIT_V(0);
;     if (wr == 0) PG8_BAR;
;     PG8_BAR;
;     __device__ __forceinline__ void operator()(const AccT& acc, const pg8::Unit& u, int wr, int wc, int fr, int fq) const {
;         const int row0 = u.pm * 256 + wr * 64 + fr, col = u.pn * 128 + wc * 32 + 8 * fq;
; #pragma unroll
;         for (int ai = 0; ai < 2; ++ai)
; #pragma unroll
;             for (int m = 0; m < 4; ++m) {
;                 f32x4 a = acc[ai][0][m][0], b = acc[ai][0][m][1];
; #pragma unroll
;                 for (int j = 0; j < 4; ++j) { a[j] = silu_f(a[j]) * acc[ai][1][m][0][j]; b[j] = silu_f(b[j]) * acc[ai][1][m][1][j]; }
;                 u32x4 w; w.x = cvt_pk_bf16(a[0], a[1]); w.y = cvt_pk_bf16(a[2], a[3]); w.z = cvt_pk_bf16(b[0], b[1]); w.w = cvt_pk_bf16(b[2], b[3]);
;                 *(u32x4*)(HID + (size_t)(row0 + ai * 128 + m * 16) * DFF + col) = w;
	v_exp_f32_e32 v60, v60
	v_exp_f32_e32 v65, v64
	v_mul_f32_e32 v64, 0xbfb8aa3b, v59
	v_pk_mul_f32 v[56:57], v[56:57], v[66:67]
	v_exp_f32_e32 v66, v64
	v_add_f32_e32 v61, 1.0, v61
	v_add_f32_e32 v60, 1.0, v60
	v_rcp_f32_e32 v64, v61
	v_add_f32_e32 v61, 1.0, v65
	v_rcp_f32_e32 v60, v60
	v_rcp_f32_e32 v61, v61
	v_add_f32_e32 v65, 1.0, v66
	v_rcp_f32_e32 v65, v65
	v_pk_mul_f32 v[56:57], v[56:57], v[48:49]
	v_pk_mul_f32 v[48:49], v[62:63], v[60:61]
	s_nop 0
	v_pk_mul_f32 v[54:55], v[48:49], v[54:55]
	v_pk_mul_f32 v[48:49], v[58:59], v[64:65]
	s_nop 0
	v_pk_mul_f32 v[58:59], v[48:49], v[50:51]
	v_cvt_pk_bf16_f32 v48, v52, v53
	v_mad_i64_i32 v[52:53], s[10:11], v68, s64, v[112:113]
	v_cvt_pk_bf16_f32 v49, v54, v55
	v_cvt_pk_bf16_f32 v50, v56, v57
	v_cvt_pk_bf16_f32 v51, v58, v59
	v_lshl_add_u64 v[52:53], v[52:53], 0, v[114:115]
	global_store_dwordx4 v[52:53], v[48:51], off
	s_nop 1
	v_mul_f32_e32 v48, 0xbfb8aa3b, v44
	v_mul_f32_e32 v49, 0xbfb8aa3b, v40
	v_mul_f32_e32 v50, 0xbfb8aa3b, v45
	v_exp_f32_e32 v48, v48
	v_exp_f32_e32 v49, v49
	v_exp_f32_e32 v50, v50
	v_add_f32_e32 v48, 1.0, v48
	v_add_f32_e32 v51, 1.0, v49
	v_add_f32_e32 v49, 1.0, v50
	v_rcp_f32_e32 v48, v48
	v_rcp_f32_e32 v49, v49
	v_mul_f32_e32 v50, 0xbfb8aa3b, v41
	v_exp_f32_e32 v52, v50
	v_rcp_f32_e32 v50, v51
	v_pk_mul_f32 v[44:45], v[44:45], v[48:49]
	v_mul_f32_e32 v48, 0xbfb8aa3b, v47
	v_pk_mul_f32 v[36:37], v[44:45], v[36:37]
	v_add_f32_e32 v44, 1.0, v52
	v_rcp_f32_e32 v51, v44
	v_mul_f32_e32 v45, 0xbfb8aa3b, v42
	v_mul_f32_e32 v44, 0xbfb8aa3b, v46
	v_exp_f32_e32 v45, v45
	v_exp_f32_e32 v44, v44
	v_exp_f32_e32 v49, v48
	v_mul_f32_e32 v48, 0xbfb8aa3b, v43
	v_pk_mul_f32 v[40:41], v[40:41], v[50:51]
	v_exp_f32_e32 v50, v48
	v_add_f32_e32 v45, 1.0, v45
	v_add_f32_e32 v44, 1.0, v44
	v_rcp_f32_e32 v48, v45
	v_add_f32_e32 v45, 1.0, v49
	v_rcp_f32_e32 v44, v44
	v_rcp_f32_e32 v45, v45
	v_add_f32_e32 v49, 1.0, v50
	v_rcp_f32_e32 v49, v49
	v_pk_mul_f32 v[40:41], v[40:41], v[32:33]
	v_pk_mul_f32 v[32:33], v[46:47], v[44:45]
	s_nop 0
	v_pk_mul_f32 v[38:39], v[32:33], v[38:39]
	v_pk_mul_f32 v[32:33], v[42:43], v[48:49]
	s_nop 0
	v_pk_mul_f32 v[42:43], v[32:33], v[34:35]
	v_cvt_pk_bf16_f32 v32, v36, v37
	v_add_u32_e32 v36, 0x90, v150
	v_mad_i64_i32 v[36:37], s[10:11], v36, s64, v[112:113]
	v_cvt_pk_bf16_f32 v33, v38, v39
	v_cvt_pk_bf16_f32 v34, v40, v41
	v_cvt_pk_bf16_f32 v35, v42, v43
	v_lshl_add_u64 v[36:37], v[36:37], 0, v[114:115]
	global_store_dwordx4 v[36:37], v[32:35], off
	s_nop 1
	v_mul_f32_e32 v32, 0xbfb8aa3b, v28
	v_mul_f32_e32 v33, 0xbfb8aa3b, v24
	v_mul_f32_e32 v34, 0xbfb8aa3b, v29
	v_exp_f32_e32 v32, v32
	v_exp_f32_e32 v33, v33
	v_exp_f32_e32 v34, v34
	v_add_f32_e32 v32, 1.0, v32
	v_add_f32_e32 v35, 1.0, v33
	v_add_f32_e32 v33, 1.0, v34
	v_rcp_f32_e32 v32, v32
	v_rcp_f32_e32 v33, v33
	v_mul_f32_e32 v34, 0xbfb8aa3b, v25
	v_exp_f32_e32 v36, v34
	v_rcp_f32_e32 v34, v35
	v_pk_mul_f32 v[28:29], v[28:29], v[32:33]
	v_mul_f32_e32 v32, 0xbfb8aa3b, v31
	v_pk_mul_f32 v[20:21], v[28:29], v[20:21]
	v_add_f32_e32 v28, 1.0, v36
	v_rcp_f32_e32 v35, v28
	v_mul_f32_e32 v29, 0xbfb8aa3b, v26
	v_mul_f32_e32 v28, 0xbfb8aa3b, v30
	v_exp_f32_e32 v29, v29
	v_exp_f32_e32 v28, v28
	v_exp_f32_e32 v33, v32
	v_mul_f32_e32 v32, 0xbfb8aa3b, v27
	v_pk_mul_f32 v[24:25], v[24:25], v[34:35]
	v_exp_f32_e32 v34, v32
	v_add_f32_e32 v29, 1.0, v29
	v_add_f32_e32 v28, 1.0, v28
	v_rcp_f32_e32 v32, v29
	v_add_f32_e32 v29, 1.0, v33
	v_rcp_f32_e32 v28, v28
	v_rcp_f32_e32 v29, v29
	v_add_f32_e32 v33, 1.0, v34
	v_rcp_f32_e32 v33, v33
	v_pk_mul_f32 v[24:25], v[24:25], v[16:17]
	v_pk_mul_f32 v[16:17], v[30:31], v[28:29]
	s_nop 0
	v_pk_mul_f32 v[22:23], v[16:17], v[22:23]
	v_pk_mul_f32 v[16:17], v[26:27], v[32:33]
	s_nop 0
	v_pk_mul_f32 v[26:27], v[16:17], v[18:19]
	v_cvt_pk_bf16_f32 v16, v20, v21
	v_add_u32_e32 v20, 0xa0, v150
	v_mad_i64_i32 v[20:21], s[10:11], v20, s64, v[112:113]
	v_cvt_pk_bf16_f32 v17, v22, v23
	v_cvt_pk_bf16_f32 v18, v24, v25
	v_cvt_pk_bf16_f32 v19, v26, v27
	v_lshl_add_u64 v[20:21], v[20:21], 0, v[114:115]
	global_store_dwordx4 v[20:21], v[16:19], off
	s_nop 1
	v_mul_f32_e32 v16, 0xbfb8aa3b, v12
	v_mul_f32_e32 v17, 0xbfb8aa3b, v8
	v_mul_f32_e32 v18, 0xbfb8aa3b, v13
	v_exp_f32_e32 v16, v16
	v_exp_f32_e32 v17, v17
	v_exp_f32_e32 v18, v18
	v_add_f32_e32 v16, 1.0, v16
	v_add_f32_e32 v19, 1.0, v17
	v_add_f32_e32 v17, 1.0, v18
	v_rcp_f32_e32 v16, v16
	v_rcp_f32_e32 v17, v17
	v_mul_f32_e32 v18, 0xbfb8aa3b, v9
	v_exp_f32_e32 v20, v18
	v_rcp_f32_e32 v18, v19
	v_pk_mul_f32 v[12:13], v[12:13], v[16:17]
	v_mul_f32_e32 v16, 0xbfb8aa3b, v15
	v_pk_mul_f32 v[4:5], v[12:13], v[4:5]
	v_add_f32_e32 v12, 1.0, v20
	v_rcp_f32_e32 v19, v12
	v_mul_f32_e32 v13, 0xbfb8aa3b, v10
	v_mul_f32_e32 v12, 0xbfb8aa3b, v14
	v_exp_f32_e32 v13, v13
	v_exp_f32_e32 v12, v12
	v_exp_f32_e32 v17, v16
	v_mul_f32_e32 v16, 0xbfb8aa3b, v11
	v_pk_mul_f32 v[8:9], v[8:9], v[18:19]
	v_exp_f32_e32 v18, v16
	v_add_f32_e32 v13, 1.0, v13
	v_add_f32_e32 v12, 1.0, v12
	v_rcp_f32_e32 v16, v13
	v_add_f32_e32 v13, 1.0, v17
	v_rcp_f32_e32 v12, v12
	v_rcp_f32_e32 v13, v13
	v_add_f32_e32 v17, 1.0, v18
	v_rcp_f32_e32 v17, v17
	v_pk_mul_f32 v[8:9], v[8:9], v[0:1]
	v_pk_mul_f32 v[0:1], v[14:15], v[12:13]
	s_nop 0
	v_pk_mul_f32 v[6:7], v[0:1], v[6:7]
	v_pk_mul_f32 v[0:1], v[10:11], v[16:17]
	s_nop 0
	v_pk_mul_f32 v[10:11], v[0:1], v[2:3]
	v_cvt_pk_bf16_f32 v0, v4, v5
	v_add_u32_e32 v4, 0xb0, v150
	v_mad_i64_i32 v[4:5], s[10:11], v4, s64, v[112:113]
	v_cvt_pk_bf16_f32 v1, v6, v7
	v_cvt_pk_bf16_f32 v2, v8, v9
	v_cvt_pk_bf16_f32 v3, v10, v11
	v_lshl_add_u64 v[4:5], v[4:5], 0, v[114:115]
	global_store_dwordx4 v[4:5], v[0:3], off
	s_cmp_eq_u32 s98, 0
	s_cbranch_scc1 .Lxb_803
	s_barrier
.Lxb_803:
	s_cbranch_vccz .LBB0_800
	s_waitcnt vmcnt(0)
	s_cmpk_gt_u32 s34, 0xff
	s_cbranch_scc1 .LBB0_807
	s_barrier

; #define PG8_STAGE(bufoff, gbase, voff) do { _Pragma("unroll") for (int _i = 0; _i < 2; ++_i) \
;         __builtin_amdgcn_global_load_lds((const unsigned*)((const char*)(gbase) + (voff)[_i]), (PG8_LAS unsigned*)(lds + (bufoff) + ldsw + _i * 8192), 16, 0, 0); } while (0)
; #define PG8_WAIT_V(n) asm volatile("s_waitcnt vmcnt(" #n ")" ::: "memory")
; #define PG8_BAR __builtin_amdgcn_s_barrier()
; template <class Epi, class Sched>
; __device__ __forceinline__ void gemm_phase(PG8_LAS unsigned char* lds, const Gemm g, const Sched& S, const Epi& E) {
;     const int tid = threadIdx.x, wid = __builtin_amdgcn_readfirstlane(tid >> 6), lane = tid & 63, wr = wid >> 2, wc = wid & 3, fr = lane & 15, fq = lane >> 4;
;     const int K = g.K, nt = K / BK;
;     unsigned voffA[2], voffB[2];
; #pragma unroll
;     for (int i = 0; i < 2; ++i) { int R, C; stage_rc(tid * 16 + i * 8192, R, C); const int Rb = Epi::PERM ? ((R & ~31) + perm32(R & 31)) : R;
;         voffA[i] = (unsigned)(R * K + C) * 2u; voffB[i] = (unsigned)(Rb * K + C) * 2u; }
;     const size_t kstep = (size_t)(BK * 2);
;     const size_t hstep = (size_t)HALF * K * 2;
;     const size_t tstep = 2 * hstep;
;     const unsigned ldsw = (unsigned)wid * 1024u;
;     const int aoff = lds_byte(wr * 64 + fr, fq * 8), boff = lds_byte(wc * 32 + fr, fq * 8);
;     ...
;     Unit cur, nxt; int ui = 0;
;     if (!S.next(0, cur)) return;
;     f32x4 acc[2][2][4][2];
; #pragma unroll
;     for (int a = 0; a < 2; ++a)
; #pragma unroll
;         for (int b = 0; b < 2; ++b)
; #pragma unroll
;             for (int m = 0; m < 4; ++m)
; #pragma unroll
;                 for (int n = 0; n < 2; ++n) acc[a][b][m][n] = (f32x4){0.f, 0.f, 0.f, 0.f};
;     bf16x8 At[4][2], B0[2][2], B1[2][2];
;     const char* cA = (const char*)g.A + (size_t)cur.pm * tstep; const char* cB = (const char*)g.Bt + (size_t)cur.pn * tstep;
;     S.a_ready(cur);
;     PG8_STAGE(PG8_SB(0, 0), cB, voffB); PG8_STAGE(PG8_SA(0, 0), cA, voffA); PG8_STAGE(PG8_SB(0, 1), cB + hstep, voffB); PG8_STAGE(PG8_SA(0, 1), cA + hstep, voffA);
;     if (wr == 1) PG8_BAR;
;     PG8_WAIT_V(4); PG8_BAR;
;     PG8_STAGE(PG8_SB(1, 0), cB + kstep, voffB); PG8_STAGE(PG8_SA(1, 0), cA + kstep, voffA); PG8_STAGE(PG8_SB(1, 1), cB + hstep + kstep, voffB);
;     PG8_WAIT_V(6); PG8_BAR;
.LBB0_870:
	s_add_u32 s6, s58, 0xfc86000
	s_addc_u32 s7, s59, 0
	s_add_u32 s8, s58, 0x6a26000
	s_addc_u32 s9, s59, 0
	s_add_u32 s16, s58, 0x7a86000
	s_addc_u32 s17, s59, 0
	s_lshl_b32 s2, s2, 5
	s_mov_b64 s[18:19], 0x80
	s_and_b32 s5, s2, 0x60
	s_add_i32 m0, s40, 0x18000
	v_lshl_add_u64 v[6:7], v[6:7], 0, s[18:19]
	s_lshl_b32 s4, s0, 13
	s_lshl_b32 s10, s5, 7
	v_readfirstlane_b32 s98, v242
	s_lshr_b32 s98, s98, 8
	s_waitcnt vmcnt(2)
	s_barrier
	global_load_lds_dwordx4 v[6:7], off
	v_lshl_add_u64 v[4:5], v[4:5], 0, s[18:19]
	s_add_i32 m0, s40, 0x1a000
	s_add_i32 s45, s40, 0x8000
	s_add_i32 s46, s40, 0xa000
	global_load_lds_dwordx4 v[4:5], off
	v_lshl_add_u64 v[2:3], v[2:3], 0, s[18:19]
	s_mov_b32 m0, s45
	s_add_u32 s2, s28, 0x160080
	global_load_lds_dwordx4 v[2:3], off
	v_lshl_add_u64 v[0:1], v[0:1], 0, s[18:19]
	s_mov_b32 m0, s46
	s_addc_u32 s3, s29, 0
	global_load_lds_dwordx4 v[0:1], off
	s_add_i32 m0, s40, 0x1c000
	v_lshl_add_u64 v[0:1], s[2:3], 0, v[178:179]
	global_load_lds_dwordx4 v[0:1], off
	v_lshl_add_u64 v[0:1], s[2:3], 0, v[182:183]
	s_add_i32 m0, s40, 0x1e000
	v_lshlrev_b32_e32 v2, 2, v242
	global_load_lds_dwordx4 v[0:1], off
	v_and_b32_e32 v0, 15, v242
	v_lshl_or_b32 v244, s0, 6, v0
	v_lshlrev_b32_e32 v1, 1, v10
	v_lshlrev_b32_e32 v3, 6, v242
	s_movk_i32 s0, 0x3c0
	v_lshl_or_b32 v0, v0, 6, v1
	v_and_b32_e32 v2, 32, v2
	v_and_or_b32 v1, v3, s0, v1
	v_bitop3_b32 v245, s10, v1, v2 bitop3:0xf6
	s_waitcnt vmcnt(6)
	v_add_u16_e32 v1, v8, v9
	v_bitop3_b32 v0, v0, s4, v2 bitop3:0xde
	v_lshrrev_b16_e32 v1, 1, v1
	s_add_i32 s49, 0, 0x10000
	s_add_i32 s50, 0, 0x14000
	s_sext_i32_i8 s66, s1
	s_ashr_i32 s47, s62, 31
	s_mov_b32 s48, s62
	v_or_b32_e32 v246, s5, v10
	v_add_lshl_u32 v184, v11, v1, 1
	v_mov_b32_e32 v185, v179
	v_add_lshl_u32 v186, v12, v1, 1
	v_mov_b32_e32 v187, v179
	v_add_u32_e32 v247, s49, v245
	v_add_u32_e32 v248, 0, v0
	v_add_u32_e32 v249, s50, v245
	s_mov_b32 s20, 0x3f9837f0
	s_barrier

; #define PG8_STAGE(bufoff, gbase, voff) do { _Pragma("unroll") for (int _i = 0; _i < 2; ++_i) \
;         __builtin_amdgcn_global_load_lds((const unsigned*)((const char*)(gbase) + (voff)[_i]), (PG8_LAS unsigned*)(lds + (bufoff) + ldsw + _i * 8192), 16, 0, 0); } while (0)
; #define PG8_LDA(dst, b, h) do { _Pragma("unroll") for (int m = 0; m < 4; ++m) _Pragma("unroll") for (int k = 0; k < 2; ++k) dst[m][k] = *(const PG8_LAS bf16x8*)(lds + PG8_SA(b, h) + aoff + m * 2048 + k * 1024); } while (0)
; #define PG8_LDB(dst, b, h) do { _Pragma("unroll") for (int n = 0; n < 2; ++n) _Pragma("unroll") for (int k = 0; k < 2; ++k) dst[n][k] = *(const PG8_LAS bf16x8*)(lds + PG8_SB(b, h) + boff + n * 2048 + k * 1024); } while (0)
; #define PG8_MMA(ai, bj, At, Bt) do { __builtin_amdgcn_s_setprio(1); _Pragma("unroll") for (int m = 0; m < 4; ++m) _Pragma("unroll") for (int n = 0; n < 2; ++n) _Pragma("unroll") for (int k = 0; k < 2; ++k) \
;         acc[ai][bj][m][n] = __builtin_amdgcn_mfma_f32_16x16x32_bf16(Bt[n][k], At[m][k], acc[ai][bj][m][n], 0, 0, 0); __builtin_amdgcn_s_setprio(0); } while (0)
; #define PG8_WAIT_V(n) asm volatile("s_waitcnt vmcnt(" #n ")" ::: "memory")
; #define PG8_WAIT_L(n) asm volatile("s_waitcnt lgkmcnt(" #n ")" ::: "memory")
; #define PG8_BAR __builtin_amdgcn_s_barrier()
; template <class Epi, class Sched>
; __device__ __forceinline__ void gemm_phase(PG8_LAS unsigned char* lds, const Gemm g, const Sched& S, const Epi& E) {
;     ...
;             const char* a1 = cA + (size_t)(t + 1) * kstep;
;             const char* a2 = last ? nA : cA + (size_t)(t + 2) * kstep; const char* b2 = last ? nB : cB + (size_t)(t + 2) * kstep;
;             const char* a3 = a2 + kstep; const char* b3 = b2 + kstep;
;             if (last && has_next) S.a_ready(nxt);
;             PG8_LDB(B0, 0, 0); PG8_SCHED; PG8_LDA(At, 0, 0); PG8_STAGE(PG8_SA(1, 1), a1 + hstep, voffA);
;             PG8_WAIT_L(8); PG8_BAR; PG8_WAIT_L(0); PG8_MMA(0, 0, At, B0); PG8_BAR; PG8_SCHED;
;             PG8_LDB(B1, 0, 1); PG8_STAGE(PG8_SB(0, 0), b2, voffB);
;             PG8_BAR; PG8_WAIT_L(0); PG8_MMA(0, 1, At, B1); PG8_BAR;
;             PG8_LDA(At, 0, 1); PG8_STAGE(PG8_SA(0, 0), a2, voffA);
;             PG8_BAR; PG8_WAIT_L(0); PG8_MMA(1, 0, At, B0); PG8_BAR; PG8_SCHED;
;             PG8_STAGE(PG8_SB(0, 1), b2 + hstep, voffB);
;             PG8_WAIT_V(6); PG8_BAR; PG8_MMA(1, 1, At, B1); PG8_BAR;
.LBB0_882:
	s_setprio 0
	ds_read_b128 v[108:111], v247
	ds_read_b128 v[112:115], v247 offset:1024
	ds_read_b128 v[124:127], v247 offset:2048
	ds_read_b128 v[128:131], v247 offset:3072
	ds_read_b128 v[144:147], v248
	ds_read_b128 v[148:151], v248 offset:1024
	ds_read_b128 v[152:155], v248 offset:2048
	ds_read_b128 v[156:159], v248 offset:3072
	ds_read_b128 v[160:163], v248 offset:4096
	ds_read_b128 v[164:167], v248 offset:5120
	ds_read_b128 v[168:171], v248 offset:6144
	ds_read_b128 v[172:175], v248 offset:7168
	ds_read_b128 v[188:191], v249
	ds_read_b128 v[192:195], v249 offset:1024
	ds_read_b128 v[196:199], v249 offset:2048
	ds_read_b128 v[200:203], v249 offset:3072
	s_add_u32 s10, s26, 0xffea0080
	s_addc_u32 s11, s27, -1
	s_cmpk_eq_i32 s69, 0x54
	s_cselect_b32 s31, s1, s11
	s_cselect_b32 s30, s0, s10
	s_cselect_b32 s29, s5, s68
	s_cselect_b32 s28, s4, s67
	v_lshl_add_u64 v[252:253], s[26:27], 0, v[184:185]
	s_add_i32 m0, s40, 0xc000
	s_nop 0
	global_load_lds_dwordx4 v[252:253], off
	v_lshl_add_u64 v[252:253], s[26:27], 0, v[186:187]
	s_add_i32 m0, s40, 0xe000
	s_nop 0
	global_load_lds_dwordx4 v[252:253], off
	s_waitcnt vmcnt(8)
	s_waitcnt lgkmcnt(0)
	s_setprio 1
	s_barrier
	v_mfma_f32_16x16x32_bf16 v[140:143], v[108:111], v[144:147], v[140:143]
	v_mfma_f32_16x16x32_bf16 v[136:139], v[124:127], v[144:147], v[136:139]
	v_mfma_f32_16x16x32_bf16 v[116:119], v[108:111], v[152:155], v[116:119]
	v_mfma_f32_16x16x32_bf16 v[104:107], v[124:127], v[152:155], v[104:107]
	v_mfma_f32_16x16x32_bf16 v[92:95], v[108:111], v[160:163], v[92:95]
	v_mfma_f32_16x16x32_bf16 v[88:91], v[124:127], v[160:163], v[88:91]
	v_mfma_f32_16x16x32_bf16 v[76:79], v[108:111], v[168:171], v[76:79]
	v_mfma_f32_16x16x32_bf16 v[72:75], v[124:127], v[168:171], v[72:75]
	v_mfma_f32_16x16x32_bf16 v[140:143], v[112:115], v[148:151], v[140:143]
	v_mfma_f32_16x16x32_bf16 v[136:139], v[128:131], v[148:151], v[136:139]
	v_mfma_f32_16x16x32_bf16 v[116:119], v[112:115], v[156:159], v[116:119]
	v_mfma_f32_16x16x32_bf16 v[104:107], v[128:131], v[156:159], v[104:107]
	v_mfma_f32_16x16x32_bf16 v[92:95], v[112:115], v[164:167], v[92:95]
	v_mfma_f32_16x16x32_bf16 v[88:91], v[128:131], v[164:167], v[88:91]
	v_mfma_f32_16x16x32_bf16 v[76:79], v[112:115], v[172:175], v[76:79]
	v_mfma_f32_16x16x32_bf16 v[72:75], v[128:131], v[172:175], v[72:75]
	v_mfma_f32_16x16x32_bf16 v[132:135], v[188:191], v[144:147], v[132:135]
	v_mfma_f32_16x16x32_bf16 v[120:123], v[196:199], v[144:147], v[120:123]
	v_mfma_f32_16x16x32_bf16 v[100:103], v[188:191], v[152:155], v[100:103]
	v_mfma_f32_16x16x32_bf16 v[96:99], v[196:199], v[152:155], v[96:99]
	v_mfma_f32_16x16x32_bf16 v[84:87], v[188:191], v[160:163], v[84:87]
	v_mfma_f32_16x16x32_bf16 v[80:83], v[196:199], v[160:163], v[80:83]
	v_mfma_f32_16x16x32_bf16 v[68:71], v[188:191], v[168:171], v[68:71]
	v_mfma_f32_16x16x32_bf16 v[64:67], v[196:199], v[168:171], v[64:67]
	v_mfma_f32_16x16x32_bf16 v[132:135], v[192:195], v[148:151], v[132:135]
	v_mfma_f32_16x16x32_bf16 v[120:123], v[200:203], v[148:151], v[120:123]
	v_mfma_f32_16x16x32_bf16 v[100:103], v[192:195], v[156:159], v[100:103]
	v_mfma_f32_16x16x32_bf16 v[96:99], v[200:203], v[156:159], v[96:99]
	v_mfma_f32_16x16x32_bf16 v[84:87], v[192:195], v[164:167], v[84:87]
	v_mfma_f32_16x16x32_bf16 v[80:83], v[200:203], v[164:167], v[80:83]
	v_mfma_f32_16x16x32_bf16 v[68:71], v[192:195], v[172:175], v[68:71]
	v_mfma_f32_16x16x32_bf16 v[64:67], v[200:203], v[172:175], v[64:67]
	s_barrier
	s_setprio 0
	ds_read_b128 v[144:147], v248 offset:16384
	ds_read_b128 v[148:151], v248 offset:17408
	ds_read_b128 v[152:155], v248 offset:18432
	ds_read_b128 v[156:159], v248 offset:19456
	ds_read_b128 v[160:163], v248 offset:20480
	ds_read_b128 v[164:167], v248 offset:21504
	ds_read_b128 v[168:171], v248 offset:22528
	ds_read_b128 v[172:175], v248 offset:23552
	s_add_i32 s10, s49, s39
	v_lshl_add_u64 v[204:205], s[28:29], 0, v[178:179]
	s_mov_b32 m0, s10
	s_nop 0
	global_load_lds_dwordx4 v[204:205], off
	v_lshl_add_u64 v[206:207], s[28:29], 0, v[182:183]
	s_add_i32 m0, s10, 0x2000
	s_nop 0
	global_load_lds_dwordx4 v[206:207], off
	s_mov_b32 m0, s40
	v_lshl_add_u64 v[208:209], s[30:31], 0, v[176:177]
	global_load_lds_dwordx4 v[208:209], off
	v_lshl_add_u64 v[210:211], s[30:31], 0, v[180:181]
	s_mov_b32 m0, s41
	s_nop 0
	global_load_lds_dwordx4 v[210:211], off
	s_add_u32 s10, s28, 0x160000
	s_addc_u32 s11, s29, 0
	s_add_i32 s33, s50, s39
	v_lshl_add_u64 v[252:253], s[10:11], 0, v[178:179]
	s_mov_b32 m0, s33
	s_nop 0
	global_load_lds_dwordx4 v[252:253], off
	v_lshl_add_u64 v[252:253], s[10:11], 0, v[182:183]
	s_add_i32 m0, s33, 0x2000
	s_nop 0
	global_load_lds_dwordx4 v[252:253], off
	s_waitcnt vmcnt(8)
	s_waitcnt lgkmcnt(0)
	s_setprio 1
	s_barrier
; #define PG8_STAGE(bufoff, gbase, voff) do { _Pragma("unroll") for (int _i = 0; _i < 2; ++_i) \
;         __builtin_amdgcn_global_load_lds((const unsigned*)((const char*)(gbase) + (voff)[_i]), (PG8_LAS unsigned*)(lds + (bufoff) + ldsw + _i * 8192), 16, 0, 0); } while (0)
; #define PG8_LDA(dst, b, h) do { _Pragma("unroll") for (int m = 0; m < 4; ++m) _Pragma("unroll") for (int k = 0; k < 2; ++k) dst[m][k] = *(const PG8_LAS bf16x8*)(lds + PG8_SA(b, h) + aoff + m * 2048 + k * 1024); } while (0)
; #define PG8_LDB(dst, b, h) do { _Pragma("unroll") for (int n = 0; n < 2; ++n) _Pragma("unroll") for (int k = 0; k < 2; ++k) dst[n][k] = *(const PG8_LAS bf16x8*)(lds + PG8_SB(b, h) + boff + n * 2048 + k * 1024); } while (0)
; #define PG8_MMA(ai, bj, At, Bt) do { __builtin_amdgcn_s_setprio(1); _Pragma("unroll") for (int m = 0; m < 4; ++m) _Pragma("unroll") for (int n = 0; n < 2; ++n) _Pragma("unroll") for (int k = 0; k < 2; ++k) \
;         acc[ai][bj][m][n] = __builtin_amdgcn_mfma_f32_16x16x32_bf16(Bt[n][k], At[m][k], acc[ai][bj][m][n], 0, 0, 0); __builtin_amdgcn_s_setprio(0); } while (0)
; #define PG8_WAIT_V(n) asm volatile("s_waitcnt vmcnt(" #n ")" ::: "memory")
; #define PG8_WAIT_L(n) asm volatile("s_waitcnt lgkmcnt(" #n ")" ::: "memory")
; #define PG8_BAR __builtin_amdgcn_s_barrier()
; #define PG8_SCHED __builtin_amdgcn_sched_barrier(0)
; template <class Epi, class Sched>
; __device__ __forceinline__ void gemm_phase(PG8_LAS unsigned char* lds, const Gemm g, const Sched& S, const Epi& E) {
;     ...
;             PG8_BAR; PG8_WAIT_L(0); PG8_MMA(1, 0, At, B0); PG8_BAR; PG8_SCHED;
;             PG8_STAGE(PG8_SB(0, 1), b2 + hstep, voffB);
;             PG8_WAIT_V(6); PG8_BAR; PG8_MMA(1, 1, At, B1); PG8_BAR;
;             PG8_LDB(B0, 1, 0); PG8_SCHED; PG8_LDA(At, 1, 0); PG8_STAGE(PG8_SA(0, 1), a2 + hstep, voffA);
;             PG8_WAIT_L(8); PG8_BAR; PG8_WAIT_L(0); PG8_MMA(0, 0, At, B0); PG8_BAR; PG8_SCHED;
;             PG8_LDB(B1, 1, 1); PG8_STAGE(PG8_SB(1, 0), b3, voffB);
;             PG8_BAR; PG8_WAIT_L(0); PG8_MMA(0, 1, At, B1); PG8_BAR;
;             PG8_LDA(At, 1, 1); PG8_STAGE(PG8_SA(1, 0), a3, voffA);
;             PG8_BAR; PG8_WAIT_L(0); PG8_MMA(1, 0, At, B0); PG8_BAR; PG8_SCHED;
	v_mfma_f32_16x16x32_bf16 v[60:63], v[108:111], v[144:147], v[60:63]
	v_mfma_f32_16x16x32_bf16 v[56:59], v[124:127], v[144:147], v[56:59]
	v_mfma_f32_16x16x32_bf16 v[44:47], v[108:111], v[152:155], v[44:47]
	v_mfma_f32_16x16x32_bf16 v[40:43], v[124:127], v[152:155], v[40:43]
	v_mfma_f32_16x16x32_bf16 v[28:31], v[108:111], v[160:163], v[28:31]
	v_mfma_f32_16x16x32_bf16 v[24:27], v[124:127], v[160:163], v[24:27]
	v_mfma_f32_16x16x32_bf16 v[12:15], v[108:111], v[168:171], v[12:15]
	v_mfma_f32_16x16x32_bf16 v[8:11], v[124:127], v[168:171], v[8:11]
	s_add_i32 s33, 0, 0x18000
	v_mfma_f32_16x16x32_bf16 v[60:63], v[112:115], v[148:151], v[60:63]
	v_mfma_f32_16x16x32_bf16 v[56:59], v[128:131], v[148:151], v[56:59]
	v_mfma_f32_16x16x32_bf16 v[44:47], v[112:115], v[156:159], v[44:47]
	v_mfma_f32_16x16x32_bf16 v[40:43], v[128:131], v[156:159], v[40:43]
	v_mfma_f32_16x16x32_bf16 v[28:31], v[112:115], v[164:167], v[28:31]
	v_mfma_f32_16x16x32_bf16 v[24:27], v[128:131], v[164:167], v[24:27]
	v_mfma_f32_16x16x32_bf16 v[12:15], v[112:115], v[172:175], v[12:15]
	v_mfma_f32_16x16x32_bf16 v[8:11], v[128:131], v[172:175], v[8:11]
	v_mfma_f32_16x16x32_bf16 v[52:55], v[188:191], v[144:147], v[52:55]
	v_mfma_f32_16x16x32_bf16 v[48:51], v[196:199], v[144:147], v[48:51]
	v_mfma_f32_16x16x32_bf16 v[36:39], v[188:191], v[152:155], v[36:39]
	v_mfma_f32_16x16x32_bf16 v[32:35], v[196:199], v[152:155], v[32:35]
	v_mfma_f32_16x16x32_bf16 v[20:23], v[188:191], v[160:163], v[20:23]
	v_mfma_f32_16x16x32_bf16 v[16:19], v[196:199], v[160:163], v[16:19]
	v_mfma_f32_16x16x32_bf16 v[4:7], v[188:191], v[168:171], v[4:7]
	v_mfma_f32_16x16x32_bf16 v[0:3], v[196:199], v[168:171], v[0:3]
	v_mfma_f32_16x16x32_bf16 v[52:55], v[192:195], v[148:151], v[52:55]
	v_mfma_f32_16x16x32_bf16 v[48:51], v[200:203], v[148:151], v[48:51]
	v_mfma_f32_16x16x32_bf16 v[36:39], v[192:195], v[156:159], v[36:39]
	v_mfma_f32_16x16x32_bf16 v[32:35], v[200:203], v[156:159], v[32:35]
	v_mfma_f32_16x16x32_bf16 v[20:23], v[192:195], v[164:167], v[20:23]
	v_mfma_f32_16x16x32_bf16 v[16:19], v[200:203], v[164:167], v[16:19]
	v_mfma_f32_16x16x32_bf16 v[4:7], v[192:195], v[172:175], v[4:7]
	v_mfma_f32_16x16x32_bf16 v[0:3], v[200:203], v[172:175], v[0:3]
	s_barrier
	s_setprio 0
	ds_read_b128 v[108:111], v247 offset:32768
	ds_read_b128 v[112:115], v247 offset:33792
	ds_read_b128 v[124:127], v247 offset:34816
	ds_read_b128 v[128:131], v247 offset:35840
	ds_read_b128 v[144:147], v248 offset:32768
	ds_read_b128 v[148:151], v248 offset:33792
	ds_read_b128 v[152:155], v248 offset:34816
	ds_read_b128 v[156:159], v248 offset:35840
	ds_read_b128 v[160:163], v248 offset:36864
	ds_read_b128 v[164:167], v248 offset:37888
	ds_read_b128 v[168:171], v248 offset:38912
	ds_read_b128 v[172:175], v248 offset:39936
	ds_read_b128 v[188:191], v249 offset:32768
	ds_read_b128 v[192:195], v249 offset:33792
	ds_read_b128 v[196:199], v249 offset:34816
	ds_read_b128 v[200:203], v249 offset:35840
	s_add_u32 s10, s30, 0x160000
	s_addc_u32 s11, s31, 0
	s_mov_b32 m0, s42
	v_lshl_add_u64 v[252:253], s[10:11], 0, v[176:177]
	global_load_lds_dwordx4 v[252:253], off
	v_lshl_add_u64 v[252:253], s[10:11], 0, v[180:181]
	s_mov_b32 m0, s43
	s_nop 0
	global_load_lds_dwordx4 v[252:253], off
	s_waitcnt vmcnt(8)
	s_waitcnt lgkmcnt(0)
	s_setprio 1
	s_barrier
	v_mfma_f32_16x16x32_bf16 v[140:143], v[108:111], v[144:147], v[140:143]
	v_mfma_f32_16x16x32_bf16 v[136:139], v[124:127], v[144:147], v[136:139]
	v_mfma_f32_16x16x32_bf16 v[116:119], v[108:111], v[152:155], v[116:119]
	v_mfma_f32_16x16x32_bf16 v[104:107], v[124:127], v[152:155], v[104:107]
	v_mfma_f32_16x16x32_bf16 v[92:95], v[108:111], v[160:163], v[92:95]
	v_mfma_f32_16x16x32_bf16 v[88:91], v[124:127], v[160:163], v[88:91]
	v_mfma_f32_16x16x32_bf16 v[76:79], v[108:111], v[168:171], v[76:79]
	v_mfma_f32_16x16x32_bf16 v[72:75], v[124:127], v[168:171], v[72:75]
	v_mfma_f32_16x16x32_bf16 v[140:143], v[112:115], v[148:151], v[140:143]
	v_mfma_f32_16x16x32_bf16 v[136:139], v[128:131], v[148:151], v[136:139]
	v_mfma_f32_16x16x32_bf16 v[116:119], v[112:115], v[156:159], v[116:119]
	v_mfma_f32_16x16x32_bf16 v[104:107], v[128:131], v[156:159], v[104:107]
	v_mfma_f32_16x16x32_bf16 v[92:95], v[112:115], v[164:167], v[92:95]
	v_mfma_f32_16x16x32_bf16 v[88:91], v[128:131], v[164:167], v[88:91]
	v_mfma_f32_16x16x32_bf16 v[76:79], v[112:115], v[172:175], v[76:79]
	v_mfma_f32_16x16x32_bf16 v[72:75], v[128:131], v[172:175], v[72:75]
	v_mfma_f32_16x16x32_bf16 v[132:135], v[188:191], v[144:147], v[132:135]
	v_mfma_f32_16x16x32_bf16 v[120:123], v[196:199], v[144:147], v[120:123]
	v_mfma_f32_16x16x32_bf16 v[100:103], v[188:191], v[152:155], v[100:103]
	v_mfma_f32_16x16x32_bf16 v[96:99], v[196:199], v[152:155], v[96:99]
	v_mfma_f32_16x16x32_bf16 v[84:87], v[188:191], v[160:163], v[84:87]
	v_mfma_f32_16x16x32_bf16 v[80:83], v[196:199], v[160:163], v[80:83]
	v_mfma_f32_16x16x32_bf16 v[68:71], v[188:191], v[168:171], v[68:71]
	v_mfma_f32_16x16x32_bf16 v[64:67], v[196:199], v[168:171], v[64:67]
	v_mfma_f32_16x16x32_bf16 v[132:135], v[192:195], v[148:151], v[132:135]
	v_mfma_f32_16x16x32_bf16 v[120:123], v[200:203], v[148:151], v[120:123]
	v_mfma_f32_16x16x32_bf16 v[100:103], v[192:195], v[156:159], v[100:103]
	v_mfma_f32_16x16x32_bf16 v[96:99], v[200:203], v[156:159], v[96:99]
	v_mfma_f32_16x16x32_bf16 v[84:87], v[192:195], v[164:167], v[84:87]
	v_mfma_f32_16x16x32_bf16 v[80:83], v[200:203], v[164:167], v[80:83]
	v_mfma_f32_16x16x32_bf16 v[68:71], v[192:195], v[172:175], v[68:71]
	v_mfma_f32_16x16x32_bf16 v[64:67], v[200:203], v[172:175], v[64:67]
	s_barrier
; #define PG8_STAGE(bufoff, gbase, voff) do { _Pragma("unroll") for (int _i = 0; _i < 2; ++_i) \
;         __builtin_amdgcn_global_load_lds((const unsigned*)((const char*)(gbase) + (voff)[_i]), (PG8_LAS unsigned*)(lds + (bufoff) + ldsw + _i * 8192), 16, 0, 0); } while (0)
; #define PG8_LDA(dst, b, h) do { _Pragma("unroll") for (int m = 0; m < 4; ++m) _Pragma("unroll") for (int k = 0; k < 2; ++k) dst[m][k] = *(const PG8_LAS bf16x8*)(lds + PG8_SA(b, h) + aoff + m * 2048 + k * 1024); } while (0)
; #define PG8_WAIT_V(n) asm volatile("s_waitcnt vmcnt(" #n ")" ::: "memory")
; #define PG8_WAIT_L(n) asm volatile("s_waitcnt lgkmcnt(" #n ")" ::: "memory")
; #define PG8_BAR __builtin_amdgcn_s_barrier()
; #define PG8_SCHED __builtin_amdgcn_sched_barrier(0)
; template <class Epi, class Sched>
; __device__ __forceinline__ void gemm_phase(PG8_LAS unsigned char* lds, const Gemm g, const Sched& S, const Epi& E) {
;     ...
;             PG8_LDA(At, 1, 1); PG8_STAGE(PG8_SA(1, 0), a3, voffA);
;             PG8_BAR; PG8_WAIT_L(0); PG8_MMA(1, 0, At, B0); PG8_BAR; PG8_SCHED;
;             PG8_STAGE(PG8_SB(1, 1), b3 + hstep, voffB);
;             PG8_WAIT_V(6); PG8_BAR; PG8_MMA(1, 1, At, B1); PG8_BAR;
;         }
;         E(acc, cur, wr, wc, fr, fq); S.done(cur);
;         if (!has_next) break;
;     __device__ __forceinline__ void operator()(const AccT& acc, const pg8::Unit& u, int wr, int wc, int fr, int fq) const {
;         const int row0 = u.pm * 256 + wr * 64 + fr, col0 = u.pn * 256 + wc * 32 + 8 * fq;
;         const float* ga = mod + (u.pm >= 64 ? 12288 : 0) + 5 * 2048;
;         f32x4 gv[2][2], lg[2][2], lbv[2][2];
; #pragma unroll
;         for (int bj = 0; bj < 2; ++bj)
; #pragma unroll
;             for (int n = 0; n < 2; ++n) { const int c = col0 + bj * 128 + n * 4; gv[bj][n] = *(const f32x4*)(ga + c); lg[bj][n] = ALPHA * *(const f32x4*)(g1 + c); lbv[bj][n] = ALPHA * *(const f32x4*)(b1 + c); }
; #pragma unroll
;         for (int ai = 0; ai < 2; ++ai) {
;             u32x4 uraw[4][2]; f32x2 stv[4];
; #pragma unroll
;             for (int m = 0; m < 4; ++m) { const int row = row0 + ai * 128 + m * 16; const size_t off = (size_t)row * D + col0; stv[m] = *(const f32x2*)(stats + 2 * row);
; #pragma unroll
;                 for (int bj = 0; bj < 2; ++bj) uraw[m][bj] = *(const u32x4*)(U1 + off + bj * 128); }
	s_setprio 0
	ds_read_b128 v[144:147], v248 offset:49152
	ds_read_b128 v[148:151], v248 offset:50176
	ds_read_b128 v[152:155], v248 offset:51200
	ds_read_b128 v[156:159], v248 offset:52224
	ds_read_b128 v[160:163], v248 offset:53248
	ds_read_b128 v[164:167], v248 offset:54272
	ds_read_b128 v[168:171], v248 offset:55296
	ds_read_b128 v[172:175], v248 offset:56320
	s_add_i32 s30, 0, 0x1c000
	s_add_i32 s10, s33, s39
	v_lshl_add_u64 v[204:205], v[204:205], 0, s[18:19]
	s_mov_b32 m0, s10
	s_nop 0
	global_load_lds_dwordx4 v[204:205], off
	v_lshl_add_u64 v[204:205], v[206:207], 0, s[18:19]
	s_add_i32 m0, s10, 0x2000
	s_nop 0
	global_load_lds_dwordx4 v[204:205], off
	s_mov_b32 m0, s45
	v_lshl_add_u64 v[204:205], v[208:209], 0, s[18:19]
	global_load_lds_dwordx4 v[204:205], off
	v_lshl_add_u64 v[204:205], v[210:211], 0, s[18:19]
	s_mov_b32 m0, s46
	s_nop 0
	global_load_lds_dwordx4 v[204:205], off
	s_add_u32 s10, s28, 0x160080
	s_addc_u32 s11, s29, 0
	s_add_i32 s28, s30, s39
	v_lshl_add_u64 v[252:253], s[10:11], 0, v[178:179]
	s_mov_b32 m0, s28
	s_nop 0
	global_load_lds_dwordx4 v[252:253], off
	v_lshl_add_u64 v[252:253], s[10:11], 0, v[182:183]
	s_add_i32 m0, s28, 0x2000
	s_nop 0
	global_load_lds_dwordx4 v[252:253], off
	s_waitcnt vmcnt(8)
	s_waitcnt lgkmcnt(0)
	s_setprio 1
	s_barrier
	v_mfma_f32_16x16x32_bf16 v[60:63], v[108:111], v[144:147], v[60:63]
	v_mfma_f32_16x16x32_bf16 v[56:59], v[124:127], v[144:147], v[56:59]
	v_mfma_f32_16x16x32_bf16 v[44:47], v[108:111], v[152:155], v[44:47]
	v_mfma_f32_16x16x32_bf16 v[40:43], v[124:127], v[152:155], v[40:43]
	v_mfma_f32_16x16x32_bf16 v[28:31], v[108:111], v[160:163], v[28:31]
	v_mfma_f32_16x16x32_bf16 v[24:27], v[124:127], v[160:163], v[24:27]
	v_mfma_f32_16x16x32_bf16 v[12:15], v[108:111], v[168:171], v[12:15]
	v_mfma_f32_16x16x32_bf16 v[8:11], v[124:127], v[168:171], v[8:11]
	s_add_i32 s69, s69, 2
	s_add_u32 s26, s26, 0x100
	s_addc_u32 s27, s27, 0
	s_add_u32 s67, s67, 0x100
	s_addc_u32 s68, s68, 0
	s_cmpk_gt_u32 s69, 0x55
	v_mfma_f32_16x16x32_bf16 v[60:63], v[112:115], v[148:151], v[60:63]
	v_mfma_f32_16x16x32_bf16 v[56:59], v[128:131], v[148:151], v[56:59]
	v_mfma_f32_16x16x32_bf16 v[44:47], v[112:115], v[156:159], v[44:47]
	v_mfma_f32_16x16x32_bf16 v[40:43], v[128:131], v[156:159], v[40:43]
	v_mfma_f32_16x16x32_bf16 v[28:31], v[112:115], v[164:167], v[28:31]
	v_mfma_f32_16x16x32_bf16 v[24:27], v[128:131], v[164:167], v[24:27]
	v_mfma_f32_16x16x32_bf16 v[12:15], v[112:115], v[172:175], v[12:15]
	v_mfma_f32_16x16x32_bf16 v[8:11], v[128:131], v[172:175], v[8:11]
	v_mfma_f32_16x16x32_bf16 v[52:55], v[188:191], v[144:147], v[52:55]
	v_mfma_f32_16x16x32_bf16 v[48:51], v[196:199], v[144:147], v[48:51]
	v_mfma_f32_16x16x32_bf16 v[36:39], v[188:191], v[152:155], v[36:39]
	v_mfma_f32_16x16x32_bf16 v[32:35], v[196:199], v[152:155], v[32:35]
	v_mfma_f32_16x16x32_bf16 v[20:23], v[188:191], v[160:163], v[20:23]
	v_mfma_f32_16x16x32_bf16 v[16:19], v[196:199], v[160:163], v[16:19]
	v_mfma_f32_16x16x32_bf16 v[4:7], v[188:191], v[168:171], v[4:7]
	v_mfma_f32_16x16x32_bf16 v[0:3], v[196:199], v[168:171], v[0:3]
	v_mfma_f32_16x16x32_bf16 v[52:55], v[192:195], v[148:151], v[52:55]
	v_mfma_f32_16x16x32_bf16 v[48:51], v[200:203], v[148:151], v[48:51]
	v_mfma_f32_16x16x32_bf16 v[36:39], v[192:195], v[156:159], v[36:39]
	v_mfma_f32_16x16x32_bf16 v[32:35], v[200:203], v[156:159], v[32:35]
	v_mfma_f32_16x16x32_bf16 v[20:23], v[192:195], v[164:167], v[20:23]
	v_mfma_f32_16x16x32_bf16 v[16:19], v[200:203], v[164:167], v[16:19]
	v_mfma_f32_16x16x32_bf16 v[4:7], v[192:195], v[172:175], v[4:7]
	v_mfma_f32_16x16x32_bf16 v[0:3], v[200:203], v[172:175], v[0:3]
	s_barrier
	s_cbranch_scc0 .LBB0_882
	s_setprio 0
	s_cmp_lg_u32 s98, 0
	s_cbranch_scc1 .Lxa_882
	s_barrier
.Lxa_882:
	s_cmp_gt_i32 s65, 63
	s_cselect_b32 s10, 0xc000, 0
	s_add_u32 s10, s58, s10
	v_lshl_or_b32 v156, s66, 8, v246
	s_addc_u32 s11, s59, 0
	s_add_u32 s10, s10, 0x6a0a000
	v_ashrrev_i32_e32 v157, 31, v156
	s_addc_u32 s11, s11, 0
	v_lshlrev_b64 v[144:145], 2, v[156:157]
	v_lshl_add_u64 v[108:109], s[10:11], 0, v[144:145]
	v_lshl_add_u64 v[148:149], s[22:23], 0, v[144:145]
	global_load_dwordx4 v[112:115], v[108:109], off offset:16
	global_load_dwordx4 v[128:131], v[108:109], off
	s_nop 0
	global_load_dwordx4 v[108:111], v[148:149], off offset:16
	global_load_dwordx4 v[124:127], v[148:149], off
	v_lshl_add_u64 v[152:153], s[24:25], 0, v[144:145]
	v_lshl_add_u32 v224, s65, 8, v244
	v_lshlrev_b64 v[220:221], 1, v[156:157]
	v_ashrrev_i32_e32 v225, 31, v224
	v_lshl_add_u64 v[222:223], s[6:7], 0, v[220:221]
	v_lshlrev_b64 v[240:241], 12, v[224:225]
	s_and_b64 vcc, exec, s[2:3]
	s_mov_b32 s66, s51
	s_mov_b32 s65, s64
	s_mov_b64 s[28:29], s[4:5]
	s_mov_b64 s[26:27], s[0:1]
	s_waitcnt vmcnt(0)
	v_pk_mul_f32 v[210:211], v[108:109], s[20:21] op_sel_hi:[1,0]
	v_pk_mul_f32 v[204:205], v[126:127], s[20:21] op_sel_hi:[1,0]
	v_pk_mul_f32 v[206:207], v[124:125], s[20:21] op_sel_hi:[1,0]
	global_load_dwordx4 v[124:127], v[152:153], off offset:16
	global_load_dwordx4 v[144:147], v[152:153], off
	v_or_b32_e32 v108, 0x80, v156
	v_ashrrev_i32_e32 v109, 31, v108
	v_pk_mul_f32 v[208:209], v[110:111], s[20:21] op_sel_hi:[1,0]
	v_or_b32_e32 v156, 48, v224
	v_ashrrev_i32_e32 v157, 31, v156
	v_lshlrev_b32_e32 v158, 1, v156
	v_ashrrev_i32_e32 v159, 31, v158
	v_lshlrev_b64 v[232:233], 12, v[156:157]
	v_lshl_add_u64 v[158:159], v[158:159], 2, s[8:9]
	v_lshl_add_u64 v[156:157], v[222:223], 0, v[232:233]
	s_waitcnt vmcnt(0)
;     __device__ __forceinline__ void operator()(const AccT& acc, const pg8::Unit& u, int wr, int wc, int fr, int fq) const {
;     ...
;         for (int ai = 0; ai < 2; ++ai) {
;             u32x4 uraw[4][2]; f32x2 stv[4];
; #pragma unroll
;             for (int m = 0; m < 4; ++m) { const int row = row0 + ai * 128 + m * 16; const size_t off = (size_t)row * D + col0; stv[m] = *(const f32x2*)(stats + 2 * row);
; #pragma unroll
;                 for (int bj = 0; bj < 2; ++bj) uraw[m][bj] = *(const u32x4*)(U1 + off + bj * 128); }
; #pragma unroll
;             for (int m = 0; m < 4; ++m) { const int row = row0 + ai * 128 + m * 16; const size_t off = (size_t)row * D + col0; const f32x2 st = stv[m];
; #pragma unroll
;                 for (int bj = 0; bj < 2; ++bj) { float uf[8]; unpack_h8(uraw[m][bj], uf);
;                     const f32x4 ua = {uf[0], uf[1], uf[2], uf[3]}, ub = {uf[4], uf[5], uf[6], uf[7]};
;                     const f32x4 a = ((ua - st.x) * st.y) * lg[bj][0] + lbv[bj][0] + gv[bj][0] * acc[ai][bj][m][0], b = ((ub - st.x) * st.y) * lg[bj][1] + lbv[bj][1] + gv[bj][1] * acc[ai][bj][m][1];
;                     u32x4 w; w.x = pk_h2(a[0], a[1]); w.y = pk_h2(a[2], a[3]); w.z = pk_h2(b[0], b[1]); w.w = pk_h2(b[2], b[3]);
;                     *(u32x4*)(U2 + off + bj * 128) = w; } }
	v_pk_mul_f32 v[214:215], v[124:125], s[20:21] op_sel_hi:[1,0]
	v_lshl_add_u64 v[124:125], v[108:109], 2, s[10:11]
	v_pk_mul_f32 v[216:217], v[146:147], s[20:21] op_sel_hi:[1,0]
	v_pk_mul_f32 v[218:219], v[144:145], s[20:21] op_sel_hi:[1,0]
	v_pk_mul_f32 v[212:213], v[126:127], s[20:21] op_sel_hi:[1,0]
	global_load_dwordx4 v[108:111], v[124:125], off offset:16
	s_nop 0
	global_load_dwordx4 v[124:127], v[124:125], off
	s_nop 0
	global_load_dwordx4 v[144:147], v[148:149], off offset:528
	s_nop 0
	global_load_dwordx4 v[148:151], v[148:149], off offset:512
	s_waitcnt vmcnt(0)
	v_pk_mul_f32 v[190:191], v[144:145], s[20:21] op_sel_hi:[1,0]
	v_pk_mul_f32 v[196:197], v[150:151], s[20:21] op_sel_hi:[1,0]
	v_pk_mul_f32 v[198:199], v[148:149], s[20:21] op_sel_hi:[1,0]
	global_load_dwordx4 v[148:151], v[152:153], off offset:528
	s_nop 0
	global_load_dwordx4 v[152:155], v[152:153], off offset:512
	v_lshlrev_b32_e32 v144, 1, v224
	v_ashrrev_i32_e32 v145, 31, v144
	v_lshl_add_u64 v[144:145], v[144:145], 2, s[8:9]
	global_load_dwordx2 v[234:235], v[144:145], off
	v_lshl_add_u64 v[144:145], v[222:223], 0, v[240:241]
	global_load_dwordx4 v[172:175], v[144:145], off
	global_load_dwordx4 v[160:163], v[144:145], off offset:256
	v_or_b32_e32 v144, 16, v224
	v_pk_mul_f32 v[188:189], v[146:147], s[20:21] op_sel_hi:[1,0]
	v_ashrrev_i32_e32 v145, 31, v144
	v_lshlrev_b32_e32 v146, 1, v144
	v_ashrrev_i32_e32 v147, 31, v146
	v_lshlrev_b64 v[238:239], 12, v[144:145]
	v_lshl_add_u64 v[146:147], v[146:147], 2, s[8:9]
	v_lshl_add_u64 v[144:145], v[222:223], 0, v[238:239]
	global_load_dwordx2 v[236:237], v[146:147], off
	s_waitcnt vmcnt(0)
	v_pk_mul_f32 v[192:193], v[150:151], s[20:21] op_sel_hi:[1,0]
	v_pk_mul_f32 v[194:195], v[148:149], s[20:21] op_sel_hi:[1,0]
	global_load_dwordx4 v[164:167], v[144:145], off
	global_load_dwordx4 v[148:151], v[144:145], off offset:256
	v_or_b32_e32 v144, 32, v224
	v_ashrrev_i32_e32 v145, 31, v144
	v_lshlrev_b32_e32 v146, 1, v144
	v_ashrrev_i32_e32 v147, 31, v146
	v_lshlrev_b64 v[230:231], 12, v[144:145]
	v_lshl_add_u64 v[146:147], v[146:147], 2, s[8:9]
	v_lshl_add_u64 v[144:145], v[222:223], 0, v[230:231]
	v_pk_mul_f32 v[200:201], v[154:155], s[20:21] op_sel_hi:[1,0]
	v_pk_mul_f32 v[202:203], v[152:153], s[20:21] op_sel_hi:[1,0]
	global_load_dwordx2 v[228:229], v[146:147], off
	global_load_dwordx4 v[152:155], v[144:145], off
	s_nop 0
	global_load_dwordx4 v[144:147], v[144:145], off offset:256
	v_cvt_f32_f16_sdwa v225, v172 dst_sel:DWORD dst_unused:UNUSED_PAD src0_sel:WORD_1
	global_load_dwordx2 v[226:227], v[158:159], off
	global_load_dwordx4 v[168:171], v[156:157], off
	s_nop 0
	global_load_dwordx4 v[156:159], v[156:157], off offset:256
	v_cvt_f32_f16_e32 v172, v172
	v_cvt_f32_f16_sdwa v250, v173 dst_sel:DWORD dst_unused:UNUSED_PAD src0_sel:WORD_1
	v_cvt_f32_f16_e32 v251, v173
	v_cvt_f32_f16_sdwa v252, v174 dst_sel:DWORD dst_unused:UNUSED_PAD src0_sel:WORD_1
	v_cvt_f32_f16_e32 v253, v174
	v_cvt_f32_f16_sdwa v254, v175 dst_sel:DWORD dst_unused:UNUSED_PAD src0_sel:WORD_1
	v_cvt_f32_f16_e32 v243, v175
	v_sub_f32_e32 v172, v172, v234
	v_sub_f32_e32 v173, v225, v234
	v_sub_f32_e32 v174, v251, v234
	v_sub_f32_e32 v175, v250, v234
	v_pk_mul_f32 v[174:175], v[234:235], v[174:175] op_sel:[1,0]
	v_pk_mul_f32 v[172:173], v[234:235], v[172:173] op_sel:[1,0]
	v_pk_fma_f32 v[174:175], v[204:205], v[174:175], v[216:217]
	v_pk_fma_f32 v[172:173], v[206:207], v[172:173], v[218:219]
	v_pk_fma_f32 v[142:143], v[142:143], v[130:131], v[174:175]
	v_pk_fma_f32 v[140:141], v[140:141], v[128:129], v[172:173]
	v_sub_f32_e32 v172, v253, v234
	v_sub_f32_e32 v173, v252, v234
	v_sub_f32_e32 v174, v243, v234
	v_sub_f32_e32 v175, v254, v234
	v_pk_mul_f32 v[174:175], v[234:235], v[174:175] op_sel:[1,0]
	v_pk_mul_f32 v[172:173], v[234:235], v[172:173] op_sel:[1,0]
	v_pk_fma_f32 v[174:175], v[208:209], v[174:175], v[212:213]
	v_pk_fma_f32 v[172:173], v[210:211], v[172:173], v[214:215]
	v_pk_fma_f32 v[174:175], v[138:139], v[114:115], v[174:175]
	v_pk_fma_f32 v[138:139], v[136:137], v[112:113], v[172:173]
	v_cvt_pk_f16_f32 v136, v140, v141
	v_lshl_add_u64 v[140:141], s[16:17], 0, v[240:241]
	v_cvt_pk_f16_f32 v137, v142, v143
	v_cvt_pk_f16_f32 v138, v138, v139
	v_cvt_pk_f16_f32 v139, v174, v175
	v_lshl_add_u64 v[140:141], v[140:141], 0, v[220:221]
	global_store_dwordx4 v[140:141], v[136:139], off
	v_cvt_f32_f16_sdwa v142, v162 dst_sel:DWORD dst_unused:UNUSED_PAD src0_sel:WORD_1
	v_cvt_f32_f16_e32 v143, v162
	v_cvt_f32_f16_sdwa v137, v160 dst_sel:DWORD dst_unused:UNUSED_PAD src0_sel:WORD_1
	v_cvt_f32_f16_e32 v136, v160
	v_cvt_f32_f16_sdwa v139, v161 dst_sel:DWORD dst_unused:UNUSED_PAD src0_sel:WORD_1
	v_cvt_f32_f16_e32 v138, v161
	v_cvt_f32_f16_sdwa v160, v163 dst_sel:DWORD dst_unused:UNUSED_PAD src0_sel:WORD_1
	v_cvt_f32_f16_e32 v161, v163
	v_sub_f32_e32 v136, v136, v234
	v_sub_f32_e32 v137, v137, v234
	v_sub_f32_e32 v138, v138, v234
	v_sub_f32_e32 v139, v139, v234
	v_pk_mul_f32 v[138:139], v[234:235], v[138:139] op_sel:[1,0]
	v_pk_mul_f32 v[136:137], v[234:235], v[136:137] op_sel:[1,0]
	v_pk_fma_f32 v[138:139], v[196:197], v[138:139], v[200:201]
	v_pk_fma_f32 v[136:137], v[198:199], v[136:137], v[202:203]
	v_pk_fma_f32 v[134:135], v[134:135], v[126:127], v[138:139]
	v_pk_fma_f32 v[132:133], v[132:133], v[124:125], v[136:137]
	v_sub_f32_e32 v136, v143, v234
	v_sub_f32_e32 v137, v142, v234
	v_sub_f32_e32 v138, v161, v234
	v_sub_f32_e32 v139, v160, v234
	v_pk_mul_f32 v[138:139], v[234:235], v[138:139] op_sel:[1,0]
	v_pk_mul_f32 v[136:137], v[234:235], v[136:137] op_sel:[1,0]
	v_pk_fma_f32 v[138:139], v[188:189], v[138:139], v[192:193]
	v_pk_fma_f32 v[136:137], v[190:191], v[136:137], v[194:195]
	v_pk_fma_f32 v[138:139], v[122:123], v[110:111], v[138:139]
	v_pk_fma_f32 v[122:123], v[120:121], v[108:109], v[136:137]
	v_cvt_pk_f16_f32 v120, v132, v133
	v_cvt_pk_f16_f32 v121, v134, v135
	v_cvt_pk_f16_f32 v122, v122, v123
	v_cvt_pk_f16_f32 v123, v138, v139
	global_store_dwordx4 v[140:141], v[120:123], off offset:256
	s_waitcnt vmcnt(0)
;     __device__ __forceinline__ void operator()(const AccT& acc, const pg8::Unit& u, int wr, int wc, int fr, int fq) const {
;     ...
;             for (int m = 0; m < 4; ++m) { const int row = row0 + ai * 128 + m * 16; const size_t off = (size_t)row * D + col0; const f32x2 st = stv[m];
; #pragma unroll
;                 for (int bj = 0; bj < 2; ++bj) { float uf[8]; unpack_h8(uraw[m][bj], uf);
;                     const f32x4 ua = {uf[0], uf[1], uf[2], uf[3]}, ub = {uf[4], uf[5], uf[6], uf[7]};
;                     const f32x4 a = ((ua - st.x) * st.y) * lg[bj][0] + lbv[bj][0] + gv[bj][0] * acc[ai][bj][m][0], b = ((ub - st.x) * st.y) * lg[bj][1] + lbv[bj][1] + gv[bj][1] * acc[ai][bj][m][1];
;                     u32x4 w; w.x = pk_h2(a[0], a[1]); w.y = pk_h2(a[2], a[3]); w.z = pk_h2(b[0], b[1]); w.w = pk_h2(b[2], b[3]);
;                     *(u32x4*)(U2 + off + bj * 128) = w; } }
	v_cvt_f32_f16_sdwa v132, v166 dst_sel:DWORD dst_unused:UNUSED_PAD src0_sel:WORD_1
	v_cvt_f32_f16_e32 v133, v166
	v_cvt_f32_f16_sdwa v121, v164 dst_sel:DWORD dst_unused:UNUSED_PAD src0_sel:WORD_1
	v_cvt_f32_f16_e32 v120, v164
	v_cvt_f32_f16_sdwa v123, v165 dst_sel:DWORD dst_unused:UNUSED_PAD src0_sel:WORD_1
	v_cvt_f32_f16_e32 v122, v165
	v_cvt_f32_f16_sdwa v134, v167 dst_sel:DWORD dst_unused:UNUSED_PAD src0_sel:WORD_1
	v_cvt_f32_f16_e32 v135, v167
	v_sub_f32_e32 v120, v120, v236
	v_sub_f32_e32 v121, v121, v236
	v_sub_f32_e32 v122, v122, v236
	v_sub_f32_e32 v123, v123, v236
	v_pk_mul_f32 v[122:123], v[236:237], v[122:123] op_sel:[1,0]
	v_pk_mul_f32 v[120:121], v[236:237], v[120:121] op_sel:[1,0]
	v_pk_fma_f32 v[122:123], v[204:205], v[122:123], v[216:217]
	v_pk_fma_f32 v[120:121], v[206:207], v[120:121], v[218:219]
	v_pk_fma_f32 v[118:119], v[118:119], v[130:131], v[122:123]
	v_pk_fma_f32 v[116:117], v[116:117], v[128:129], v[120:121]
	v_sub_f32_e32 v120, v133, v236
	v_sub_f32_e32 v121, v132, v236
	v_sub_f32_e32 v122, v135, v236
	v_sub_f32_e32 v123, v134, v236
	v_pk_mul_f32 v[122:123], v[236:237], v[122:123] op_sel:[1,0]
	v_pk_mul_f32 v[120:121], v[236:237], v[120:121] op_sel:[1,0]
	v_pk_fma_f32 v[122:123], v[208:209], v[122:123], v[212:213]
	v_pk_fma_f32 v[120:121], v[210:211], v[120:121], v[214:215]
	v_pk_fma_f32 v[122:123], v[106:107], v[114:115], v[122:123]
	v_pk_fma_f32 v[106:107], v[104:105], v[112:113], v[120:121]
	v_cvt_pk_f16_f32 v104, v116, v117
	v_lshl_add_u64 v[116:117], s[16:17], 0, v[238:239]
	v_cvt_pk_f16_f32 v105, v118, v119
	v_cvt_pk_f16_f32 v106, v106, v107
	v_cvt_pk_f16_f32 v107, v122, v123
	v_lshl_add_u64 v[116:117], v[116:117], 0, v[220:221]
	global_store_dwordx4 v[116:117], v[104:107], off
	v_cvt_f32_f16_sdwa v118, v150 dst_sel:DWORD dst_unused:UNUSED_PAD src0_sel:WORD_1
	v_cvt_f32_f16_e32 v119, v150
	v_cvt_f32_f16_sdwa v105, v148 dst_sel:DWORD dst_unused:UNUSED_PAD src0_sel:WORD_1
	v_cvt_f32_f16_e32 v104, v148
	v_cvt_f32_f16_sdwa v107, v149 dst_sel:DWORD dst_unused:UNUSED_PAD src0_sel:WORD_1
	v_cvt_f32_f16_e32 v106, v149
	v_cvt_f32_f16_sdwa v120, v151 dst_sel:DWORD dst_unused:UNUSED_PAD src0_sel:WORD_1
	v_cvt_f32_f16_e32 v121, v151
	v_sub_f32_e32 v104, v104, v236
	v_sub_f32_e32 v105, v105, v236
	v_sub_f32_e32 v106, v106, v236
	v_sub_f32_e32 v107, v107, v236
	v_pk_mul_f32 v[106:107], v[236:237], v[106:107] op_sel:[1,0]
	v_pk_mul_f32 v[104:105], v[236:237], v[104:105] op_sel:[1,0]
	v_pk_fma_f32 v[106:107], v[196:197], v[106:107], v[200:201]
	v_pk_fma_f32 v[104:105], v[198:199], v[104:105], v[202:203]
	v_pk_fma_f32 v[102:103], v[102:103], v[126:127], v[106:107]
	v_pk_fma_f32 v[100:101], v[100:101], v[124:125], v[104:105]
	v_sub_f32_e32 v104, v119, v236
	v_sub_f32_e32 v105, v118, v236
	v_sub_f32_e32 v106, v121, v236
	v_sub_f32_e32 v107, v120, v236
	v_pk_mul_f32 v[106:107], v[236:237], v[106:107] op_sel:[1,0]
	v_pk_mul_f32 v[104:105], v[236:237], v[104:105] op_sel:[1,0]
	v_pk_fma_f32 v[106:107], v[188:189], v[106:107], v[192:193]
	v_pk_fma_f32 v[104:105], v[190:191], v[104:105], v[194:195]
	v_pk_fma_f32 v[106:107], v[98:99], v[110:111], v[106:107]
	v_pk_fma_f32 v[98:99], v[96:97], v[108:109], v[104:105]
	v_cvt_pk_f16_f32 v96, v100, v101
	v_cvt_pk_f16_f32 v97, v102, v103
	v_cvt_pk_f16_f32 v98, v98, v99
	v_cvt_pk_f16_f32 v99, v106, v107
	global_store_dwordx4 v[116:117], v[96:99], off offset:256
	v_cvt_f32_f16_sdwa v100, v154 dst_sel:DWORD dst_unused:UNUSED_PAD src0_sel:WORD_1
	v_cvt_f32_f16_e32 v101, v154
	v_cvt_f32_f16_sdwa v97, v152 dst_sel:DWORD dst_unused:UNUSED_PAD src0_sel:WORD_1
	v_cvt_f32_f16_e32 v96, v152
	v_cvt_f32_f16_sdwa v99, v153 dst_sel:DWORD dst_unused:UNUSED_PAD src0_sel:WORD_1
	v_cvt_f32_f16_e32 v98, v153
	v_cvt_f32_f16_sdwa v102, v155 dst_sel:DWORD dst_unused:UNUSED_PAD src0_sel:WORD_1
	v_cvt_f32_f16_e32 v103, v155
	v_sub_f32_e32 v96, v96, v228
	v_sub_f32_e32 v97, v97, v228
	v_sub_f32_e32 v98, v98, v228
	v_sub_f32_e32 v99, v99, v228
	v_pk_mul_f32 v[98:99], v[228:229], v[98:99] op_sel:[1,0]
	v_pk_mul_f32 v[96:97], v[228:229], v[96:97] op_sel:[1,0]
	v_pk_fma_f32 v[98:99], v[204:205], v[98:99], v[216:217]
	v_pk_fma_f32 v[96:97], v[206:207], v[96:97], v[218:219]
	v_pk_fma_f32 v[94:95], v[94:95], v[130:131], v[98:99]
	v_pk_fma_f32 v[92:93], v[92:93], v[128:129], v[96:97]
	v_sub_f32_e32 v96, v101, v228
	v_sub_f32_e32 v97, v100, v228
	v_sub_f32_e32 v98, v103, v228
	v_sub_f32_e32 v99, v102, v228
	v_pk_mul_f32 v[98:99], v[228:229], v[98:99] op_sel:[1,0]
	v_pk_mul_f32 v[96:97], v[228:229], v[96:97] op_sel:[1,0]
	v_pk_fma_f32 v[98:99], v[208:209], v[98:99], v[212:213]
	v_pk_fma_f32 v[96:97], v[210:211], v[96:97], v[214:215]
	v_pk_fma_f32 v[98:99], v[90:91], v[114:115], v[98:99]
	v_pk_fma_f32 v[90:91], v[88:89], v[112:113], v[96:97]
	v_cvt_pk_f16_f32 v88, v92, v93
	v_lshl_add_u64 v[92:93], s[16:17], 0, v[230:231]
	v_cvt_pk_f16_f32 v89, v94, v95
	v_cvt_pk_f16_f32 v90, v90, v91
	v_cvt_pk_f16_f32 v91, v98, v99
	v_lshl_add_u64 v[92:93], v[92:93], 0, v[220:221]
	global_store_dwordx4 v[92:93], v[88:91], off
	v_cvt_f32_f16_sdwa v94, v146 dst_sel:DWORD dst_unused:UNUSED_PAD src0_sel:WORD_1
	v_cvt_f32_f16_e32 v95, v146
	v_cvt_f32_f16_sdwa v89, v144 dst_sel:DWORD dst_unused:UNUSED_PAD src0_sel:WORD_1
	v_cvt_f32_f16_e32 v88, v144
	v_cvt_f32_f16_sdwa v91, v145 dst_sel:DWORD dst_unused:UNUSED_PAD src0_sel:WORD_1
	v_cvt_f32_f16_e32 v90, v145
	v_cvt_f32_f16_sdwa v96, v147 dst_sel:DWORD dst_unused:UNUSED_PAD src0_sel:WORD_1
	v_cvt_f32_f16_e32 v97, v147
	v_sub_f32_e32 v88, v88, v228
	v_sub_f32_e32 v89, v89, v228
	v_sub_f32_e32 v90, v90, v228
	v_sub_f32_e32 v91, v91, v228
	v_pk_mul_f32 v[90:91], v[228:229], v[90:91] op_sel:[1,0]
;     __device__ __forceinline__ void operator()(const AccT& acc, const pg8::Unit& u, int wr, int wc, int fr, int fq) const {
;     ...
;         for (int ai = 0; ai < 2; ++ai) {
;             u32x4 uraw[4][2]; f32x2 stv[4];
; #pragma unroll
;             for (int m = 0; m < 4; ++m) { const int row = row0 + ai * 128 + m * 16; const size_t off = (size_t)row * D + col0; stv[m] = *(const f32x2*)(stats + 2 * row);
; #pragma unroll
;                 for (int bj = 0; bj < 2; ++bj) uraw[m][bj] = *(const u32x4*)(U1 + off + bj * 128); }
; #pragma unroll
;             for (int m = 0; m < 4; ++m) { const int row = row0 + ai * 128 + m * 16; const size_t off = (size_t)row * D + col0; const f32x2 st = stv[m];
; #pragma unroll
;                 for (int bj = 0; bj < 2; ++bj) { float uf[8]; unpack_h8(uraw[m][bj], uf);
;                     const f32x4 ua = {uf[0], uf[1], uf[2], uf[3]}, ub = {uf[4], uf[5], uf[6], uf[7]};
;                     const f32x4 a = ((ua - st.x) * st.y) * lg[bj][0] + lbv[bj][0] + gv[bj][0] * acc[ai][bj][m][0], b = ((ub - st.x) * st.y) * lg[bj][1] + lbv[bj][1] + gv[bj][1] * acc[ai][bj][m][1];
;                     u32x4 w; w.x = pk_h2(a[0], a[1]); w.y = pk_h2(a[2], a[3]); w.z = pk_h2(b[0], b[1]); w.w = pk_h2(b[2], b[3]);
;                     *(u32x4*)(U2 + off + bj * 128) = w; } }
	v_pk_mul_f32 v[88:89], v[228:229], v[88:89] op_sel:[1,0]
	v_pk_fma_f32 v[90:91], v[196:197], v[90:91], v[200:201]
	v_pk_fma_f32 v[88:89], v[198:199], v[88:89], v[202:203]
	v_pk_fma_f32 v[86:87], v[86:87], v[126:127], v[90:91]
	v_pk_fma_f32 v[84:85], v[84:85], v[124:125], v[88:89]
	v_sub_f32_e32 v88, v95, v228
	v_sub_f32_e32 v89, v94, v228
	v_sub_f32_e32 v90, v97, v228
	v_sub_f32_e32 v91, v96, v228
	v_pk_mul_f32 v[90:91], v[228:229], v[90:91] op_sel:[1,0]
	v_pk_mul_f32 v[88:89], v[228:229], v[88:89] op_sel:[1,0]
	v_pk_fma_f32 v[90:91], v[188:189], v[90:91], v[192:193]
	v_pk_fma_f32 v[88:89], v[190:191], v[88:89], v[194:195]
	v_pk_fma_f32 v[90:91], v[82:83], v[110:111], v[90:91]
	v_pk_fma_f32 v[82:83], v[80:81], v[108:109], v[88:89]
	v_cvt_pk_f16_f32 v80, v84, v85
	v_cvt_pk_f16_f32 v81, v86, v87
	v_cvt_pk_f16_f32 v82, v82, v83
	v_cvt_pk_f16_f32 v83, v90, v91
	global_store_dwordx4 v[92:93], v[80:83], off offset:256
	v_cvt_f32_f16_sdwa v84, v170 dst_sel:DWORD dst_unused:UNUSED_PAD src0_sel:WORD_1
	v_cvt_f32_f16_e32 v85, v170
	v_cvt_f32_f16_sdwa v81, v168 dst_sel:DWORD dst_unused:UNUSED_PAD src0_sel:WORD_1
	v_cvt_f32_f16_e32 v80, v168
	v_cvt_f32_f16_sdwa v83, v169 dst_sel:DWORD dst_unused:UNUSED_PAD src0_sel:WORD_1
	v_cvt_f32_f16_e32 v82, v169
	v_cvt_f32_f16_sdwa v86, v171 dst_sel:DWORD dst_unused:UNUSED_PAD src0_sel:WORD_1
	v_cvt_f32_f16_e32 v87, v171
	v_sub_f32_e32 v80, v80, v226
	v_sub_f32_e32 v81, v81, v226
	v_sub_f32_e32 v82, v82, v226
	v_sub_f32_e32 v83, v83, v226
	v_pk_mul_f32 v[82:83], v[226:227], v[82:83] op_sel:[1,0]
	v_pk_mul_f32 v[80:81], v[226:227], v[80:81] op_sel:[1,0]
	v_pk_fma_f32 v[82:83], v[204:205], v[82:83], v[216:217]
	v_pk_fma_f32 v[80:81], v[206:207], v[80:81], v[218:219]
	v_pk_fma_f32 v[78:79], v[78:79], v[130:131], v[82:83]
	v_pk_fma_f32 v[76:77], v[76:77], v[128:129], v[80:81]
	v_sub_f32_e32 v80, v85, v226
	v_sub_f32_e32 v81, v84, v226
	v_sub_f32_e32 v82, v87, v226
	v_sub_f32_e32 v83, v86, v226
	v_pk_mul_f32 v[82:83], v[226:227], v[82:83] op_sel:[1,0]
	v_pk_mul_f32 v[80:81], v[226:227], v[80:81] op_sel:[1,0]
	v_pk_fma_f32 v[82:83], v[208:209], v[82:83], v[212:213]
	v_pk_fma_f32 v[80:81], v[210:211], v[80:81], v[214:215]
	v_pk_fma_f32 v[82:83], v[74:75], v[114:115], v[82:83]
	v_pk_fma_f32 v[74:75], v[72:73], v[112:113], v[80:81]
	v_cvt_pk_f16_f32 v72, v76, v77
	v_lshl_add_u64 v[76:77], s[16:17], 0, v[232:233]
	v_cvt_pk_f16_f32 v73, v78, v79
	v_cvt_pk_f16_f32 v74, v74, v75
	v_cvt_pk_f16_f32 v75, v82, v83
	v_lshl_add_u64 v[76:77], v[76:77], 0, v[220:221]
	global_store_dwordx4 v[76:77], v[72:75], off
	v_cvt_f32_f16_sdwa v78, v158 dst_sel:DWORD dst_unused:UNUSED_PAD src0_sel:WORD_1
	v_cvt_f32_f16_e32 v79, v158
	v_cvt_f32_f16_sdwa v73, v156 dst_sel:DWORD dst_unused:UNUSED_PAD src0_sel:WORD_1
	v_cvt_f32_f16_e32 v72, v156
	v_cvt_f32_f16_sdwa v75, v157 dst_sel:DWORD dst_unused:UNUSED_PAD src0_sel:WORD_1
	v_cvt_f32_f16_e32 v74, v157
	v_cvt_f32_f16_sdwa v80, v159 dst_sel:DWORD dst_unused:UNUSED_PAD src0_sel:WORD_1
	v_cvt_f32_f16_e32 v81, v159
	v_sub_f32_e32 v72, v72, v226
	v_sub_f32_e32 v73, v73, v226
	v_sub_f32_e32 v74, v74, v226
	v_sub_f32_e32 v75, v75, v226
	v_pk_mul_f32 v[74:75], v[226:227], v[74:75] op_sel:[1,0]
	v_pk_mul_f32 v[72:73], v[226:227], v[72:73] op_sel:[1,0]
	v_pk_fma_f32 v[74:75], v[196:197], v[74:75], v[200:201]
	v_pk_fma_f32 v[72:73], v[198:199], v[72:73], v[202:203]
	v_pk_fma_f32 v[70:71], v[70:71], v[126:127], v[74:75]
	v_pk_fma_f32 v[68:69], v[68:69], v[124:125], v[72:73]
	v_sub_f32_e32 v72, v79, v226
	v_sub_f32_e32 v73, v78, v226
	v_sub_f32_e32 v74, v81, v226
	v_sub_f32_e32 v75, v80, v226
	v_pk_mul_f32 v[74:75], v[226:227], v[74:75] op_sel:[1,0]
	v_pk_mul_f32 v[72:73], v[226:227], v[72:73] op_sel:[1,0]
	v_pk_fma_f32 v[74:75], v[188:189], v[74:75], v[192:193]
	v_pk_fma_f32 v[72:73], v[190:191], v[72:73], v[194:195]
	v_pk_fma_f32 v[74:75], v[66:67], v[110:111], v[74:75]
	v_pk_fma_f32 v[66:67], v[64:65], v[108:109], v[72:73]
	v_cvt_pk_f16_f32 v64, v68, v69
	v_cvt_pk_f16_f32 v65, v70, v71
	v_cvt_pk_f16_f32 v66, v66, v67
	v_cvt_pk_f16_f32 v67, v74, v75
	global_store_dwordx4 v[76:77], v[64:67], off offset:256
	s_nop 1
	v_add_u32_e32 v64, 0x80, v224
	v_ashrrev_i32_e32 v65, 31, v64
	v_lshlrev_b32_e32 v66, 1, v64
	v_ashrrev_i32_e32 v67, 31, v66
	v_lshlrev_b64 v[106:107], 12, v[64:65]
	v_lshl_add_u64 v[66:67], v[66:67], 2, s[8:9]
	v_lshl_add_u64 v[64:65], v[222:223], 0, v[106:107]
	global_load_dwordx2 v[104:105], v[66:67], off
	global_load_dwordx4 v[84:87], v[64:65], off
	global_load_dwordx4 v[88:91], v[64:65], off offset:256
	v_add_u32_e32 v64, 0x90, v224
	v_ashrrev_i32_e32 v65, 31, v64
	v_lshlrev_b32_e32 v66, 1, v64
	v_ashrrev_i32_e32 v67, 31, v66
	v_lshlrev_b64 v[118:119], 12, v[64:65]
	v_lshl_add_u64 v[66:67], v[66:67], 2, s[8:9]
	v_lshl_add_u64 v[64:65], v[222:223], 0, v[118:119]
	global_load_dwordx2 v[116:117], v[66:67], off
	global_load_dwordx4 v[92:95], v[64:65], off
	global_load_dwordx4 v[96:99], v[64:65], off offset:256
	v_add_u32_e32 v64, 0xa0, v224
	v_ashrrev_i32_e32 v65, 31, v64
	v_lshlrev_b32_e32 v66, 1, v64
	v_ashrrev_i32_e32 v67, 31, v66
	v_lshlrev_b64 v[82:83], 12, v[64:65]
	v_lshl_add_u64 v[66:67], v[66:67], 2, s[8:9]
	v_lshl_add_u64 v[64:65], v[222:223], 0, v[82:83]
	global_load_dwordx2 v[80:81], v[66:67], off
	global_load_dwordx4 v[100:103], v[64:65], off
	global_load_dwordx4 v[72:75], v[64:65], off offset:256
	v_add_u32_e32 v64, 0xb0, v224
	v_ashrrev_i32_e32 v65, 31, v64
	v_lshlrev_b32_e32 v66, 1, v64
	v_ashrrev_i32_e32 v67, 31, v66
	v_lshlrev_b64 v[78:79], 12, v[64:65]
	v_lshl_add_u64 v[66:67], v[66:67], 2, s[8:9]
	v_lshl_add_u64 v[64:65], v[222:223], 0, v[78:79]
	global_load_dwordx2 v[76:77], v[66:67], off
	global_load_dwordx4 v[68:71], v[64:65], off
	s_nop 0
	global_load_dwordx4 v[64:67], v[64:65], off offset:256
	s_waitcnt vmcnt(0)
;     __device__ __forceinline__ void operator()(const AccT& acc, const pg8::Unit& u, int wr, int wc, int fr, int fq) const {
;     ...
;             for (int m = 0; m < 4; ++m) { const int row = row0 + ai * 128 + m * 16; const size_t off = (size_t)row * D + col0; const f32x2 st = stv[m];
; #pragma unroll
;                 for (int bj = 0; bj < 2; ++bj) { float uf[8]; unpack_h8(uraw[m][bj], uf);
;                     const f32x4 ua = {uf[0], uf[1], uf[2], uf[3]}, ub = {uf[4], uf[5], uf[6], uf[7]};
;                     const f32x4 a = ((ua - st.x) * st.y) * lg[bj][0] + lbv[bj][0] + gv[bj][0] * acc[ai][bj][m][0], b = ((ub - st.x) * st.y) * lg[bj][1] + lbv[bj][1] + gv[bj][1] * acc[ai][bj][m][1];
;                     u32x4 w; w.x = pk_h2(a[0], a[1]); w.y = pk_h2(a[2], a[3]); w.z = pk_h2(b[0], b[1]); w.w = pk_h2(b[2], b[3]);
;                     *(u32x4*)(U2 + off + bj * 128) = w; } }
	v_cvt_f32_f16_e32 v120, v84
	v_cvt_f32_f16_sdwa v84, v84 dst_sel:DWORD dst_unused:UNUSED_PAD src0_sel:WORD_1
	v_cvt_f32_f16_e32 v121, v85
	v_cvt_f32_f16_sdwa v122, v85 dst_sel:DWORD dst_unused:UNUSED_PAD src0_sel:WORD_1
	v_cvt_f32_f16_e32 v123, v86
	v_cvt_f32_f16_sdwa v132, v86 dst_sel:DWORD dst_unused:UNUSED_PAD src0_sel:WORD_1
	v_cvt_f32_f16_e32 v133, v87
	v_cvt_f32_f16_sdwa v134, v87 dst_sel:DWORD dst_unused:UNUSED_PAD src0_sel:WORD_1
	v_sub_f32_e32 v85, v84, v104
	v_sub_f32_e32 v84, v120, v104
	v_sub_f32_e32 v87, v122, v104
	v_sub_f32_e32 v86, v121, v104
	v_pk_mul_f32 v[86:87], v[104:105], v[86:87] op_sel:[1,0]
	v_pk_mul_f32 v[84:85], v[104:105], v[84:85] op_sel:[1,0]
	v_pk_fma_f32 v[86:87], v[204:205], v[86:87], v[216:217]
	v_pk_fma_f32 v[84:85], v[206:207], v[84:85], v[218:219]
	v_pk_fma_f32 v[62:63], v[62:63], v[130:131], v[86:87]
	v_pk_fma_f32 v[60:61], v[60:61], v[128:129], v[84:85]
	v_sub_f32_e32 v85, v132, v104
	v_sub_f32_e32 v84, v123, v104
	v_sub_f32_e32 v87, v134, v104
	v_sub_f32_e32 v86, v133, v104
	v_pk_mul_f32 v[86:87], v[104:105], v[86:87] op_sel:[1,0]
	v_pk_mul_f32 v[84:85], v[104:105], v[84:85] op_sel:[1,0]
	v_pk_fma_f32 v[86:87], v[208:209], v[86:87], v[212:213]
	v_pk_fma_f32 v[84:85], v[210:211], v[84:85], v[214:215]
	v_pk_fma_f32 v[86:87], v[58:59], v[114:115], v[86:87]
	v_pk_fma_f32 v[58:59], v[56:57], v[112:113], v[84:85]
	v_cvt_pk_f16_f32 v56, v60, v61
	v_lshl_add_u64 v[60:61], s[16:17], 0, v[106:107]
	v_cvt_pk_f16_f32 v57, v62, v63
	v_cvt_pk_f16_f32 v58, v58, v59
	v_cvt_pk_f16_f32 v59, v86, v87
	v_lshl_add_u64 v[60:61], v[60:61], 0, v[220:221]
	global_store_dwordx4 v[60:61], v[56:59], off
	v_cvt_f32_f16_e32 v62, v90
	v_cvt_f32_f16_sdwa v63, v90 dst_sel:DWORD dst_unused:UNUSED_PAD src0_sel:WORD_1
	v_cvt_f32_f16_e32 v56, v88
	v_cvt_f32_f16_sdwa v57, v88 dst_sel:DWORD dst_unused:UNUSED_PAD src0_sel:WORD_1
	v_cvt_f32_f16_e32 v58, v89
	v_cvt_f32_f16_sdwa v59, v89 dst_sel:DWORD dst_unused:UNUSED_PAD src0_sel:WORD_1
	v_cvt_f32_f16_e32 v84, v91
	v_cvt_f32_f16_sdwa v85, v91 dst_sel:DWORD dst_unused:UNUSED_PAD src0_sel:WORD_1
	v_sub_f32_e32 v57, v57, v104
	v_sub_f32_e32 v56, v56, v104
	v_sub_f32_e32 v59, v59, v104
	v_sub_f32_e32 v58, v58, v104
	v_pk_mul_f32 v[58:59], v[104:105], v[58:59] op_sel:[1,0]
	v_pk_mul_f32 v[56:57], v[104:105], v[56:57] op_sel:[1,0]
	v_pk_fma_f32 v[58:59], v[196:197], v[58:59], v[200:201]
	v_pk_fma_f32 v[56:57], v[198:199], v[56:57], v[202:203]
	v_pk_fma_f32 v[54:55], v[54:55], v[126:127], v[58:59]
	v_pk_fma_f32 v[52:53], v[52:53], v[124:125], v[56:57]
	v_sub_f32_e32 v57, v63, v104
	v_sub_f32_e32 v56, v62, v104
	v_sub_f32_e32 v59, v85, v104
	v_sub_f32_e32 v58, v84, v104
	v_pk_mul_f32 v[58:59], v[104:105], v[58:59] op_sel:[1,0]
	v_pk_mul_f32 v[56:57], v[104:105], v[56:57] op_sel:[1,0]
	v_pk_fma_f32 v[58:59], v[188:189], v[58:59], v[192:193]
	v_pk_fma_f32 v[56:57], v[190:191], v[56:57], v[194:195]
	v_pk_fma_f32 v[58:59], v[50:51], v[110:111], v[58:59]
	v_pk_fma_f32 v[50:51], v[48:49], v[108:109], v[56:57]
	v_cvt_pk_f16_f32 v48, v52, v53
	v_cvt_pk_f16_f32 v49, v54, v55
	v_cvt_pk_f16_f32 v50, v50, v51
	v_cvt_pk_f16_f32 v51, v58, v59
	global_store_dwordx4 v[60:61], v[48:51], off offset:256
	v_cvt_f32_f16_e32 v52, v94
	v_cvt_f32_f16_sdwa v53, v94 dst_sel:DWORD dst_unused:UNUSED_PAD src0_sel:WORD_1
	v_cvt_f32_f16_e32 v48, v92
	v_cvt_f32_f16_sdwa v49, v92 dst_sel:DWORD dst_unused:UNUSED_PAD src0_sel:WORD_1
	v_cvt_f32_f16_e32 v50, v93
	v_cvt_f32_f16_sdwa v51, v93 dst_sel:DWORD dst_unused:UNUSED_PAD src0_sel:WORD_1
	v_cvt_f32_f16_e32 v54, v95
	v_cvt_f32_f16_sdwa v55, v95 dst_sel:DWORD dst_unused:UNUSED_PAD src0_sel:WORD_1
	v_sub_f32_e32 v49, v49, v116
	v_sub_f32_e32 v48, v48, v116
	v_sub_f32_e32 v51, v51, v116
	v_sub_f32_e32 v50, v50, v116
	v_pk_mul_f32 v[50:51], v[116:117], v[50:51] op_sel:[1,0]
	v_pk_mul_f32 v[48:49], v[116:117], v[48:49] op_sel:[1,0]
	v_pk_fma_f32 v[50:51], v[204:205], v[50:51], v[216:217]
	v_pk_fma_f32 v[48:49], v[206:207], v[48:49], v[218:219]
	v_pk_fma_f32 v[46:47], v[46:47], v[130:131], v[50:51]
	v_pk_fma_f32 v[44:45], v[44:45], v[128:129], v[48:49]
	v_sub_f32_e32 v49, v53, v116
	v_sub_f32_e32 v48, v52, v116
	v_sub_f32_e32 v51, v55, v116
	v_sub_f32_e32 v50, v54, v116
	v_pk_mul_f32 v[50:51], v[116:117], v[50:51] op_sel:[1,0]
	v_pk_mul_f32 v[48:49], v[116:117], v[48:49] op_sel:[1,0]
	v_pk_fma_f32 v[50:51], v[208:209], v[50:51], v[212:213]
	v_pk_fma_f32 v[48:49], v[210:211], v[48:49], v[214:215]
	v_pk_fma_f32 v[50:51], v[42:43], v[114:115], v[50:51]
	v_pk_fma_f32 v[42:43], v[40:41], v[112:113], v[48:49]
	v_cvt_pk_f16_f32 v40, v44, v45
	v_lshl_add_u64 v[44:45], s[16:17], 0, v[118:119]
	v_cvt_pk_f16_f32 v41, v46, v47
	v_cvt_pk_f16_f32 v42, v42, v43
	v_cvt_pk_f16_f32 v43, v50, v51
	v_lshl_add_u64 v[44:45], v[44:45], 0, v[220:221]
	global_store_dwordx4 v[44:45], v[40:43], off
	v_cvt_f32_f16_e32 v46, v98
	v_cvt_f32_f16_sdwa v47, v98 dst_sel:DWORD dst_unused:UNUSED_PAD src0_sel:WORD_1
	v_cvt_f32_f16_e32 v40, v96
	v_cvt_f32_f16_sdwa v41, v96 dst_sel:DWORD dst_unused:UNUSED_PAD src0_sel:WORD_1
	v_cvt_f32_f16_e32 v42, v97
	v_cvt_f32_f16_sdwa v43, v97 dst_sel:DWORD dst_unused:UNUSED_PAD src0_sel:WORD_1
	v_cvt_f32_f16_e32 v48, v99
	v_cvt_f32_f16_sdwa v49, v99 dst_sel:DWORD dst_unused:UNUSED_PAD src0_sel:WORD_1
	v_sub_f32_e32 v41, v41, v116
	v_sub_f32_e32 v40, v40, v116
	v_sub_f32_e32 v43, v43, v116
	v_sub_f32_e32 v42, v42, v116
	v_pk_mul_f32 v[42:43], v[116:117], v[42:43] op_sel:[1,0]
	v_pk_mul_f32 v[40:41], v[116:117], v[40:41] op_sel:[1,0]
	v_pk_fma_f32 v[42:43], v[196:197], v[42:43], v[200:201]
	v_pk_fma_f32 v[40:41], v[198:199], v[40:41], v[202:203]
	v_pk_fma_f32 v[38:39], v[38:39], v[126:127], v[42:43]
; template <class Epi, class Sched>
; __device__ __forceinline__ void gemm_phase(PG8_LAS unsigned char* lds, const Gemm g, const Sched& S, const Epi& E) {
;     ...
;         E(acc, cur, wr, wc, fr, fq); S.done(cur);
;         if (!has_next) break;
;     __device__ __forceinline__ void operator()(const AccT& acc, const pg8::Unit& u, int wr, int wc, int fr, int fq) const {
;     ...
;             for (int m = 0; m < 4; ++m) { const int row = row0 + ai * 128 + m * 16; const size_t off = (size_t)row * D + col0; const f32x2 st = stv[m];
; #pragma unroll
;                 for (int bj = 0; bj < 2; ++bj) { float uf[8]; unpack_h8(uraw[m][bj], uf);
;                     const f32x4 ua = {uf[0], uf[1], uf[2], uf[3]}, ub = {uf[4], uf[5], uf[6], uf[7]};
;                     const f32x4 a = ((ua - st.x) * st.y) * lg[bj][0] + lbv[bj][0] + gv[bj][0] * acc[ai][bj][m][0], b = ((ub - st.x) * st.y) * lg[bj][1] + lbv[bj][1] + gv[bj][1] * acc[ai][bj][m][1];
;                     u32x4 w; w.x = pk_h2(a[0], a[1]); w.y = pk_h2(a[2], a[3]); w.z = pk_h2(b[0], b[1]); w.w = pk_h2(b[2], b[3]);
;                     *(u32x4*)(U2 + off + bj * 128) = w; } }
	v_pk_fma_f32 v[36:37], v[36:37], v[124:125], v[40:41]
	v_sub_f32_e32 v41, v47, v116
	v_sub_f32_e32 v40, v46, v116
	v_sub_f32_e32 v43, v49, v116
	v_sub_f32_e32 v42, v48, v116
	v_pk_mul_f32 v[42:43], v[116:117], v[42:43] op_sel:[1,0]
	v_pk_mul_f32 v[40:41], v[116:117], v[40:41] op_sel:[1,0]
	v_pk_fma_f32 v[42:43], v[188:189], v[42:43], v[192:193]
	v_pk_fma_f32 v[40:41], v[190:191], v[40:41], v[194:195]
	v_pk_fma_f32 v[42:43], v[34:35], v[110:111], v[42:43]
	v_pk_fma_f32 v[34:35], v[32:33], v[108:109], v[40:41]
	v_cvt_pk_f16_f32 v32, v36, v37
	v_cvt_pk_f16_f32 v33, v38, v39
	v_cvt_pk_f16_f32 v34, v34, v35
	v_cvt_pk_f16_f32 v35, v42, v43
	global_store_dwordx4 v[44:45], v[32:35], off offset:256
	v_cvt_f32_f16_e32 v36, v102
	v_cvt_f32_f16_sdwa v37, v102 dst_sel:DWORD dst_unused:UNUSED_PAD src0_sel:WORD_1
	v_cvt_f32_f16_e32 v32, v100
	v_cvt_f32_f16_sdwa v33, v100 dst_sel:DWORD dst_unused:UNUSED_PAD src0_sel:WORD_1
	v_cvt_f32_f16_e32 v34, v101
	v_cvt_f32_f16_sdwa v35, v101 dst_sel:DWORD dst_unused:UNUSED_PAD src0_sel:WORD_1
	v_cvt_f32_f16_e32 v38, v103
	v_cvt_f32_f16_sdwa v39, v103 dst_sel:DWORD dst_unused:UNUSED_PAD src0_sel:WORD_1
	v_sub_f32_e32 v33, v33, v80
	v_sub_f32_e32 v32, v32, v80
	v_sub_f32_e32 v35, v35, v80
	v_sub_f32_e32 v34, v34, v80
	v_pk_mul_f32 v[34:35], v[80:81], v[34:35] op_sel:[1,0]
	v_pk_mul_f32 v[32:33], v[80:81], v[32:33] op_sel:[1,0]
	v_pk_fma_f32 v[34:35], v[204:205], v[34:35], v[216:217]
	v_pk_fma_f32 v[32:33], v[206:207], v[32:33], v[218:219]
	v_pk_fma_f32 v[30:31], v[30:31], v[130:131], v[34:35]
	v_pk_fma_f32 v[28:29], v[28:29], v[128:129], v[32:33]
	v_sub_f32_e32 v33, v37, v80
	v_sub_f32_e32 v32, v36, v80
	v_sub_f32_e32 v35, v39, v80
	v_sub_f32_e32 v34, v38, v80
	v_pk_mul_f32 v[34:35], v[80:81], v[34:35] op_sel:[1,0]
	v_pk_mul_f32 v[32:33], v[80:81], v[32:33] op_sel:[1,0]
	v_pk_fma_f32 v[34:35], v[208:209], v[34:35], v[212:213]
	v_pk_fma_f32 v[32:33], v[210:211], v[32:33], v[214:215]
	v_pk_fma_f32 v[34:35], v[26:27], v[114:115], v[34:35]
	v_pk_fma_f32 v[26:27], v[24:25], v[112:113], v[32:33]
	v_cvt_pk_f16_f32 v24, v28, v29
	v_lshl_add_u64 v[28:29], s[16:17], 0, v[82:83]
	v_cvt_pk_f16_f32 v25, v30, v31
	v_cvt_pk_f16_f32 v26, v26, v27
	v_cvt_pk_f16_f32 v27, v34, v35
	v_lshl_add_u64 v[28:29], v[28:29], 0, v[220:221]
	global_store_dwordx4 v[28:29], v[24:27], off
	v_cvt_f32_f16_e32 v30, v74
	v_cvt_f32_f16_sdwa v31, v74 dst_sel:DWORD dst_unused:UNUSED_PAD src0_sel:WORD_1
	v_cvt_f32_f16_e32 v24, v72
	v_cvt_f32_f16_sdwa v25, v72 dst_sel:DWORD dst_unused:UNUSED_PAD src0_sel:WORD_1
	v_cvt_f32_f16_e32 v26, v73
	v_cvt_f32_f16_sdwa v27, v73 dst_sel:DWORD dst_unused:UNUSED_PAD src0_sel:WORD_1
	v_cvt_f32_f16_e32 v32, v75
	v_cvt_f32_f16_sdwa v33, v75 dst_sel:DWORD dst_unused:UNUSED_PAD src0_sel:WORD_1
	v_sub_f32_e32 v25, v25, v80
	v_sub_f32_e32 v24, v24, v80
	v_sub_f32_e32 v27, v27, v80
	v_sub_f32_e32 v26, v26, v80
	v_pk_mul_f32 v[26:27], v[80:81], v[26:27] op_sel:[1,0]
	v_pk_mul_f32 v[24:25], v[80:81], v[24:25] op_sel:[1,0]
	v_pk_fma_f32 v[26:27], v[196:197], v[26:27], v[200:201]
	v_pk_fma_f32 v[24:25], v[198:199], v[24:25], v[202:203]
	v_pk_fma_f32 v[22:23], v[22:23], v[126:127], v[26:27]
	v_pk_fma_f32 v[20:21], v[20:21], v[124:125], v[24:25]
	v_sub_f32_e32 v25, v31, v80
	v_sub_f32_e32 v24, v30, v80
	v_sub_f32_e32 v27, v33, v80
	v_sub_f32_e32 v26, v32, v80
	v_pk_mul_f32 v[26:27], v[80:81], v[26:27] op_sel:[1,0]
	v_pk_mul_f32 v[24:25], v[80:81], v[24:25] op_sel:[1,0]
	v_pk_fma_f32 v[26:27], v[188:189], v[26:27], v[192:193]
	v_pk_fma_f32 v[24:25], v[190:191], v[24:25], v[194:195]
	v_pk_fma_f32 v[26:27], v[18:19], v[110:111], v[26:27]
	v_pk_fma_f32 v[18:19], v[16:17], v[108:109], v[24:25]
	v_cvt_pk_f16_f32 v16, v20, v21
	v_cvt_pk_f16_f32 v17, v22, v23
	v_cvt_pk_f16_f32 v18, v18, v19
	v_cvt_pk_f16_f32 v19, v26, v27
	global_store_dwordx4 v[28:29], v[16:19], off offset:256
	v_cvt_f32_f16_e32 v20, v70
	v_cvt_f32_f16_sdwa v21, v70 dst_sel:DWORD dst_unused:UNUSED_PAD src0_sel:WORD_1
	v_cvt_f32_f16_e32 v16, v68
	v_cvt_f32_f16_sdwa v17, v68 dst_sel:DWORD dst_unused:UNUSED_PAD src0_sel:WORD_1
	v_cvt_f32_f16_e32 v18, v69
	v_cvt_f32_f16_sdwa v19, v69 dst_sel:DWORD dst_unused:UNUSED_PAD src0_sel:WORD_1
	v_cvt_f32_f16_e32 v22, v71
	v_cvt_f32_f16_sdwa v23, v71 dst_sel:DWORD dst_unused:UNUSED_PAD src0_sel:WORD_1
	v_sub_f32_e32 v17, v17, v76
	v_sub_f32_e32 v16, v16, v76
	v_sub_f32_e32 v19, v19, v76
	v_sub_f32_e32 v18, v18, v76
	v_pk_mul_f32 v[18:19], v[76:77], v[18:19] op_sel:[1,0]
	v_pk_mul_f32 v[16:17], v[76:77], v[16:17] op_sel:[1,0]
	v_pk_fma_f32 v[18:19], v[204:205], v[18:19], v[216:217]
	v_pk_fma_f32 v[16:17], v[206:207], v[16:17], v[218:219]
	v_pk_fma_f32 v[14:15], v[14:15], v[130:131], v[18:19]
	v_pk_fma_f32 v[12:13], v[12:13], v[128:129], v[16:17]
	v_sub_f32_e32 v17, v21, v76
	v_sub_f32_e32 v16, v20, v76
	v_sub_f32_e32 v19, v23, v76
	v_sub_f32_e32 v18, v22, v76
	v_pk_mul_f32 v[18:19], v[76:77], v[18:19] op_sel:[1,0]
	v_pk_mul_f32 v[16:17], v[76:77], v[16:17] op_sel:[1,0]
	v_pk_fma_f32 v[18:19], v[208:209], v[18:19], v[212:213]
	v_pk_fma_f32 v[16:17], v[210:211], v[16:17], v[214:215]
	v_pk_fma_f32 v[18:19], v[10:11], v[114:115], v[18:19]
	v_pk_fma_f32 v[10:11], v[8:9], v[112:113], v[16:17]
	v_cvt_pk_f16_f32 v8, v12, v13
	v_lshl_add_u64 v[12:13], s[16:17], 0, v[78:79]
	v_cvt_pk_f16_f32 v9, v14, v15
	v_cvt_pk_f16_f32 v10, v10, v11
	v_cvt_pk_f16_f32 v11, v18, v19
	v_lshl_add_u64 v[12:13], v[12:13], 0, v[220:221]
	global_store_dwordx4 v[12:13], v[8:11], off
	v_cvt_f32_f16_e32 v14, v66
	v_cvt_f32_f16_sdwa v15, v66 dst_sel:DWORD dst_unused:UNUSED_PAD src0_sel:WORD_1
	v_cvt_f32_f16_e32 v8, v64
	v_cvt_f32_f16_sdwa v9, v64 dst_sel:DWORD dst_unused:UNUSED_PAD src0_sel:WORD_1
	v_cvt_f32_f16_e32 v10, v65
	v_cvt_f32_f16_sdwa v11, v65 dst_sel:DWORD dst_unused:UNUSED_PAD src0_sel:WORD_1
	v_cvt_f32_f16_e32 v16, v67
	v_cvt_f32_f16_sdwa v17, v67 dst_sel:DWORD dst_unused:UNUSED_PAD src0_sel:WORD_1
	v_sub_f32_e32 v9, v9, v76
	v_sub_f32_e32 v8, v8, v76
	v_sub_f32_e32 v11, v11, v76
	v_sub_f32_e32 v10, v10, v76
	v_pk_mul_f32 v[10:11], v[76:77], v[10:11] op_sel:[1,0]
	v_pk_mul_f32 v[8:9], v[76:77], v[8:9] op_sel:[1,0]
	v_pk_fma_f32 v[10:11], v[196:197], v[10:11], v[200:201]
	v_pk_fma_f32 v[8:9], v[198:199], v[8:9], v[202:203]
	v_pk_fma_f32 v[6:7], v[6:7], v[126:127], v[10:11]
	v_pk_fma_f32 v[4:5], v[4:5], v[124:125], v[8:9]
	v_sub_f32_e32 v9, v15, v76
	v_sub_f32_e32 v8, v14, v76
	v_sub_f32_e32 v11, v17, v76
	v_sub_f32_e32 v10, v16, v76
	v_pk_mul_f32 v[10:11], v[76:77], v[10:11] op_sel:[1,0]
	v_pk_mul_f32 v[8:9], v[76:77], v[8:9] op_sel:[1,0]
	v_pk_fma_f32 v[10:11], v[188:189], v[10:11], v[192:193]
	v_pk_fma_f32 v[8:9], v[190:191], v[8:9], v[194:195]
	v_pk_fma_f32 v[10:11], v[2:3], v[110:111], v[10:11]
	v_pk_fma_f32 v[2:3], v[0:1], v[108:109], v[8:9]
	v_cvt_pk_f16_f32 v0, v4, v5
	v_cvt_pk_f16_f32 v1, v6, v7
	v_cvt_pk_f16_f32 v2, v2, v3
	v_cvt_pk_f16_f32 v3, v10, v11
	global_store_dwordx4 v[12:13], v[0:3], off offset:256
	s_cmp_eq_u32 s98, 0
	s_cbranch_scc1 .Lxb_882
	s_barrier
; #define PG8_WAIT_V(n) asm volatile("s_waitcnt vmcnt(" #n ")" ::: "memory")
; #define PG8_BAR __builtin_amdgcn_s_barrier()
; template <class Epi, class Sched>
; __device__ __forceinline__ void gemm_phase(PG8_LAS unsigned char* lds, const Gemm g, const Sched& S, const Epi& E) {
;     ...
;         E(acc, cur, wr, wc, fr, fq); S.done(cur);
;         if (!has_next) break;
; #pragma unroll
;         for (int a = 0; a < 2; ++a)
; #pragma unroll
;             for (int b = 0; b < 2; ++b)
; #pragma unroll
;                 for (int m = 0; m < 4; ++m)
; #pragma unroll
;                     for (int n = 0; n < 2; ++n) acc[a][b][m][n] = (f32x4){0.f, 0.f, 0.f, 0.f};
;         cur = nxt; cA = nA; cB = nB; ++ui;
;     }
;     PG8_WAIT_V(0);
;     if (wr == 0) PG8_BAR;
;     PG8_BAR;
.Lxb_882:
	s_cbranch_vccz .LBB0_871
	s_waitcnt vmcnt(0)
	s_cmpk_gt_u32 s21, 0xff
	s_cbranch_scc1 .LBB0_886
	s_barrier

; __global__ void __launch_bounds__(512, 2) hymba_fwd(Params p) {
;     extern __shared__ __attribute__((aligned(16))) unsigned char shm[];
;     cg::grid_group grid = cg::this_grid();
;     PG8_LAS unsigned char* lds3 = (PG8_LAS unsigned char*)shm;
;     const int lo = p.lo, hi = p.hi;
;     ...
;     if (threadIdx.x == 0) { *(volatile PG8_LAS unsigned*)(lds3 + pg8::STAGE_BYTES) = 0u; *(volatile PG8_LAS unsigned*)(lds3 + pg8::STAGE_BYTES + 4) = 0u; }
;     __syncthreads();
;     XcdBarrier xbar = xcd_barrier_post((unsigned*)(p.ws + WS_BAR), (volatile PG8_LAS unsigned*)(lds3 + pg8::STAGE_BYTES));
;     if (lo < 0) grid.sync();
;     ...
;     if (IN(0)) { phase_prep(p, shm); SEAM(0); }
;     if (IN(1)) {
;         const int NCW = (gridDim.x >= 64) ? 24 : 0;
;         if ((int)blockIdx.x < NCW) {
;             const int cb = (int)blockIdx.x / 12, cpn = (int)blockIdx.x % 12;
;             ln_ctx_rows(p, T + cb * CTXL, CTXL);
;             asm volatile("s_waitcnt vmcnt(0)" ::: "memory"); __syncthreads();
;             pg8::Gemm g{(const bf16_t*)(p.ws + WS_H), (const bf16_t*)(p.ws + WS_WIN), TALL, NIN, D}; OneUnit S1{T / 256 + cb, cpn};
;             EpiIn E{(unsigned short*)(p.ws + WS_G), (bf16_t*)(p.ws + WS_V), (bf16_t*)(p.ws + WS_Q), (bf16_t*)(p.ws + WS_GATE), (bf16_t*)(p.ws + WS_BG), (bf16_t*)(p.ws + WS_P), (const float*)(p.ws + WS_LB)};
;             pg8::gemm_phase<EpiIn, OneUnit>(lds3, g, S1, E);
;         } else {
;             if (NCW == 0) phase_ln_in(p, T, TALL, (int)(blockIdx.x * 8 + (threadIdx.x >> 6)), (int)gridDim.x * 8);
;             phase_ln_in(p, 0, T, (int)((blockIdx.x - NCW) * 8 + (threadIdx.x >> 6)), (int)(gridDim.x - NCW) * 8);
;         }
;         SEAM(1);
;     }
;     if (IN(2)) {
;         const int Min = (gridDim.x >= 64) ? T : TALL;
;         pg8::Gemm g{(const bf16_t*)(p.ws + WS_H), (const bf16_t*)(p.ws + WS_WIN), Min, NIN, D}; pg8::StaticOrder S; S.init(Min, NIN, (int)gridDim.x, (int)blockIdx.x);
;         EpiIn E{(unsigned short*)(p.ws + WS_G), (bf16_t*)(p.ws + WS_V), (bf16_t*)(p.ws + WS_Q), (bf16_t*)(p.ws + WS_GATE), (bf16_t*)(p.ws + WS_BG), (bf16_t*)(p.ws + WS_P), (const float*)(p.ws + WS_LB)};
;         pg8::gemm_phase<EpiIn, pg8::StaticOrder>(lds3, g, S, E); SEAM(2);
;     }
;     if (IN(3)) { phase_scan1(p, shm); SEAM(3); }
;     if (IN(4)) { phase_scan2(p, shm); SEAM(4); }
;     if (IN(5)) { phase_combine(p); SEAM(5); }
;     if (IN(6)) {
	.amdhsa_kernel _Z9hymba_fwd6Params
		.amdhsa_group_segment_fixed_size 0
		.amdhsa_private_segment_fixed_size 0
		.amdhsa_kernarg_size 424
		.amdhsa_user_sgpr_count 2
		.amdhsa_user_sgpr_dispatch_ptr 0
		.amdhsa_user_sgpr_queue_ptr 0
		.amdhsa_user_sgpr_kernarg_segment_ptr 1
		.amdhsa_user_sgpr_dispatch_id 0
		.amdhsa_user_sgpr_kernarg_preload_length 0
		.amdhsa_user_sgpr_kernarg_preload_offset 0
		.amdhsa_user_sgpr_private_segment_size 0
		.amdhsa_uses_dynamic_stack 0
		.amdhsa_enable_private_segment 0
		.amdhsa_system_sgpr_workgroup_id_x 1
		.amdhsa_system_sgpr_workgroup_id_y 0
		.amdhsa_system_sgpr_workgroup_id_z 0
		.amdhsa_system_sgpr_workgroup_info 0
		.amdhsa_system_vgpr_workitem_id 2
		.amdhsa_next_free_vgpr 256
		.amdhsa_next_free_sgpr 99
		.amdhsa_accum_offset 256
		.amdhsa_reserve_vcc 1
		.amdhsa_float_round_mode_32 0
		.amdhsa_float_round_mode_16_64 0
		.amdhsa_float_denorm_mode_32 3
		.amdhsa_float_denorm_mode_16_64 3
		.amdhsa_dx10_clamp 1
		.amdhsa_ieee_mode 1
		.amdhsa_fp16_overflow 0
		.amdhsa_tg_split 0
		.amdhsa_exception_fp_ieee_invalid_op 0
		.amdhsa_exception_fp_denorm_src 0
		.amdhsa_exception_fp_ieee_div_zero 0
		.amdhsa_exception_fp_ieee_overflow 0
		.amdhsa_exception_fp_ieee_underflow 0
		.amdhsa_exception_fp_ieee_inexact 0
		.amdhsa_exception_int_div_zero 0
	.end_amdhsa_kernel

; __global__ void __launch_bounds__(512, 2) hymba_fwd(Params p) {
;     extern __shared__ __attribute__((aligned(16))) unsigned char shm[];
;     cg::grid_group grid = cg::this_grid();
;     PG8_LAS unsigned char* lds3 = (PG8_LAS unsigned char*)shm;
;     const int lo = p.lo, hi = p.hi;
;     ...
;     if (threadIdx.x == 0) { *(volatile PG8_LAS unsigned*)(lds3 + pg8::STAGE_BYTES) = 0u; *(volatile PG8_LAS unsigned*)(lds3 + pg8::STAGE_BYTES + 4) = 0u; }
;     __syncthreads();
;     XcdBarrier xbar = xcd_barrier_post((unsigned*)(p.ws + WS_BAR), (volatile PG8_LAS unsigned*)(lds3 + pg8::STAGE_BYTES));
;     if (lo < 0) grid.sync();
;     ...
;     if (IN(0)) { phase_prep(p, shm); SEAM(0); }
;     if (IN(1)) {
;         const int NCW = (gridDim.x >= 64) ? 24 : 0;
;         if ((int)blockIdx.x < NCW) {
;             const int cb = (int)blockIdx.x / 12, cpn = (int)blockIdx.x % 12;
;             ln_ctx_rows(p, T + cb * CTXL, CTXL);
;             asm volatile("s_waitcnt vmcnt(0)" ::: "memory"); __syncthreads();
;             pg8::Gemm g{(const bf16_t*)(p.ws + WS_H), (const bf16_t*)(p.ws + WS_WIN), TALL, NIN, D}; OneUnit S1{T / 256 + cb, cpn};
;             EpiIn E{(unsigned short*)(p.ws + WS_G), (bf16_t*)(p.ws + WS_V), (bf16_t*)(p.ws + WS_Q), (bf16_t*)(p.ws + WS_GATE), (bf16_t*)(p.ws + WS_BG), (bf16_t*)(p.ws + WS_P), (const float*)(p.ws + WS_LB)};
;             pg8::gemm_phase<EpiIn, OneUnit>(lds3, g, S1, E);
;         } else {
;             if (NCW == 0) phase_ln_in(p, T, TALL, (int)(blockIdx.x * 8 + (threadIdx.x >> 6)), (int)gridDim.x * 8);
;             phase_ln_in(p, 0, T, (int)((blockIdx.x - NCW) * 8 + (threadIdx.x >> 6)), (int)(gridDim.x - NCW) * 8);
;         }
;         SEAM(1);
;     }
;     if (IN(2)) {
;         const int Min = (gridDim.x >= 64) ? T : TALL;
;         pg8::Gemm g{(const bf16_t*)(p.ws + WS_H), (const bf16_t*)(p.ws + WS_WIN), Min, NIN, D}; pg8::StaticOrder S; S.init(Min, NIN, (int)gridDim.x, (int)blockIdx.x);
;         EpiIn E{(unsigned short*)(p.ws + WS_G), (bf16_t*)(p.ws + WS_V), (bf16_t*)(p.ws + WS_Q), (bf16_t*)(p.ws + WS_GATE), (bf16_t*)(p.ws + WS_BG), (bf16_t*)(p.ws + WS_P), (const float*)(p.ws + WS_LB)};
;         pg8::gemm_phase<EpiIn, pg8::StaticOrder>(lds3, g, S, E); SEAM(2);
;     }
;     if (IN(3)) { phase_scan1(p, shm); SEAM(3); }
;     if (IN(4)) { phase_scan2(p, shm); SEAM(4); }
;     if (IN(5)) { phase_combine(p); SEAM(5); }
;     if (IN(6)) {
amdhsa.kernels:
  - .agpr_count:     0
    .args:
      - .offset:         0
        .size:           168
        .value_kind:     by_value
      - .offset:         168
        .size:           4
        .value_kind:     hidden_block_count_x
      - .offset:         172
        .size:           4
        .value_kind:     hidden_block_count_y
      - .offset:         176
        .size:           4
        .value_kind:     hidden_block_count_z
      - .offset:         180
        .size:           2
        .value_kind:     hidden_group_size_x
      - .offset:         182
        .size:           2
        .value_kind:     hidden_group_size_y
      - .offset:         184
        .size:           2
        .value_kind:     hidden_group_size_z
      - .offset:         186
        .size:           2
        .value_kind:     hidden_remainder_x
      - .offset:         188
        .size:           2
        .value_kind:     hidden_remainder_y
      - .offset:         190
        .size:           2
        .value_kind:     hidden_remainder_z
      - .offset:         208
        .size:           8
        .value_kind:     hidden_global_offset_x
      - .offset:         216
        .size:           8
        .value_kind:     hidden_global_offset_y
      - .offset:         224
        .size:           8
        .value_kind:     hidden_global_offset_z
      - .offset:         232
        .size:           2
        .value_kind:     hidden_grid_dims
      - .offset:         256
        .size:           8
        .value_kind:     hidden_multigrid_sync_arg
      - .offset:         288
        .size:           4
        .value_kind:     hidden_dynamic_lds_size
    .group_segment_fixed_size: 0
    .kernarg_segment_align: 8
    .kernarg_segment_size: 424
    .language:       OpenCL C
    .language_version:
      - 2
      - 0
    .max_flat_workgroup_size: 512
    .name:           _Z9hymba_fwd6Params
    .private_segment_fixed_size: 0
    .sgpr_count:     105
    .sgpr_spill_count: 3
    .symbol:         _Z9hymba_fwd6Params.kd
    .uniform_work_group_size: 1
    .uses_dynamic_stack: false
    .vgpr_count:     256
    .vgpr_spill_count: 0
    .wavefront_size: 64
